# speedup vs baseline: 1.0214x; 1.0026x over previous
; __device__ __forceinline__ int mytid(int wv) { return (wv << 6) | (int)__builtin_amdgcn_mbcnt_hi(~0u, __builtin_amdgcn_mbcnt_lo(~0u, 0u)); }
; #define STAGE_A(P, hf, kt) do { if constexpr (ABLK) { const bf16* _gp = A + ((long)(brow >> 8) * nt + (kt)) * 16384 + (hf) * 8192; GLDS2(_gp, 4096, offA, P); } \
;     else { const bf16* _gp = A + (long)(brow + (hf) * HALF) * lda + (long)(kt) * BK; GLDS2(_gp, 64 * (long)lda, offA, P); } } while (0)
; #define STAGE_B(P, hf, kt) do { const bf16* _gp = Bt + (long)(bcol + (hf) * 2) * ldb + (long)(kt) * BK; GLDS2(_gp, 128 * (long)ldb, offB, P); } while (0)
; #define BAR __builtin_amdgcn_s_barrier()
; template <bool ABLK, class Epi>
; __device__ __forceinline__ void gemm_tile(const bf16* __restrict__ A, int lda, const bf16* __restrict__ Bt, int ldb, int K,
;                                           int brow, int bcol, bf16* shm, const Epi& epi, int wv) {
;     ...
;   int tid = mytid(wv); asm volatile("" : "+v"(tid));
;   const int wid = tid >> 6, lane = tid & 63, wr = wid >> 2, wc = wid & 3, fr = lane & 15, fq = lane >> 4;
;   f32x4 acc[2][2][4][2] = {};
;   bf16x8 At[4][2], B0[2][2], B1[2][2];
;   const int nt = K / BK;
;   int offA, offB;
;   { int r_, c_; stage_rc(tid * 16, r_, c_); offA = ABLK ? r_ * 64 + c_ : r_ * lda + c_;
;     offB = ((r_ >> 5) * 64 + (r_ & 15) * 4 + ((r_ >> 4) & 1)) * ldb + c_; }
;   STAGE_B(SB(0, 0), 0, 0); STAGE_A(SA(0, 0), 0, 0);
;   STAGE_B(SB(0, 1), 1, 0); STAGE_A(SA(0, 1), 1, 0);
;   if (wr == 1) BAR;
; template <bool ABLK, class Epi>
; __device__ __forceinline__ void gemm_phase(const bf16* A, int lda, const bf16* Bt, int ldb, int M, int N, int K, char* smem, const Epi& epi, int wv) {
;     ...
;     { int q = nwg / NXCD, r = nwg % NXCD, xcd = wgid % NXCD, off = wgid / NXCD;
;       wgid = (xcd < r ? xcd * (q + 1) : r * (q + 1) + (xcd - r) * q) + off; }
;     const int nig = WGM * nN, gid = wgid / nig, fm = gid * WGM, gsz = min(nM - fm, WGM);
;     const int pm = fm + ((wgid % nig) % gsz), pn = (wgid % nig) / gsz;
;     gemm_tile<ABLK>(A, lda, Bt, ldb, K, pm * BM, pn * BM, (bf16*)smem, epi, wv);
.LBB0_83:
	s_ashr_i32 s2, s83, 31
	s_lshr_b32 s2, s2, 29
	s_add_i32 s2, s83, s2
	s_ashr_i32 s33, s2, 3
	s_and_b32 s2, s2, -8
	v_mov_b32_e32 v135, v192
	s_sub_i32 s2, s83, s2
	s_cmp_lt_i32 s2, 0
	v_ashrrev_i32_e32 v0, 31, v135
	v_lshrrev_b32_e32 v0, 26, v0
	s_cselect_b32 s62, s0, 0x240
	v_add_u32_e32 v0, v135, v0
	s_mul_i32 s2, s62, s2
	v_ashrrev_i32_e32 v4, 6, v0
	v_bfe_i32 v0, v135, 27, 1
	s_add_i32 s2, s2, s33
	v_lshlrev_b32_e32 v11, 4, v135
	v_lshrrev_b32_e32 v0, 22, v0
	s_mul_hi_i32 s33, s2, 0x2aaaaaab
	v_add_u32_e32 v0, v11, v0
	s_lshr_b32 s62, s33, 31
	s_ashr_i32 s33, s33, 4
	v_and_b32_e32 v0, 0xfffffc00, v0
	s_add_i32 s33, s33, s62
	v_sub_u32_e32 v0, v11, v0
	s_lshl_b32 s62, s33, 2
	s_mulk_i32 s33, 0x60
	v_lshrrev_b32_e32 v1, 4, v0
	s_sub_i32 s2, s2, s33
	v_bitop3_b32 v0, v1, v0, 32 bitop3:0x6c
	s_bfe_i32 s33, s2, 0x80000
	v_ashrrev_i32_e32 v2, 31, v0
	s_bfe_u32 s33, s33, 0x2000d
	v_lshrrev_b32_e32 v2, 26, v2
	s_add_i32 s33, s2, s33
	v_lshlrev_b32_e32 v1, 3, v4
	v_add_u32_e32 v2, v0, v2
	s_bfe_i32 s63, s33, 0x80000
	s_and_b32 s33, s33, 0xfc
	v_and_b32_e32 v1, -16, v1
	v_ashrrev_i32_e32 v3, 6, v2
	v_and_b32_e32 v9, 0xffffffc0, v2
	s_sub_i32 s2, s2, s33
	v_add_u32_e32 v1, v3, v1
	v_lshlrev_b32_e32 v3, 5, v4
	v_sub_u32_e32 v0, v0, v9
	s_sext_i32_i16 s63, s63
	s_sext_i32_i8 s2, s2
	v_and_b32_e32 v5, 32, v3
	v_ashrrev_i16_sdwa v0, v134, sext(v0) dst_sel:DWORD dst_unused:UNUSED_PAD src0_sel:DWORD src1_sel:BYTE_0
	v_lshlrev_b32_e32 v3, 1, v1
	s_add_i32 s62, s62, s2
	s_lshl_b32 s2, s63, 6
	v_bfe_i32 v6, v0, 0, 16
	v_and_b32_e32 v7, 0xffffffc0, v3
	v_lshlrev_b32_e32 v3, 2, v1
	s_and_b32 s64, s2, 0xffffff00
	v_add_u32_e32 v0, v5, v6
	v_and_b32_e32 v8, 60, v3
	v_bfe_u32 v10, v1, 4, 1
	v_lshl_add_u32 v2, v1, 6, v0
	v_or3_b32 v1, v7, v8, v10
	s_ashr_i32 s65, s64, 31
	v_lshl_add_u32 v0, v1, 11, v0
	s_lshl_b64 s[66:67], s[64:65], 12
	s_add_u32 s68, s4, s66
	v_ashrrev_i32_e32 v1, 31, v0
	s_addc_u32 s69, s5, s67
	v_lshlrev_b64 v[12:13], 1, v[0:1]
	s_ashr_i32 s63, s62, 31
	v_lshl_add_u64 v[0:1], s[68:69], 0, v[12:13]
	s_lshl_b64 s[68:69], s[62:63], 20
	s_add_u32 s70, s1, s68
	v_add_u32_e32 v144, s76, v11
	s_addc_u32 s71, s3, s69
	v_ashrrev_i32_e32 v3, 31, v2
	v_readfirstlane_b32 s2, v144
	v_add_u32_e32 v145, 0x2000, v144
	v_lshl_add_u64 v[128:129], v[2:3], 1, s[70:71]
	s_or_b32 s70, s64, 2
	s_mov_b32 m0, s2
	v_readfirstlane_b32 s2, v145
	v_add_u32_e32 v147, 0, v11
	s_ashr_i32 s71, s70, 31
	global_load_lds_dwordx4 v[0:1], off
	v_lshl_add_u64 v[14:15], v[0:1], 0, s[10:11]
	s_mov_b32 m0, s2
	v_readfirstlane_b32 s2, v147
	v_add_u32_e32 v148, 0x2000, v147
	s_lshl_b64 s[70:71], s[70:71], 12
	global_load_lds_dwordx4 v[14:15], off
	s_mov_b32 m0, s2
	v_readfirstlane_b32 s2, v148
	s_add_u32 s70, s4, s70
	v_add_u32_e32 v150, s77, v11
	global_load_lds_dwordx4 v[128:129], off
	v_lshl_add_u64 v[2:3], v[128:129], 0, s[12:13]
	s_mov_b32 m0, s2
	s_addc_u32 s71, s5, s71
	v_readfirstlane_b32 s2, v150
	v_add_u32_e32 v151, 0x2000, v150
	global_load_lds_dwordx4 v[2:3], off
	v_lshl_add_u64 v[2:3], s[70:71], 0, v[12:13]
	s_mov_b32 m0, s2
	v_readfirstlane_b32 s2, v151
	v_add_u32_e32 v152, 0x4000, v147
	global_load_lds_dwordx4 v[2:3], off
	v_lshl_add_u64 v[12:13], v[2:3], 0, s[10:11]
	s_mov_b32 m0, s2
	v_readfirstlane_b32 s2, v152
	v_add_u32_e32 v153, 0x6000, v147
	global_load_lds_dwordx4 v[12:13], off
	v_lshl_add_u64 v[12:13], v[128:129], 0, s[14:15]
	s_mov_b32 m0, s2
	v_readfirstlane_b32 s2, v153
	global_load_lds_dwordx4 v[12:13], off
	v_lshl_add_u64 v[12:13], v[128:129], 0, s[16:17]
	s_mov_b32 m0, s2
	s_nop 0
	global_load_lds_dwordx4 v[12:13], off
	v_mov_b32_e32 v20, 0
	v_mov_b32_e32 v21, 0
	v_mov_b32_e32 v22, 0
	v_mov_b32_e32 v23, 0
	v_mov_b32_e32 v24, 0
	v_mov_b32_e32 v25, 0
	v_mov_b32_e32 v26, 0
	v_mov_b32_e32 v27, 0
	v_mov_b32_e32 v28, 0
	v_mov_b32_e32 v29, 0
	v_mov_b32_e32 v30, 0
	v_mov_b32_e32 v31, 0
	v_mov_b32_e32 v32, 0
	v_mov_b32_e32 v33, 0
	v_mov_b32_e32 v34, 0
	v_mov_b32_e32 v35, 0
	v_mov_b32_e32 v36, 0
	v_mov_b32_e32 v37, 0
	v_mov_b32_e32 v38, 0
	v_mov_b32_e32 v39, 0
	v_mov_b32_e32 v40, 0
	v_mov_b32_e32 v41, 0
	v_mov_b32_e32 v42, 0
	v_mov_b32_e32 v43, 0
	v_mov_b32_e32 v44, 0
	v_mov_b32_e32 v45, 0
	v_mov_b32_e32 v46, 0
	v_mov_b32_e32 v47, 0
	v_mov_b32_e32 v48, 0
	v_mov_b32_e32 v49, 0
	v_mov_b32_e32 v50, 0
	v_mov_b32_e32 v51, 0
	v_mov_b32_e32 v52, 0
	v_mov_b32_e32 v53, 0
	v_mov_b32_e32 v54, 0
	v_mov_b32_e32 v55, 0
	v_mov_b32_e32 v56, 0
	v_mov_b32_e32 v57, 0
	v_mov_b32_e32 v58, 0
	v_mov_b32_e32 v59, 0
	v_mov_b32_e32 v60, 0
	v_mov_b32_e32 v61, 0
	v_mov_b32_e32 v62, 0
	v_mov_b32_e32 v63, 0
	v_mov_b32_e32 v64, 0
	v_mov_b32_e32 v65, 0
	v_mov_b32_e32 v66, 0
	v_mov_b32_e32 v67, 0
	v_mov_b32_e32 v68, 0
	v_mov_b32_e32 v69, 0
	v_mov_b32_e32 v70, 0
	v_mov_b32_e32 v71, 0
	v_mov_b32_e32 v72, 0
	v_mov_b32_e32 v73, 0
	v_mov_b32_e32 v74, 0
	v_mov_b32_e32 v75, 0
	v_mov_b32_e32 v76, 0
	v_mov_b32_e32 v77, 0
	v_mov_b32_e32 v78, 0
	v_mov_b32_e32 v79, 0
	v_mov_b32_e32 v80, 0
	v_mov_b32_e32 v81, 0
	v_mov_b32_e32 v82, 0
	v_mov_b32_e32 v83, 0
	v_mov_b32_e32 v84, 0
	v_mov_b32_e32 v85, 0
	v_mov_b32_e32 v86, 0
	v_mov_b32_e32 v87, 0
	v_mov_b32_e32 v88, 0
	v_mov_b32_e32 v89, 0
	v_mov_b32_e32 v90, 0
	v_mov_b32_e32 v91, 0
	v_mov_b32_e32 v92, 0
	v_mov_b32_e32 v93, 0
	v_mov_b32_e32 v94, 0
	v_mov_b32_e32 v95, 0
	v_mov_b32_e32 v96, 0
	v_mov_b32_e32 v97, 0
	v_mov_b32_e32 v98, 0
	v_mov_b32_e32 v99, 0
	v_mov_b32_e32 v100, 0
	v_mov_b32_e32 v101, 0
	v_mov_b32_e32 v102, 0
	v_mov_b32_e32 v103, 0
	v_mov_b32_e32 v104, 0
	v_mov_b32_e32 v105, 0
	v_mov_b32_e32 v106, 0
	v_mov_b32_e32 v107, 0
	v_mov_b32_e32 v108, 0
	v_mov_b32_e32 v109, 0
	v_mov_b32_e32 v110, 0
	v_mov_b32_e32 v111, 0
	v_mov_b32_e32 v112, 0
	v_mov_b32_e32 v113, 0
	v_mov_b32_e32 v114, 0
	v_mov_b32_e32 v115, 0
	v_mov_b32_e32 v116, 0
	v_mov_b32_e32 v117, 0
	v_mov_b32_e32 v118, 0
	v_mov_b32_e32 v119, 0
	v_mov_b32_e32 v120, 0
	v_mov_b32_e32 v121, 0
	v_mov_b32_e32 v122, 0
	v_mov_b32_e32 v123, 0
	v_mov_b32_e32 v124, 0
	v_mov_b32_e32 v125, 0
	v_mov_b32_e32 v126, 0
	v_mov_b32_e32 v127, 0
	v_ashrrev_i32_e32 v12, 8, v135
	v_cmp_eq_u32_e32 vcc, 1, v12
	s_and_saveexec_b64 s[70:71], vcc
	s_cbranch_execz .LBB0_85
	s_barrier
; #define STAGE_A(P, hf, kt) do { if constexpr (ABLK) { const bf16* _gp = A + ((long)(brow >> 8) * nt + (kt)) * 16384 + (hf) * 8192; GLDS2(_gp, 4096, offA, P); } \
;     else { const bf16* _gp = A + (long)(brow + (hf) * HALF) * lda + (long)(kt) * BK; GLDS2(_gp, 64 * (long)lda, offA, P); } } while (0)
; #define STAGE_B(P, hf, kt) do { const bf16* _gp = Bt + (long)(bcol + (hf) * 2) * ldb + (long)(kt) * BK; GLDS2(_gp, 128 * (long)ldb, offB, P); } while (0)
; #define WAIT_V(n) asm volatile("s_waitcnt vmcnt(" #n ")" ::: "memory")
; #define BAR __builtin_amdgcn_s_barrier()
; template <bool ABLK, class Epi>
; __device__ __forceinline__ void gemm_tile(const bf16* __restrict__ A, int lda, const bf16* __restrict__ Bt, int ldb, int K,
;                                           int brow, int bcol, bf16* shm, const Epi& epi, int wv) {
;     ...
;   if (wr == 1) BAR;
;   WAIT_V(4); BAR;
;   STAGE_B(SB(1, 0), 0, 1); STAGE_A(SA(1, 0), 0, 1); STAGE_B(SB(1, 1), 1, 1);
;   WAIT_V(6); BAR;
.LBB0_85:
	s_or_b64 exec, exec, s[70:71]
	v_add_u32_e32 v154, s78, v11
	v_add_u32_e32 v155, 0x2000, v154
	v_readfirstlane_b32 s2, v154
	v_lshl_add_u64 v[14:15], v[0:1], 0, s[18:19]
	s_mov_b32 m0, s2
	v_readfirstlane_b32 s2, v155
	v_add_u32_e32 v156, 0x8000, v147
	s_waitcnt vmcnt(4)
	s_barrier
	global_load_lds_dwordx4 v[14:15], off
	v_lshl_add_u64 v[0:1], v[0:1], 0, s[20:21]
	s_mov_b32 m0, s2
	v_readfirstlane_b32 s2, v156
	v_add_u32_e32 v157, 0xa000, v147
	global_load_lds_dwordx4 v[0:1], off
	v_lshl_add_u64 v[0:1], v[128:129], 0, s[22:23]
	s_mov_b32 m0, s2
	v_readfirstlane_b32 s2, v157
	v_add_u32_e32 v158, s79, v11
	global_load_lds_dwordx4 v[0:1], off
	v_lshl_add_u64 v[0:1], v[128:129], 0, s[24:25]
	s_mov_b32 m0, s2
	v_readfirstlane_b32 s2, v158
	v_add_u32_e32 v159, 0x2000, v158
	global_load_lds_dwordx4 v[0:1], off
	v_lshl_add_u64 v[0:1], v[2:3], 0, s[18:19]
	s_mov_b32 m0, s2
	v_readfirstlane_b32 s2, v159
	global_load_lds_dwordx4 v[0:1], off
	v_lshl_add_u64 v[0:1], v[2:3], 0, s[20:21]
	s_mov_b32 m0, s2
	v_and_b32_e32 v13, 15, v135
	global_load_lds_dwordx4 v[0:1], off
	v_bfe_u32 v136, v135, 4, 2
	v_lshlrev_b32_e32 v139, 2, v13
	v_lshlrev_b32_e32 v0, 4, v136
	v_lshlrev_b32_e32 v1, 6, v13
	v_and_b32_e32 v3, 32, v139
	v_bitop3_b32 v1, v0, v3, v1 bitop3:0x36
	v_add_u32_e32 v11, s76, v1
	v_add_u32_e32 v13, s77, v1
	v_add_u32_e32 v14, s78, v1
	v_add_u32_e32 v15, s79, v1
	v_add_u32_e32 v16, 0, v1
	v_lshlrev_b32_e32 v1, 6, v135
	v_and_or_b32 v0, v1, s80, v0
	v_xad_u32 v3, v0, v3, 0
	v_lshlrev_b32_e32 v0, 9, v4
	v_and_b32_e32 v0, 0xfffffc00, v0
	v_add_u32_e32 v0, v0, v9
	v_add3_u32 v0, v0, v5, v6
	s_add_u32 s68, s72, s68
	v_ashrrev_i32_e32 v1, 31, v0
	s_addc_u32 s69, s73, s69
	v_lshl_add_u64 v[130:131], v[0:1], 1, s[68:69]
	v_add3_u32 v0, v7, v8, v10
	v_lshl_or_b32 v0, v0, 11, v5
	v_add_u32_e32 v0, v0, v6
	s_add_u32 s66, s74, s66
	v_bfe_u32 v137, v135, 6, 2
	s_waitcnt vmcnt(6)
	v_lshlrev_b32_e32 v138, 6, v12
	v_lshlrev_b32_e32 v12, 13, v12
	v_ashrrev_i32_e32 v1, 31, v0
	s_addc_u32 s67, s75, s67
	v_lshlrev_b32_e32 v2, 12, v137
	v_or_b32_e32 v17, 0x800, v12
	v_or_b32_e32 v18, 0x1000, v12
	v_or_b32_e32 v19, 0x1800, v12
	v_lshl_add_u64 v[132:133], v[0:1], 1, s[66:67]
	v_mov_b32_e32 v0, 0
	s_mov_b32 s33, -2
	v_add_u32_e32 v161, v11, v2
	v_add_u32_e32 v143, v16, v12
	v_add_u32_e32 v142, v3, v17
	v_add_u32_e32 v141, v3, v18
	v_add_u32_e32 v140, v3, v19
	v_add_u32_e32 v160, v13, v2
	v_add_u32_e32 v149, v14, v2
	v_add_u32_e32 v146, v15, v2
	v_mov_b32_e32 v1, v0
	v_mov_b32_e32 v2, v0
	v_mov_b32_e32 v3, v0
	v_mov_b32_e32 v4, v0
	v_mov_b32_e32 v5, v0
	v_mov_b32_e32 v6, v0
	v_mov_b32_e32 v7, v0
	v_mov_b32_e32 v8, v0
	v_mov_b32_e32 v9, v0
	v_mov_b32_e32 v10, v0
	v_mov_b32_e32 v11, v0
	v_mov_b32_e32 v12, v0
	v_mov_b32_e32 v13, v0
	v_mov_b32_e32 v14, v0
	v_mov_b32_e32 v15, v0
	v_mov_b32_e32 v16, v0
	v_mov_b32_e32 v17, v0
	v_mov_b32_e32 v18, v0
	v_mov_b32_e32 v19, v0
	s_barrier

; __device__ __forceinline__ int mytid(int wv) { return (wv << 6) | (int)__builtin_amdgcn_mbcnt_hi(~0u, __builtin_amdgcn_mbcnt_lo(~0u, 0u)); }
; #define STAGE_A(P, hf, kt) do { if constexpr (ABLK) { const bf16* _gp = A + ((long)(brow >> 8) * nt + (kt)) * 16384 + (hf) * 8192; GLDS2(_gp, 4096, offA, P); } \
;     else { const bf16* _gp = A + (long)(brow + (hf) * HALF) * lda + (long)(kt) * BK; GLDS2(_gp, 64 * (long)lda, offA, P); } } while (0)
; #define STAGE_B(P, hf, kt) do { const bf16* _gp = Bt + (long)(bcol + (hf) * 2) * ldb + (long)(kt) * BK; GLDS2(_gp, 128 * (long)ldb, offB, P); } while (0)
; #define BAR __builtin_amdgcn_s_barrier()
; template <bool ABLK, class Epi>
; __device__ __forceinline__ void gemm_tile(const bf16* __restrict__ A, int lda, const bf16* __restrict__ Bt, int ldb, int K,
;                                           int brow, int bcol, bf16* shm, const Epi& epi, int wv) {
;     ...
;   int tid = mytid(wv); asm volatile("" : "+v"(tid));
;   const int wid = tid >> 6, lane = tid & 63, wr = wid >> 2, wc = wid & 3, fr = lane & 15, fq = lane >> 4;
;   f32x4 acc[2][2][4][2] = {};
;   bf16x8 At[4][2], B0[2][2], B1[2][2];
;   const int nt = K / BK;
;   int offA, offB;
;   { int r_, c_; stage_rc(tid * 16, r_, c_); offA = ABLK ? r_ * 64 + c_ : r_ * lda + c_;
;     offB = ((r_ >> 5) * 64 + (r_ & 15) * 4 + ((r_ >> 4) & 1)) * ldb + c_; }
;   STAGE_B(SB(0, 0), 0, 0); STAGE_A(SA(0, 0), 0, 0);
;   STAGE_B(SB(0, 1), 1, 0); STAGE_A(SA(0, 1), 1, 0);
;   if (wr == 1) BAR;
; template <bool ABLK, class Epi>
; __device__ __forceinline__ void gemm_phase(const bf16* A, int lda, const bf16* Bt, int ldb, int M, int N, int K, char* smem, const Epi& epi, int wv) {
;     ...
;     { int q = nwg / NXCD, r = nwg % NXCD, xcd = wgid % NXCD, off = wgid / NXCD;
;       wgid = (xcd < r ? xcd * (q + 1) : r * (q + 1) + (xcd - r) * q) + off; }
;     const int nig = WGM * nN, gid = wgid / nig, fm = gid * WGM, gsz = min(nM - fm, WGM);
;     const int pm = fm + ((wgid % nig) % gsz), pn = (wgid % nig) / gsz;
;     gemm_tile<ABLK>(A, lda, Bt, ldb, K, pm * BM, pn * BM, (bf16*)smem, epi, wv);
.LBB0_367:
	s_ashr_i32 s2, s83, 31
	s_lshr_b32 s2, s2, 29
	s_add_i32 s2, s83, s2
	s_ashr_i32 s33, s2, 3
	s_and_b32 s2, s2, -8
	v_mov_b32_e32 v128, v192
	s_sub_i32 s2, s83, s2
	s_cmp_lt_i32 s2, 0
	v_ashrrev_i32_e32 v0, 31, v128
	s_movk_i32 s58, 0xc1
	v_lshrrev_b32_e32 v0, 26, v0
	s_cselect_b32 s58, s58, 0xc0
	v_add_u32_e32 v0, v128, v0
	s_mul_i32 s2, s58, s2
	v_ashrrev_i32_e32 v4, 6, v0
	v_bfe_i32 v0, v128, 27, 1
	s_add_i32 s2, s2, s33
	v_lshlrev_b32_e32 v11, 4, v128
	v_lshrrev_b32_e32 v0, 22, v0
	s_ashr_i32 s33, s2, 31
	v_add_u32_e32 v0, v11, v0
	s_lshr_b32 s33, s33, 27
	v_and_b32_e32 v0, 0xfffffc00, v0
	s_add_i32 s33, s2, s33
	v_sub_u32_e32 v0, v11, v0
	s_ashr_i32 s58, s33, 5
	s_and_b32 s33, s33, 0xffe0
	v_lshrrev_b32_e32 v1, 4, v0
	s_sub_i32 s2, s2, s33
	v_bitop3_b32 v0, v1, v0, 32 bitop3:0x6c
	s_bfe_i32 s33, s2, 0x80000
	v_ashrrev_i32_e32 v2, 31, v0
	s_bfe_u32 s33, s33, 0x2000d
	v_lshrrev_b32_e32 v2, 26, v2
	s_add_i32 s33, s2, s33
	v_lshlrev_b32_e32 v1, 3, v4
	v_add_u32_e32 v2, v0, v2
	s_bfe_i32 s59, s33, 0x80000
	s_and_b32 s33, s33, 0xfc
	v_and_b32_e32 v1, -16, v1
	v_ashrrev_i32_e32 v3, 6, v2
	v_and_b32_e32 v9, 0xffffffc0, v2
	s_sub_i32 s2, s2, s33
	v_add_u32_e32 v1, v3, v1
	v_lshlrev_b32_e32 v3, 5, v4
	v_sub_u32_e32 v0, v0, v9
	s_lshl_b32 s58, s58, 2
	s_sext_i32_i16 s59, s59
	s_sext_i32_i8 s2, s2
	v_and_b32_e32 v5, 32, v3
	v_ashrrev_i16_sdwa v0, v140, sext(v0) dst_sel:DWORD dst_unused:UNUSED_PAD src0_sel:DWORD src1_sel:BYTE_0
	v_lshlrev_b32_e32 v3, 1, v1
	s_add_i32 s60, s58, s2
	s_lshl_b32 s2, s59, 6
	v_bfe_i32 v6, v0, 0, 16
	v_and_b32_e32 v7, 0xffffffc0, v3
	v_lshlrev_b32_e32 v3, 2, v1
	s_and_b32 s58, s2, 0xffffff00
	v_add_u32_e32 v0, v5, v6
	v_and_b32_e32 v8, 60, v3
	v_bfe_u32 v10, v1, 4, 1
	v_lshl_add_u32 v2, v1, 6, v0
	v_or3_b32 v1, v7, v8, v10
	s_ashr_i32 s59, s58, 31
	v_lshl_add_u32 v0, v1, 11, v0
	s_lshl_b64 s[62:63], s[58:59], 12
	s_add_u32 s64, s3, s62
	v_ashrrev_i32_e32 v1, 31, v0
	s_addc_u32 s65, s68, s63
	v_lshlrev_b64 v[12:13], 1, v[0:1]
	s_ashr_i32 s61, s60, 31
	v_lshl_add_u64 v[0:1], s[64:65], 0, v[12:13]
	s_lshl_b64 s[64:65], s[60:61], 20
	s_add_u32 s66, s0, s64
	s_addc_u32 s67, s1, s65
	v_ashrrev_i32_e32 v3, 31, v2
	v_add_u32_e32 v145, s73, v11
	v_lshl_add_u64 v[130:131], v[2:3], 1, s[66:67]
	s_mov_b64 s[66:67], 0x2000
	v_readfirstlane_b32 s2, v145
	v_add_u32_e32 v146, 0x2000, v145
	v_lshl_add_u64 v[2:3], v[130:131], 0, s[66:67]
	s_or_b32 s66, s58, 2
	s_mov_b32 m0, s2
	v_readfirstlane_b32 s2, v146
	v_add_u32_e32 v148, 0, v11
	s_ashr_i32 s67, s66, 31
	global_load_lds_dwordx4 v[0:1], off
	v_lshl_add_u64 v[14:15], v[0:1], 0, s[12:13]
	s_mov_b32 m0, s2
	v_readfirstlane_b32 s2, v148
	v_add_u32_e32 v149, 0x2000, v148
	s_lshl_b64 s[66:67], s[66:67], 12
	global_load_lds_dwordx4 v[14:15], off
	s_mov_b32 m0, s2
	v_readfirstlane_b32 s2, v149
	s_add_u32 s66, s3, s66
	v_add_u32_e32 v150, s74, v11
	global_load_lds_dwordx4 v[130:131], off
	s_mov_b32 m0, s2
	s_addc_u32 s67, s68, s67
	v_readfirstlane_b32 s2, v150
	v_add_u32_e32 v152, 0x2000, v150
	global_load_lds_dwordx4 v[2:3], off
	v_lshl_add_u64 v[2:3], s[66:67], 0, v[12:13]
	s_mov_b32 m0, s2
	v_readfirstlane_b32 s2, v152
	v_add_u32_e32 v153, 0x4000, v148
	global_load_lds_dwordx4 v[2:3], off
	v_lshl_add_u64 v[12:13], v[2:3], 0, s[12:13]
	s_mov_b32 m0, s2
	s_mov_b64 s[66:67], 0x4000
	v_readfirstlane_b32 s2, v153
	v_add_u32_e32 v154, 0x6000, v148
	global_load_lds_dwordx4 v[12:13], off
	v_lshl_add_u64 v[12:13], v[130:131], 0, s[66:67]
	s_mov_b32 m0, s2
	s_mov_b64 s[66:67], 0x6000
	v_readfirstlane_b32 s2, v154
	global_load_lds_dwordx4 v[12:13], off
	v_lshl_add_u64 v[12:13], v[130:131], 0, s[66:67]
	s_mov_b32 m0, s2
	s_nop 0
	global_load_lds_dwordx4 v[12:13], off
	v_mov_b32_e32 v20, 0
	v_mov_b32_e32 v21, 0
	v_mov_b32_e32 v22, 0
	v_mov_b32_e32 v23, 0
	v_mov_b32_e32 v24, 0
	v_mov_b32_e32 v25, 0
	v_mov_b32_e32 v26, 0
	v_mov_b32_e32 v27, 0
	v_mov_b32_e32 v28, 0
	v_mov_b32_e32 v29, 0
	v_mov_b32_e32 v30, 0
	v_mov_b32_e32 v31, 0
	v_mov_b32_e32 v32, 0
	v_mov_b32_e32 v33, 0
	v_mov_b32_e32 v34, 0
	v_mov_b32_e32 v35, 0
	v_mov_b32_e32 v36, 0
	v_mov_b32_e32 v37, 0
	v_mov_b32_e32 v38, 0
	v_mov_b32_e32 v39, 0
	v_mov_b32_e32 v40, 0
	v_mov_b32_e32 v41, 0
	v_mov_b32_e32 v42, 0
	v_mov_b32_e32 v43, 0
	v_mov_b32_e32 v44, 0
	v_mov_b32_e32 v45, 0
	v_mov_b32_e32 v46, 0
	v_mov_b32_e32 v47, 0
	v_mov_b32_e32 v48, 0
	v_mov_b32_e32 v49, 0
	v_mov_b32_e32 v50, 0
	v_mov_b32_e32 v51, 0
	v_mov_b32_e32 v52, 0
	v_mov_b32_e32 v53, 0
	v_mov_b32_e32 v54, 0
	v_mov_b32_e32 v55, 0
	v_mov_b32_e32 v56, 0
	v_mov_b32_e32 v57, 0
	v_mov_b32_e32 v58, 0
	v_mov_b32_e32 v59, 0
	v_mov_b32_e32 v60, 0
	v_mov_b32_e32 v61, 0
	v_mov_b32_e32 v62, 0
	v_mov_b32_e32 v63, 0
	v_mov_b32_e32 v64, 0
	v_mov_b32_e32 v65, 0
	v_mov_b32_e32 v66, 0
	v_mov_b32_e32 v67, 0
	v_mov_b32_e32 v68, 0
	v_mov_b32_e32 v69, 0
	v_mov_b32_e32 v70, 0
	v_mov_b32_e32 v71, 0
	v_mov_b32_e32 v72, 0
	v_mov_b32_e32 v73, 0
	v_mov_b32_e32 v74, 0
	v_mov_b32_e32 v75, 0
	v_mov_b32_e32 v76, 0
	v_mov_b32_e32 v77, 0
	v_mov_b32_e32 v78, 0
	v_mov_b32_e32 v79, 0
	v_mov_b32_e32 v80, 0
	v_mov_b32_e32 v81, 0
	v_mov_b32_e32 v82, 0
	v_mov_b32_e32 v83, 0
	v_mov_b32_e32 v84, 0
	v_mov_b32_e32 v85, 0
	v_mov_b32_e32 v86, 0
	v_mov_b32_e32 v87, 0
	v_mov_b32_e32 v88, 0
	v_mov_b32_e32 v89, 0
	v_mov_b32_e32 v90, 0
	v_mov_b32_e32 v91, 0
	v_mov_b32_e32 v92, 0
	v_mov_b32_e32 v93, 0
	v_mov_b32_e32 v94, 0
	v_mov_b32_e32 v95, 0
	v_mov_b32_e32 v96, 0
	v_mov_b32_e32 v97, 0
	v_mov_b32_e32 v98, 0
	v_mov_b32_e32 v99, 0
	v_mov_b32_e32 v100, 0
	v_mov_b32_e32 v101, 0
	v_mov_b32_e32 v102, 0
	v_mov_b32_e32 v103, 0
	v_mov_b32_e32 v104, 0
	v_mov_b32_e32 v105, 0
	v_mov_b32_e32 v106, 0
	v_mov_b32_e32 v107, 0
	v_mov_b32_e32 v108, 0
	v_mov_b32_e32 v109, 0
	v_mov_b32_e32 v110, 0
	v_mov_b32_e32 v111, 0
	v_mov_b32_e32 v112, 0
	v_mov_b32_e32 v113, 0
	v_mov_b32_e32 v114, 0
	v_mov_b32_e32 v115, 0
	v_mov_b32_e32 v116, 0
	v_mov_b32_e32 v117, 0
	v_mov_b32_e32 v118, 0
	v_mov_b32_e32 v119, 0
	v_mov_b32_e32 v120, 0
	v_mov_b32_e32 v121, 0
	v_mov_b32_e32 v122, 0
	v_mov_b32_e32 v123, 0
	v_mov_b32_e32 v124, 0
	v_mov_b32_e32 v125, 0
	v_mov_b32_e32 v126, 0
	v_mov_b32_e32 v127, 0
	v_ashrrev_i32_e32 v12, 8, v128
	v_cmp_eq_u32_e32 vcc, 1, v12
	s_and_saveexec_b64 s[66:67], vcc
	s_cbranch_execz .LBB0_369
	s_barrier
; #define STAGE_A(P, hf, kt) do { if constexpr (ABLK) { const bf16* _gp = A + ((long)(brow >> 8) * nt + (kt)) * 16384 + (hf) * 8192; GLDS2(_gp, 4096, offA, P); } \
;     else { const bf16* _gp = A + (long)(brow + (hf) * HALF) * lda + (long)(kt) * BK; GLDS2(_gp, 64 * (long)lda, offA, P); } } while (0)
; #define STAGE_B(P, hf, kt) do { const bf16* _gp = Bt + (long)(bcol + (hf) * 2) * ldb + (long)(kt) * BK; GLDS2(_gp, 128 * (long)ldb, offB, P); } while (0)
; #define WAIT_V(n) asm volatile("s_waitcnt vmcnt(" #n ")" ::: "memory")
; #define BAR __builtin_amdgcn_s_barrier()
; template <bool ABLK, class Epi>
; __device__ __forceinline__ void gemm_tile(const bf16* __restrict__ A, int lda, const bf16* __restrict__ Bt, int ldb, int K,
;                                           int brow, int bcol, bf16* shm, const Epi& epi, int wv) {
;     ...
;   if (wr == 1) BAR;
;   WAIT_V(4); BAR;
;   STAGE_B(SB(1, 0), 0, 1); STAGE_A(SA(1, 0), 0, 1); STAGE_B(SB(1, 1), 1, 1);
;   WAIT_V(6); BAR;
.LBB0_369:
	s_or_b64 exec, exec, s[66:67]
	v_add_u32_e32 v155, s75, v11
	v_add_u32_e32 v156, 0x2000, v155
	v_readfirstlane_b32 s2, v155
	v_lshl_add_u64 v[14:15], v[0:1], 0, s[14:15]
	s_mov_b32 m0, s2
	v_readfirstlane_b32 s2, v156
	v_add_u32_e32 v157, 0x8000, v148
	s_waitcnt vmcnt(4)
	s_barrier
	global_load_lds_dwordx4 v[14:15], off
	v_lshl_add_u64 v[0:1], v[0:1], 0, s[16:17]
	s_mov_b32 m0, s2
	v_readfirstlane_b32 s2, v157
	v_add_u32_e32 v158, 0xa000, v148
	global_load_lds_dwordx4 v[0:1], off
	v_lshl_add_u64 v[0:1], v[130:131], 0, s[18:19]
	s_mov_b32 m0, s2
	v_readfirstlane_b32 s2, v158
	v_add_u32_e32 v159, s76, v11
	global_load_lds_dwordx4 v[0:1], off
	v_lshl_add_u64 v[0:1], v[130:131], 0, s[20:21]
	s_mov_b32 m0, s2
	v_readfirstlane_b32 s2, v159
	v_add_u32_e32 v160, 0x2000, v159
	global_load_lds_dwordx4 v[0:1], off
	v_lshl_add_u64 v[0:1], v[2:3], 0, s[14:15]
	s_mov_b32 m0, s2
	v_readfirstlane_b32 s2, v160
	global_load_lds_dwordx4 v[0:1], off
	v_lshl_add_u64 v[0:1], v[2:3], 0, s[16:17]
	s_mov_b32 m0, s2
	v_and_b32_e32 v13, 15, v128
	global_load_lds_dwordx4 v[0:1], off
	v_bfe_u32 v136, v128, 4, 2
	v_lshlrev_b32_e32 v139, 2, v13
	v_lshlrev_b32_e32 v0, 4, v136
	v_lshlrev_b32_e32 v1, 6, v13
	v_and_b32_e32 v3, 32, v139
	v_bitop3_b32 v1, v0, v3, v1 bitop3:0x36
	v_add_u32_e32 v11, s73, v1
	v_add_u32_e32 v13, s74, v1
	v_add_u32_e32 v14, s75, v1
	v_add_u32_e32 v15, s76, v1
	v_add_u32_e32 v16, 0, v1
	v_lshlrev_b32_e32 v1, 6, v128
	v_and_or_b32 v0, v1, s77, v0
	v_xad_u32 v3, v0, v3, 0
	v_lshlrev_b32_e32 v0, 9, v4
	v_and_b32_e32 v0, 0xfffffc00, v0
	v_add_u32_e32 v0, v0, v9
	v_add3_u32 v0, v0, v5, v6
	s_add_u32 s64, s69, s64
	v_ashrrev_i32_e32 v1, 31, v0
	s_addc_u32 s65, s70, s65
	v_lshl_add_u64 v[132:133], v[0:1], 1, s[64:65]
	v_add3_u32 v0, v7, v8, v10
	v_lshl_or_b32 v0, v0, 11, v5
	v_add_u32_e32 v0, v0, v6
	s_add_u32 s62, s71, s62
	v_bfe_u32 v138, v128, 6, 2
	s_waitcnt vmcnt(6)
	v_lshlrev_b32_e32 v137, 6, v12
	v_lshlrev_b32_e32 v12, 13, v12
	v_ashrrev_i32_e32 v1, 31, v0
	s_addc_u32 s63, s72, s63
	v_lshlrev_b32_e32 v2, 12, v138
	v_or_b32_e32 v17, 0x800, v12
	v_or_b32_e32 v18, 0x1000, v12
	v_or_b32_e32 v19, 0x1800, v12
	v_lshl_add_u64 v[134:135], v[0:1], 1, s[62:63]
	v_mov_b32_e32 v0, 0
	s_mov_b32 s33, -2
	v_add_u32_e32 v162, v11, v2
	v_add_u32_e32 v144, v16, v12
	v_add_u32_e32 v143, v3, v17
	v_add_u32_e32 v142, v3, v18
	v_add_u32_e32 v141, v3, v19
	v_add_u32_e32 v161, v13, v2
	v_add_u32_e32 v151, v14, v2
	v_add_u32_e32 v147, v15, v2
	v_mov_b32_e32 v1, v0
	v_mov_b32_e32 v2, v0
	v_mov_b32_e32 v3, v0
	v_mov_b32_e32 v4, v0
	v_mov_b32_e32 v5, v0
	v_mov_b32_e32 v6, v0
	v_mov_b32_e32 v7, v0
	v_mov_b32_e32 v8, v0
	v_mov_b32_e32 v9, v0
	v_mov_b32_e32 v10, v0
	v_mov_b32_e32 v11, v0
	v_mov_b32_e32 v12, v0
	v_mov_b32_e32 v13, v0
	v_mov_b32_e32 v14, v0
	v_mov_b32_e32 v15, v0
	v_mov_b32_e32 v16, v0
	v_mov_b32_e32 v17, v0
	v_mov_b32_e32 v18, v0
	v_mov_b32_e32 v19, v0
	s_barrier

; __device__ __forceinline__ int mytid(int wv) { return (wv << 6) | (int)__builtin_amdgcn_mbcnt_hi(~0u, __builtin_amdgcn_mbcnt_lo(~0u, 0u)); }
; #define STAGE_A(P, hf, kt) do { if constexpr (ABLK) { const bf16* _gp = A + ((long)(brow >> 8) * nt + (kt)) * 16384 + (hf) * 8192; GLDS2(_gp, 4096, offA, P); } \
;     else { const bf16* _gp = A + (long)(brow + (hf) * HALF) * lda + (long)(kt) * BK; GLDS2(_gp, 64 * (long)lda, offA, P); } } while (0)
; #define STAGE_B(P, hf, kt) do { const bf16* _gp = Bt + (long)(bcol + (hf) * 2) * ldb + (long)(kt) * BK; GLDS2(_gp, 128 * (long)ldb, offB, P); } while (0)
; #define BAR __builtin_amdgcn_s_barrier()
; template <bool ABLK, class Epi>
; __device__ __forceinline__ void gemm_tile(const bf16* __restrict__ A, int lda, const bf16* __restrict__ Bt, int ldb, int K,
;                                           int brow, int bcol, bf16* shm, const Epi& epi, int wv) {
;     ...
;   int tid = mytid(wv); asm volatile("" : "+v"(tid));
;   const int wid = tid >> 6, lane = tid & 63, wr = wid >> 2, wc = wid & 3, fr = lane & 15, fq = lane >> 4;
;   f32x4 acc[2][2][4][2] = {};
;   bf16x8 At[4][2], B0[2][2], B1[2][2];
;   const int nt = K / BK;
;   int offA, offB;
;   { int r_, c_; stage_rc(tid * 16, r_, c_); offA = ABLK ? r_ * 64 + c_ : r_ * lda + c_;
;     offB = ((r_ >> 5) * 64 + (r_ & 15) * 4 + ((r_ >> 4) & 1)) * ldb + c_; }
;   STAGE_B(SB(0, 0), 0, 0); STAGE_A(SA(0, 0), 0, 0);
;   STAGE_B(SB(0, 1), 1, 0); STAGE_A(SA(0, 1), 1, 0);
;   if (wr == 1) BAR;
; template <bool ABLK, class Epi>
; __device__ __forceinline__ void gemm_phase(const bf16* A, int lda, const bf16* Bt, int ldb, int M, int N, int K, char* smem, const Epi& epi, int wv) {
;     ...
;     { int q = nwg / NXCD, r = nwg % NXCD, xcd = wgid % NXCD, off = wgid / NXCD;
;       wgid = (xcd < r ? xcd * (q + 1) : r * (q + 1) + (xcd - r) * q) + off; }
;     const int nig = WGM * nN, gid = wgid / nig, fm = gid * WGM, gsz = min(nM - fm, WGM);
;     const int pm = fm + ((wgid % nig) % gsz), pn = (wgid % nig) / gsz;
;     gemm_tile<ABLK>(A, lda, Bt, ldb, K, pm * BM, pn * BM, (bf16*)smem, epi, wv);
.LBB0_582:
	s_ashr_i32 s2, s83, 31
	s_lshr_b32 s2, s2, 29
	s_add_i32 s2, s83, s2
	s_ashr_i32 s33, s2, 3
	s_and_b32 s2, s2, -8
	v_mov_b32_e32 v128, v192
	s_sub_i32 s2, s83, s2
	s_cmp_lt_i32 s2, 0
	v_ashrrev_i32_e32 v0, 31, v128
	s_movk_i32 s60, 0x421
	v_lshrrev_b32_e32 v0, 26, v0
	s_cselect_b32 s60, s60, 0x420
	v_add_u32_e32 v0, v128, v0
	s_mul_i32 s2, s60, s2
	v_ashrrev_i32_e32 v4, 6, v0
	v_bfe_i32 v0, v128, 27, 1
	s_add_i32 s2, s2, s33
	v_lshlrev_b32_e32 v11, 4, v128
	v_lshrrev_b32_e32 v0, 22, v0
	s_mul_hi_i32 s33, s2, 0x2e8ba2e9
	v_add_u32_e32 v0, v11, v0
	s_lshr_b32 s60, s33, 31
	s_ashr_i32 s33, s33, 5
	v_and_b32_e32 v0, 0xfffffc00, v0
	s_add_i32 s33, s33, s60
	v_sub_u32_e32 v0, v11, v0
	s_lshl_b32 s60, s33, 2
	s_mulk_i32 s33, 0xb0
	v_lshrrev_b32_e32 v1, 4, v0
	s_sub_i32 s2, s2, s33
	v_bitop3_b32 v0, v1, v0, 32 bitop3:0x6c
	s_sext_i32_i16 s33, s2
	v_ashrrev_i32_e32 v2, 31, v0
	s_bfe_u32 s33, s33, 0x2001d
	v_lshrrev_b32_e32 v2, 26, v2
	s_add_i32 s33, s2, s33
	v_lshlrev_b32_e32 v1, 3, v4
	v_add_u32_e32 v2, v0, v2
	s_sext_i32_i16 s61, s33
	s_and_b32 s33, s33, 0xfffc
	v_and_b32_e32 v1, -16, v1
	v_ashrrev_i32_e32 v3, 6, v2
	v_and_b32_e32 v9, 0xffffffc0, v2
	s_sub_i32 s2, s2, s33
	v_add_u32_e32 v1, v3, v1
	v_lshlrev_b32_e32 v3, 5, v4
	v_sub_u32_e32 v0, v0, v9
	s_sext_i32_i16 s2, s2
	v_and_b32_e32 v5, 32, v3
	v_ashrrev_i16_sdwa v0, v136, sext(v0) dst_sel:DWORD dst_unused:UNUSED_PAD src0_sel:DWORD src1_sel:BYTE_0
	v_lshlrev_b32_e32 v3, 1, v1
	s_add_i32 s62, s60, s2
	s_lshl_b32 s2, s61, 6
	v_bfe_i32 v6, v0, 0, 16
	v_and_b32_e32 v7, 0xffffffc0, v3
	v_lshlrev_b32_e32 v3, 2, v1
	s_and_b32 s60, s2, 0xffffff00
	v_add_u32_e32 v0, v5, v6
	v_and_b32_e32 v8, 60, v3
	v_bfe_u32 v10, v1, 4, 1
	v_lshl_add_u32 v2, v1, 6, v0
	v_or3_b32 v1, v7, v8, v10
	s_ashr_i32 s61, s60, 31
	v_lshl_add_u32 v0, v1, 11, v0
	s_lshl_b64 s[64:65], s[60:61], 12
	s_add_u32 s66, s3, s64
	v_ashrrev_i32_e32 v1, 31, v0
	s_addc_u32 s67, s70, s65
	v_lshlrev_b64 v[12:13], 1, v[0:1]
	s_ashr_i32 s63, s62, 31
	v_lshl_add_u64 v[0:1], s[66:67], 0, v[12:13]
	s_lshl_b64 s[66:67], s[62:63], 20
	s_add_u32 s68, s0, s66
	s_addc_u32 s69, s1, s67
	v_ashrrev_i32_e32 v3, 31, v2
	v_add_u32_e32 v145, s75, v11
	v_lshl_add_u64 v[130:131], v[2:3], 1, s[68:69]
	s_mov_b64 s[68:69], 0x2000
	v_readfirstlane_b32 s2, v145
	v_add_u32_e32 v146, 0x2000, v145
	v_lshl_add_u64 v[2:3], v[130:131], 0, s[68:69]
	s_or_b32 s68, s60, 2
	s_mov_b32 m0, s2
	v_readfirstlane_b32 s2, v146
	v_add_u32_e32 v148, 0, v11
	s_ashr_i32 s69, s68, 31
	global_load_lds_dwordx4 v[0:1], off
	v_lshl_add_u64 v[14:15], v[0:1], 0, s[8:9]
	s_mov_b32 m0, s2
	v_readfirstlane_b32 s2, v148
	v_add_u32_e32 v149, 0x2000, v148
	s_lshl_b64 s[68:69], s[68:69], 12
	global_load_lds_dwordx4 v[14:15], off
	s_mov_b32 m0, s2
	v_readfirstlane_b32 s2, v149
	s_add_u32 s68, s3, s68
	v_add_u32_e32 v151, s76, v11
	global_load_lds_dwordx4 v[130:131], off
	s_mov_b32 m0, s2
	s_addc_u32 s69, s70, s69
	v_readfirstlane_b32 s2, v151
	v_add_u32_e32 v152, 0x2000, v151
	global_load_lds_dwordx4 v[2:3], off
	v_lshl_add_u64 v[2:3], s[68:69], 0, v[12:13]
	s_mov_b32 m0, s2
	v_readfirstlane_b32 s2, v152
	v_add_u32_e32 v153, 0x4000, v148
	global_load_lds_dwordx4 v[2:3], off
	v_lshl_add_u64 v[12:13], v[2:3], 0, s[8:9]
	s_mov_b32 m0, s2
	v_readfirstlane_b32 s2, v153
	v_add_u32_e32 v154, 0x6000, v148
	global_load_lds_dwordx4 v[12:13], off
	v_lshl_add_u64 v[12:13], v[130:131], 0, s[10:11]
	s_mov_b32 m0, s2
	v_readfirstlane_b32 s2, v154
	global_load_lds_dwordx4 v[12:13], off
	v_lshl_add_u64 v[12:13], v[130:131], 0, s[12:13]
	s_mov_b32 m0, s2
	s_nop 0
	global_load_lds_dwordx4 v[12:13], off
	v_mov_b32_e32 v20, 0
	v_mov_b32_e32 v21, 0
	v_mov_b32_e32 v22, 0
	v_mov_b32_e32 v23, 0
	v_mov_b32_e32 v24, 0
	v_mov_b32_e32 v25, 0
	v_mov_b32_e32 v26, 0
	v_mov_b32_e32 v27, 0
	v_mov_b32_e32 v28, 0
	v_mov_b32_e32 v29, 0
	v_mov_b32_e32 v30, 0
	v_mov_b32_e32 v31, 0
	v_mov_b32_e32 v32, 0
	v_mov_b32_e32 v33, 0
	v_mov_b32_e32 v34, 0
	v_mov_b32_e32 v35, 0
	v_mov_b32_e32 v36, 0
	v_mov_b32_e32 v37, 0
	v_mov_b32_e32 v38, 0
	v_mov_b32_e32 v39, 0
	v_mov_b32_e32 v40, 0
	v_mov_b32_e32 v41, 0
	v_mov_b32_e32 v42, 0
	v_mov_b32_e32 v43, 0
	v_mov_b32_e32 v44, 0
	v_mov_b32_e32 v45, 0
	v_mov_b32_e32 v46, 0
	v_mov_b32_e32 v47, 0
	v_mov_b32_e32 v48, 0
	v_mov_b32_e32 v49, 0
	v_mov_b32_e32 v50, 0
	v_mov_b32_e32 v51, 0
	v_mov_b32_e32 v52, 0
	v_mov_b32_e32 v53, 0
	v_mov_b32_e32 v54, 0
	v_mov_b32_e32 v55, 0
	v_mov_b32_e32 v56, 0
	v_mov_b32_e32 v57, 0
	v_mov_b32_e32 v58, 0
	v_mov_b32_e32 v59, 0
	v_mov_b32_e32 v60, 0
	v_mov_b32_e32 v61, 0
	v_mov_b32_e32 v62, 0
	v_mov_b32_e32 v63, 0
	v_mov_b32_e32 v64, 0
	v_mov_b32_e32 v65, 0
	v_mov_b32_e32 v66, 0
	v_mov_b32_e32 v67, 0
	v_mov_b32_e32 v68, 0
	v_mov_b32_e32 v69, 0
	v_mov_b32_e32 v70, 0
	v_mov_b32_e32 v71, 0
	v_mov_b32_e32 v72, 0
	v_mov_b32_e32 v73, 0
	v_mov_b32_e32 v74, 0
	v_mov_b32_e32 v75, 0
	v_mov_b32_e32 v76, 0
	v_mov_b32_e32 v77, 0
	v_mov_b32_e32 v78, 0
	v_mov_b32_e32 v79, 0
	v_mov_b32_e32 v80, 0
	v_mov_b32_e32 v81, 0
	v_mov_b32_e32 v82, 0
	v_mov_b32_e32 v83, 0
	v_mov_b32_e32 v84, 0
	v_mov_b32_e32 v85, 0
	v_mov_b32_e32 v86, 0
	v_mov_b32_e32 v87, 0
	v_mov_b32_e32 v88, 0
	v_mov_b32_e32 v89, 0
	v_mov_b32_e32 v90, 0
	v_mov_b32_e32 v91, 0
	v_mov_b32_e32 v92, 0
	v_mov_b32_e32 v93, 0
	v_mov_b32_e32 v94, 0
	v_mov_b32_e32 v95, 0
	v_mov_b32_e32 v96, 0
	v_mov_b32_e32 v97, 0
	v_mov_b32_e32 v98, 0
	v_mov_b32_e32 v99, 0
	v_mov_b32_e32 v100, 0
	v_mov_b32_e32 v101, 0
	v_mov_b32_e32 v102, 0
	v_mov_b32_e32 v103, 0
	v_mov_b32_e32 v104, 0
	v_mov_b32_e32 v105, 0
	v_mov_b32_e32 v106, 0
	v_mov_b32_e32 v107, 0
	v_mov_b32_e32 v108, 0
	v_mov_b32_e32 v109, 0
	v_mov_b32_e32 v110, 0
	v_mov_b32_e32 v111, 0
	v_mov_b32_e32 v112, 0
	v_mov_b32_e32 v113, 0
	v_mov_b32_e32 v114, 0
	v_mov_b32_e32 v115, 0
	v_mov_b32_e32 v116, 0
	v_mov_b32_e32 v117, 0
	v_mov_b32_e32 v118, 0
	v_mov_b32_e32 v119, 0
	v_mov_b32_e32 v120, 0
	v_mov_b32_e32 v121, 0
	v_mov_b32_e32 v122, 0
	v_mov_b32_e32 v123, 0
	v_mov_b32_e32 v124, 0
	v_mov_b32_e32 v125, 0
	v_mov_b32_e32 v126, 0
	v_mov_b32_e32 v127, 0
	v_ashrrev_i32_e32 v12, 8, v128
	v_cmp_eq_u32_e32 vcc, 1, v12
	s_and_saveexec_b64 s[68:69], vcc
	s_cbranch_execz .LBB0_584
	s_barrier
; #define STAGE_A(P, hf, kt) do { if constexpr (ABLK) { const bf16* _gp = A + ((long)(brow >> 8) * nt + (kt)) * 16384 + (hf) * 8192; GLDS2(_gp, 4096, offA, P); } \
;     else { const bf16* _gp = A + (long)(brow + (hf) * HALF) * lda + (long)(kt) * BK; GLDS2(_gp, 64 * (long)lda, offA, P); } } while (0)
; #define STAGE_B(P, hf, kt) do { const bf16* _gp = Bt + (long)(bcol + (hf) * 2) * ldb + (long)(kt) * BK; GLDS2(_gp, 128 * (long)ldb, offB, P); } while (0)
; #define WAIT_V(n) asm volatile("s_waitcnt vmcnt(" #n ")" ::: "memory")
; #define BAR __builtin_amdgcn_s_barrier()
; template <bool ABLK, class Epi>
; __device__ __forceinline__ void gemm_tile(const bf16* __restrict__ A, int lda, const bf16* __restrict__ Bt, int ldb, int K,
;                                           int brow, int bcol, bf16* shm, const Epi& epi, int wv) {
;     ...
;   if (wr == 1) BAR;
;   WAIT_V(4); BAR;
;   STAGE_B(SB(1, 0), 0, 1); STAGE_A(SA(1, 0), 0, 1); STAGE_B(SB(1, 1), 1, 1);
;   WAIT_V(6); BAR;
.LBB0_584:
	s_or_b64 exec, exec, s[68:69]
	v_add_u32_e32 v155, s77, v11
	v_add_u32_e32 v156, 0x2000, v155
	v_readfirstlane_b32 s2, v155
	v_lshl_add_u64 v[14:15], v[0:1], 0, s[14:15]
	s_mov_b32 m0, s2
	v_readfirstlane_b32 s2, v156
	v_add_u32_e32 v157, 0x8000, v148
	s_waitcnt vmcnt(4)
	s_barrier
	global_load_lds_dwordx4 v[14:15], off
	v_lshl_add_u64 v[0:1], v[0:1], 0, s[16:17]
	s_mov_b32 m0, s2
	v_readfirstlane_b32 s2, v157
	v_add_u32_e32 v158, 0xa000, v148
	global_load_lds_dwordx4 v[0:1], off
	v_lshl_add_u64 v[0:1], v[130:131], 0, s[18:19]
	s_mov_b32 m0, s2
	v_readfirstlane_b32 s2, v158
	v_add_u32_e32 v159, s78, v11
	global_load_lds_dwordx4 v[0:1], off
	v_lshl_add_u64 v[0:1], v[130:131], 0, s[20:21]
	s_mov_b32 m0, s2
	v_readfirstlane_b32 s2, v159
	v_add_u32_e32 v160, 0x2000, v159
	global_load_lds_dwordx4 v[0:1], off
	v_lshl_add_u64 v[0:1], v[2:3], 0, s[14:15]
	s_mov_b32 m0, s2
	v_readfirstlane_b32 s2, v160
	global_load_lds_dwordx4 v[0:1], off
	v_lshl_add_u64 v[0:1], v[2:3], 0, s[16:17]
	s_mov_b32 m0, s2
	v_and_b32_e32 v13, 15, v128
	global_load_lds_dwordx4 v[0:1], off
	v_bfe_u32 v138, v128, 4, 2
	v_lshlrev_b32_e32 v139, 2, v13
	v_lshlrev_b32_e32 v0, 4, v138
	v_lshlrev_b32_e32 v1, 6, v13
	v_and_b32_e32 v3, 32, v139
	v_bitop3_b32 v1, v0, v3, v1 bitop3:0x36
	v_add_u32_e32 v11, s75, v1
	v_add_u32_e32 v13, s76, v1
	v_add_u32_e32 v14, s77, v1
	v_add_u32_e32 v15, s78, v1
	v_add_u32_e32 v16, 0, v1
	v_lshlrev_b32_e32 v1, 6, v128
	v_and_or_b32 v0, v1, s79, v0
	v_xad_u32 v3, v0, v3, 0
	v_lshlrev_b32_e32 v0, 9, v4
	v_and_b32_e32 v0, 0xfffffc00, v0
	v_add_u32_e32 v0, v0, v9
	v_add3_u32 v0, v0, v5, v6
	s_add_u32 s66, s71, s66
	v_ashrrev_i32_e32 v1, 31, v0
	s_addc_u32 s67, s72, s67
	v_lshl_add_u64 v[132:133], v[0:1], 1, s[66:67]
	v_add3_u32 v0, v7, v8, v10
	v_lshl_or_b32 v0, v0, 11, v5
	v_add_u32_e32 v0, v0, v6
	s_add_u32 s64, s73, s64
	v_bfe_u32 v137, v128, 6, 2
	s_waitcnt vmcnt(6)
	v_lshlrev_b32_e32 v140, 6, v12
	v_lshlrev_b32_e32 v12, 13, v12
	v_ashrrev_i32_e32 v1, 31, v0
	s_addc_u32 s65, s74, s65
	v_lshlrev_b32_e32 v2, 12, v137
	v_or_b32_e32 v17, 0x800, v12
	v_or_b32_e32 v18, 0x1000, v12
	v_or_b32_e32 v19, 0x1800, v12
	v_lshl_add_u64 v[134:135], v[0:1], 1, s[64:65]
	v_mov_b32_e32 v0, 0
	s_mov_b32 s33, -2
	v_add_u32_e32 v162, v11, v2
	v_add_u32_e32 v144, v16, v12
	v_add_u32_e32 v143, v3, v17
	v_add_u32_e32 v142, v3, v18
	v_add_u32_e32 v141, v3, v19
	v_add_u32_e32 v161, v13, v2
	v_add_u32_e32 v150, v14, v2
	v_add_u32_e32 v147, v15, v2
	v_mov_b32_e32 v1, v0
	v_mov_b32_e32 v2, v0
	v_mov_b32_e32 v3, v0
	v_mov_b32_e32 v4, v0
	v_mov_b32_e32 v5, v0
	v_mov_b32_e32 v6, v0
	v_mov_b32_e32 v7, v0
	v_mov_b32_e32 v8, v0
	v_mov_b32_e32 v9, v0
	v_mov_b32_e32 v10, v0
	v_mov_b32_e32 v11, v0
	v_mov_b32_e32 v12, v0
	v_mov_b32_e32 v13, v0
	v_mov_b32_e32 v14, v0
	v_mov_b32_e32 v15, v0
	v_mov_b32_e32 v16, v0
	v_mov_b32_e32 v17, v0
	v_mov_b32_e32 v18, v0
	v_mov_b32_e32 v19, v0
	s_barrier

; __device__ __forceinline__ int mytid(int wv) { return (wv << 6) | (int)__builtin_amdgcn_mbcnt_hi(~0u, __builtin_amdgcn_mbcnt_lo(~0u, 0u)); }
; #define STAGE_A(P, hf, kt) do { if constexpr (ABLK) { const bf16* _gp = A + ((long)(brow >> 8) * nt + (kt)) * 16384 + (hf) * 8192; GLDS2(_gp, 4096, offA, P); } \
;     else { const bf16* _gp = A + (long)(brow + (hf) * HALF) * lda + (long)(kt) * BK; GLDS2(_gp, 64 * (long)lda, offA, P); } } while (0)
; #define STAGE_B(P, hf, kt) do { const bf16* _gp = Bt + (long)(bcol + (hf) * 2) * ldb + (long)(kt) * BK; GLDS2(_gp, 128 * (long)ldb, offB, P); } while (0)
; #define BAR __builtin_amdgcn_s_barrier()
; template <bool ABLK, class Epi>
; __device__ __forceinline__ void gemm_tile(const bf16* __restrict__ A, int lda, const bf16* __restrict__ Bt, int ldb, int K,
;                                           int brow, int bcol, bf16* shm, const Epi& epi, int wv) {
;     ...
;   int tid = mytid(wv); asm volatile("" : "+v"(tid));
;   const int wid = tid >> 6, lane = tid & 63, wr = wid >> 2, wc = wid & 3, fr = lane & 15, fq = lane >> 4;
;   f32x4 acc[2][2][4][2] = {};
;   bf16x8 At[4][2], B0[2][2], B1[2][2];
;   const int nt = K / BK;
;   int offA, offB;
;   { int r_, c_; stage_rc(tid * 16, r_, c_); offA = ABLK ? r_ * 64 + c_ : r_ * lda + c_;
;     offB = ((r_ >> 5) * 64 + (r_ & 15) * 4 + ((r_ >> 4) & 1)) * ldb + c_; }
;   STAGE_B(SB(0, 0), 0, 0); STAGE_A(SA(0, 0), 0, 0);
;   STAGE_B(SB(0, 1), 1, 0); STAGE_A(SA(0, 1), 1, 0);
;   if (wr == 1) BAR;
; template <bool ABLK, class Epi>
; __device__ __forceinline__ void gemm_phase(const bf16* A, int lda, const bf16* Bt, int ldb, int M, int N, int K, char* smem, const Epi& epi, int wv) {
;     ...
;     { int q = nwg / NXCD, r = nwg % NXCD, xcd = wgid % NXCD, off = wgid / NXCD;
;       wgid = (xcd < r ? xcd * (q + 1) : r * (q + 1) + (xcd - r) * q) + off; }
;     const int nig = WGM * nN, gid = wgid / nig, fm = gid * WGM, gsz = min(nM - fm, WGM);
;     const int pm = fm + ((wgid % nig) % gsz), pn = (wgid % nig) / gsz;
;     gemm_tile<ABLK>(A, lda, Bt, ldb, K, pm * BM, pn * BM, (bf16*)smem, epi, wv);
.LBB0_629:
	v_mov_b32_e32 v136, v192
	s_ashr_i32 s2, s78, 31
	s_lshr_b32 s2, s2, 29
	v_ashrrev_i32_e32 v0, 31, v136
	v_lshrrev_b32_e32 v0, 26, v0
	s_add_i32 s2, s78, s2
	v_add_u32_e32 v0, v136, v0
	s_ashr_i32 s33, s2, 3
	s_and_b32 s2, s2, -8
	v_ashrrev_i32_e32 v2, 6, v0
	v_bfe_i32 v0, v136, 27, 1
	s_sub_i32 s2, s78, s2
	v_lshlrev_b32_e32 v9, 4, v136
	v_lshrrev_b32_e32 v0, 22, v0
	s_cmp_lt_i32 s2, 0
	s_movk_i32 s62, 0xc1
	v_add_u32_e32 v0, v9, v0
	s_cselect_b32 s62, s62, 0xc0
	v_and_b32_e32 v0, 0xfffffc00, v0
	s_mul_i32 s2, s62, s2
	v_sub_u32_e32 v0, v9, v0
	s_add_i32 s2, s2, s33
	v_lshrrev_b32_e32 v1, 4, v0
	s_ashr_i32 s33, s2, 31
	v_bitop3_b32 v0, v1, v0, 32 bitop3:0x6c
	s_lshr_b32 s33, s33, 27
	v_ashrrev_i32_e32 v3, 31, v0
	s_add_i32 s33, s2, s33
	v_lshrrev_b32_e32 v3, 26, v3
	s_ashr_i32 s62, s33, 5
	s_and_b32 s33, s33, 0xffe0
	v_add_u32_e32 v4, v0, v3
	s_sub_i32 s2, s2, s33
	v_lshlrev_b32_e32 v1, 3, v2
	v_and_b32_e32 v7, 0xffffffc0, v4
	s_bfe_i32 s33, s2, 0x80000
	v_and_b32_e32 v1, -16, v1
	v_ashrrev_i32_e32 v3, 6, v4
	v_sub_u32_e32 v0, v0, v7
	s_bfe_u32 s33, s33, 0x2000d
	v_add_u32_e32 v1, v3, v1
	v_lshlrev_b32_e32 v3, 5, v2
	v_ashrrev_i16_sdwa v0, v188, sext(v0) dst_sel:DWORD dst_unused:UNUSED_PAD src0_sel:DWORD src1_sel:BYTE_0
	s_add_i32 s33, s2, s33
	v_and_b32_e32 v3, 32, v3
	v_bfe_i32 v4, v0, 0, 16
	v_lshlrev_b32_e32 v5, 1, v1
	v_lshlrev_b32_e32 v6, 2, v1
	s_lshl_b32 s79, s62, 2
	s_bfe_i32 s62, s33, 0x80000
	v_add_u32_e32 v0, v3, v4
	v_and_b32_e32 v5, 0xffffffc0, v5
	v_and_b32_e32 v6, 60, v6
	v_bfe_u32 v8, v1, 4, 1
	s_sext_i32_i16 s62, s62
	v_lshl_add_u32 v10, v1, 6, v0
	v_or3_b32 v1, v5, v6, v8
	s_and_b32 s33, s33, 0xfc
	s_ashr_i32 s80, s62, 2
	v_mad_u64_u32 v[0:1], s[62:63], v1, s0, v[0:1]
	s_sub_i32 s2, s2, s33
	s_mul_i32 s62, s80, 0x160000
	s_sext_i32_i8 s2, s2
	s_ashr_i32 s63, s62, 31
	s_add_i32 s79, s79, s2
	s_lshl_b64 s[62:63], s[62:63], 1
	s_add_u32 s64, s66, s62
	s_addc_u32 s65, s67, s63
	v_ashrrev_i32_e32 v1, 31, v0
	v_add_u32_e32 v134, s72, v9
	v_lshl_add_u64 v[0:1], v[0:1], 1, s[64:65]
	v_readfirstlane_b32 s2, v134
	s_mov_b64 s[64:65], 0x160000
	v_add_u32_e32 v135, 0x2000, v134
	s_mul_i32 s81, s79, 0x2c0000
	s_mov_b32 m0, s2
	v_lshl_add_u64 v[12:13], v[0:1], 0, s[64:65]
	v_readfirstlane_b32 s2, v135
	s_mul_hi_i32 s33, s79, 0x2c0000
	s_add_u32 s64, s1, s81
	v_add_u32_e32 v141, 0, v9
	global_load_lds_dwordx4 v[0:1], off
	s_mov_b32 m0, s2
	s_addc_u32 s65, s3, s33
	v_ashrrev_i32_e32 v11, 31, v10
	v_readfirstlane_b32 s2, v141
	v_add_u32_e32 v142, 0x2000, v141
	global_load_lds_dwordx4 v[12:13], off
	v_lshl_add_u64 v[128:129], v[10:11], 1, s[64:65]
	s_mov_b32 m0, s2
	s_mov_b64 s[64:65], 0x2000
	v_readfirstlane_b32 s2, v142
	v_add_u32_e32 v143, s73, v9
	global_load_lds_dwordx4 v[128:129], off
	v_lshl_add_u64 v[10:11], v[128:129], 0, s[64:65]
	s_mov_b32 m0, s2
	s_mov_b64 s[64:65], 0x5800
	v_readfirstlane_b32 s2, v143
	v_add_u32_e32 v150, 0x2000, v143
	global_load_lds_dwordx4 v[10:11], off
	v_lshl_add_u64 v[10:11], v[0:1], 0, s[64:65]
	s_mov_b32 m0, s2
	s_mov_b64 s[64:65], 0x165800
	v_readfirstlane_b32 s2, v150
	v_add_u32_e32 v151, 0x4000, v141
	global_load_lds_dwordx4 v[10:11], off
	v_lshl_add_u64 v[10:11], v[0:1], 0, s[64:65]
	s_mov_b32 m0, s2
	s_mov_b64 s[64:65], 0x4000
	v_readfirstlane_b32 s2, v151
	v_add_u32_e32 v152, 0x6000, v141
	global_load_lds_dwordx4 v[10:11], off
	v_lshl_add_u64 v[10:11], v[128:129], 0, s[64:65]
	s_mov_b32 m0, s2
	v_readfirstlane_b32 s2, v152
	global_load_lds_dwordx4 v[10:11], off
	v_lshl_add_u64 v[10:11], v[128:129], 0, s[8:9]
	s_mov_b32 m0, s2
	s_nop 0
	global_load_lds_dwordx4 v[10:11], off
	v_mov_b32_e32 v20, 0
	v_mov_b32_e32 v21, 0
	v_mov_b32_e32 v22, 0
	v_mov_b32_e32 v23, 0
	v_mov_b32_e32 v24, 0
	v_mov_b32_e32 v25, 0
	v_mov_b32_e32 v26, 0
	v_mov_b32_e32 v27, 0
	v_mov_b32_e32 v28, 0
	v_mov_b32_e32 v29, 0
	v_mov_b32_e32 v30, 0
	v_mov_b32_e32 v31, 0
	v_mov_b32_e32 v32, 0
	v_mov_b32_e32 v33, 0
	v_mov_b32_e32 v34, 0
	v_mov_b32_e32 v35, 0
	v_mov_b32_e32 v36, 0
	v_mov_b32_e32 v37, 0
	v_mov_b32_e32 v38, 0
	v_mov_b32_e32 v39, 0
	v_mov_b32_e32 v40, 0
	v_mov_b32_e32 v41, 0
	v_mov_b32_e32 v42, 0
	v_mov_b32_e32 v43, 0
	v_mov_b32_e32 v44, 0
	v_mov_b32_e32 v45, 0
	v_mov_b32_e32 v46, 0
	v_mov_b32_e32 v47, 0
	v_mov_b32_e32 v48, 0
	v_mov_b32_e32 v49, 0
	v_mov_b32_e32 v50, 0
	v_mov_b32_e32 v51, 0
	v_mov_b32_e32 v52, 0
	v_mov_b32_e32 v53, 0
	v_mov_b32_e32 v54, 0
	v_mov_b32_e32 v55, 0
	v_mov_b32_e32 v56, 0
	v_mov_b32_e32 v57, 0
	v_mov_b32_e32 v58, 0
	v_mov_b32_e32 v59, 0
	v_mov_b32_e32 v60, 0
	v_mov_b32_e32 v61, 0
	v_mov_b32_e32 v62, 0
	v_mov_b32_e32 v63, 0
	v_mov_b32_e32 v64, 0
	v_mov_b32_e32 v65, 0
	v_mov_b32_e32 v66, 0
	v_mov_b32_e32 v67, 0
	v_mov_b32_e32 v68, 0
	v_mov_b32_e32 v69, 0
	v_mov_b32_e32 v70, 0
	v_mov_b32_e32 v71, 0
	v_mov_b32_e32 v72, 0
	v_mov_b32_e32 v73, 0
	v_mov_b32_e32 v74, 0
	v_mov_b32_e32 v75, 0
	v_mov_b32_e32 v76, 0
	v_mov_b32_e32 v77, 0
	v_mov_b32_e32 v78, 0
	v_mov_b32_e32 v79, 0
	v_mov_b32_e32 v80, 0
	v_mov_b32_e32 v81, 0
	v_mov_b32_e32 v82, 0
	v_mov_b32_e32 v83, 0
	v_mov_b32_e32 v84, 0
	v_mov_b32_e32 v85, 0
	v_mov_b32_e32 v86, 0
	v_mov_b32_e32 v87, 0
	v_mov_b32_e32 v88, 0
	v_mov_b32_e32 v89, 0
	v_mov_b32_e32 v90, 0
	v_mov_b32_e32 v91, 0
	v_mov_b32_e32 v92, 0
	v_mov_b32_e32 v93, 0
	v_mov_b32_e32 v94, 0
	v_mov_b32_e32 v95, 0
	v_mov_b32_e32 v96, 0
	v_mov_b32_e32 v97, 0
	v_mov_b32_e32 v98, 0
	v_mov_b32_e32 v99, 0
	v_mov_b32_e32 v100, 0
	v_mov_b32_e32 v101, 0
	v_mov_b32_e32 v102, 0
	v_mov_b32_e32 v103, 0
	v_mov_b32_e32 v104, 0
	v_mov_b32_e32 v105, 0
	v_mov_b32_e32 v106, 0
	v_mov_b32_e32 v107, 0
	v_mov_b32_e32 v108, 0
	v_mov_b32_e32 v109, 0
	v_mov_b32_e32 v110, 0
	v_mov_b32_e32 v111, 0
	v_mov_b32_e32 v112, 0
	v_mov_b32_e32 v113, 0
	v_mov_b32_e32 v114, 0
	v_mov_b32_e32 v115, 0
	v_mov_b32_e32 v116, 0
	v_mov_b32_e32 v117, 0
	v_mov_b32_e32 v118, 0
	v_mov_b32_e32 v119, 0
	v_mov_b32_e32 v120, 0
	v_mov_b32_e32 v121, 0
	v_mov_b32_e32 v122, 0
	v_mov_b32_e32 v123, 0
	v_mov_b32_e32 v124, 0
	v_mov_b32_e32 v125, 0
	v_mov_b32_e32 v126, 0
	v_mov_b32_e32 v127, 0
	v_ashrrev_i32_e32 v10, 8, v136
	v_cmp_eq_u32_e32 vcc, 1, v10
	s_and_saveexec_b64 s[64:65], vcc
	s_cbranch_execz .LBB0_631
	s_barrier
; #define STAGE_A(P, hf, kt) do { if constexpr (ABLK) { const bf16* _gp = A + ((long)(brow >> 8) * nt + (kt)) * 16384 + (hf) * 8192; GLDS2(_gp, 4096, offA, P); } \
;     else { const bf16* _gp = A + (long)(brow + (hf) * HALF) * lda + (long)(kt) * BK; GLDS2(_gp, 64 * (long)lda, offA, P); } } while (0)
; #define STAGE_B(P, hf, kt) do { const bf16* _gp = Bt + (long)(bcol + (hf) * 2) * ldb + (long)(kt) * BK; GLDS2(_gp, 128 * (long)ldb, offB, P); } while (0)
; #define WAIT_V(n) asm volatile("s_waitcnt vmcnt(" #n ")" ::: "memory")
; #define BAR __builtin_amdgcn_s_barrier()
; template <bool ABLK, class Epi>
; __device__ __forceinline__ void gemm_tile(const bf16* __restrict__ A, int lda, const bf16* __restrict__ Bt, int ldb, int K,
;                                           int brow, int bcol, bf16* shm, const Epi& epi, int wv) {
;     ...
;   if (wr == 1) BAR;
;   WAIT_V(4); BAR;
;   STAGE_B(SB(1, 0), 0, 1); STAGE_A(SA(1, 0), 0, 1); STAGE_B(SB(1, 1), 1, 1);
;   WAIT_V(6); BAR;
.LBB0_631:
	s_or_b64 exec, exec, s[64:65]
	v_add_u32_e32 v153, s74, v9
	v_add_u32_e32 v154, 0x2000, v153
	v_readfirstlane_b32 s2, v153
	v_lshl_add_u64 v[12:13], v[0:1], 0, s[10:11]
	s_mov_b32 m0, s2
	v_readfirstlane_b32 s2, v154
	v_add_u32_e32 v155, 0x8000, v141
	s_waitcnt vmcnt(4)
	s_barrier
	global_load_lds_dwordx4 v[12:13], off
	v_lshl_add_u64 v[12:13], v[0:1], 0, s[12:13]
	s_mov_b32 m0, s2
	v_readfirstlane_b32 s2, v155
	v_add_u32_e32 v156, 0xa000, v141
	global_load_lds_dwordx4 v[12:13], off
	v_lshl_add_u64 v[12:13], v[128:129], 0, s[14:15]
	s_mov_b32 m0, s2
	v_readfirstlane_b32 s2, v156
	v_add_u32_e32 v157, s75, v9
	global_load_lds_dwordx4 v[12:13], off
	v_lshl_add_u64 v[12:13], v[128:129], 0, s[16:17]
	s_mov_b32 m0, s2
	v_readfirstlane_b32 s2, v157
	v_add_u32_e32 v158, 0x2000, v157
	global_load_lds_dwordx4 v[12:13], off
	v_lshl_add_u64 v[12:13], v[0:1], 0, s[18:19]
	s_mov_b32 m0, s2
	v_readfirstlane_b32 s2, v158
	global_load_lds_dwordx4 v[12:13], off
	v_lshl_add_u64 v[0:1], v[0:1], 0, s[20:21]
	s_mov_b32 m0, s2
	v_and_b32_e32 v11, 15, v136
	global_load_lds_dwordx4 v[0:1], off
	v_bfe_u32 v138, v136, 4, 2
	v_lshlrev_b32_e32 v139, 2, v11
	v_lshlrev_b32_e32 v0, 4, v138
	v_lshlrev_b32_e32 v1, 6, v11
	v_and_b32_e32 v11, 32, v139
	v_bitop3_b32 v1, v0, v11, v1 bitop3:0x36
	v_add_u32_e32 v12, s72, v1
	v_add_u32_e32 v13, s73, v1
	v_add_u32_e32 v14, s74, v1
	v_add_u32_e32 v15, s75, v1
	v_add_u32_e32 v16, 0, v1
	v_lshlrev_b32_e32 v1, 6, v136
	v_and_or_b32 v0, v1, s76, v0
	v_xad_u32 v11, v0, v11, 0
	v_lshlrev_b32_e32 v0, 9, v2
	v_and_b32_e32 v0, 0xfffffc00, v0
	v_add_u32_e32 v0, v0, v7
	v_add3_u32 v0, v0, v3, v4
	s_add_u32 s64, s68, s81
	v_ashrrev_i32_e32 v1, 31, v0
	s_addc_u32 s65, s69, s33
	v_lshl_add_u64 v[130:131], v[0:1], 1, s[64:65]
	v_add3_u32 v0, v5, v6, v8
	v_mul_lo_u32 v0, v0, s0
	v_or_b32_e32 v0, v0, v3
	v_add_u32_e32 v0, v0, v4
	s_add_u32 s62, s70, s62
	v_bfe_u32 v137, v136, 6, 2
	s_waitcnt vmcnt(6)
	v_lshlrev_b32_e32 v144, 6, v10
	v_lshlrev_b32_e32 v10, 13, v10
	v_ashrrev_i32_e32 v1, 31, v0
	s_addc_u32 s63, s71, s63
	v_lshlrev_b32_e32 v9, 12, v137
	v_or_b32_e32 v17, 0x800, v10
	v_or_b32_e32 v18, 0x1000, v10
	v_or_b32_e32 v19, 0x1800, v10
	v_lshl_add_u64 v[132:133], v[0:1], 1, s[62:63]
	v_mov_b32_e32 v0, 0
	s_mov_b32 s33, -2
	v_add_u32_e32 v160, v12, v9
	v_add_u32_e32 v148, v16, v10
	v_add_u32_e32 v147, v11, v17
	v_add_u32_e32 v146, v11, v18
	v_add_u32_e32 v145, v11, v19
	v_add_u32_e32 v159, v13, v9
	v_add_u32_e32 v149, v14, v9
	v_add_u32_e32 v140, v15, v9
	v_mov_b32_e32 v1, v0
	v_mov_b32_e32 v2, v0
	v_mov_b32_e32 v3, v0
	v_mov_b32_e32 v4, v0
	v_mov_b32_e32 v5, v0
	v_mov_b32_e32 v6, v0
	v_mov_b32_e32 v7, v0
	v_mov_b32_e32 v8, v0
	v_mov_b32_e32 v9, v0
	v_mov_b32_e32 v10, v0
	v_mov_b32_e32 v11, v0
	v_mov_b32_e32 v12, v0
	v_mov_b32_e32 v13, v0
	v_mov_b32_e32 v14, v0
	v_mov_b32_e32 v15, v0
	v_mov_b32_e32 v16, v0
	v_mov_b32_e32 v17, v0
	v_mov_b32_e32 v18, v0
	v_mov_b32_e32 v19, v0
	s_barrier

; __device__ __forceinline__ int mytid(int wv) { return (wv << 6) | (int)__builtin_amdgcn_mbcnt_hi(~0u, __builtin_amdgcn_mbcnt_lo(~0u, 0u)); }
; #define STAGE_A(P, hf, kt) do { if constexpr (ABLK) { const bf16* _gp = A + ((long)(brow >> 8) * nt + (kt)) * 16384 + (hf) * 8192; GLDS2(_gp, 4096, offA, P); } \
;     else { const bf16* _gp = A + (long)(brow + (hf) * HALF) * lda + (long)(kt) * BK; GLDS2(_gp, 64 * (long)lda, offA, P); } } while (0)
; #define STAGE_B(P, hf, kt) do { const bf16* _gp = Bt + (long)(bcol + (hf) * 2) * ldb + (long)(kt) * BK; GLDS2(_gp, 128 * (long)ldb, offB, P); } while (0)
; #define BAR __builtin_amdgcn_s_barrier()
; template <bool ABLK, class Epi>
; __device__ __forceinline__ void gemm_tile(const bf16* __restrict__ A, int lda, const bf16* __restrict__ Bt, int ldb, int K,
;                                           int brow, int bcol, bf16* shm, const Epi& epi, int wv) {
;     ...
;   int tid = mytid(wv); asm volatile("" : "+v"(tid));
;   const int wid = tid >> 6, lane = tid & 63, wr = wid >> 2, wc = wid & 3, fr = lane & 15, fq = lane >> 4;
;   f32x4 acc[2][2][4][2] = {};
;   bf16x8 At[4][2], B0[2][2], B1[2][2];
;   const int nt = K / BK;
;   int offA, offB;
;   { int r_, c_; stage_rc(tid * 16, r_, c_); offA = ABLK ? r_ * 64 + c_ : r_ * lda + c_;
;     offB = ((r_ >> 5) * 64 + (r_ & 15) * 4 + ((r_ >> 4) & 1)) * ldb + c_; }
;   STAGE_B(SB(0, 0), 0, 0); STAGE_A(SA(0, 0), 0, 0);
;   STAGE_B(SB(0, 1), 1, 0); STAGE_A(SA(0, 1), 1, 0);
;   if (wr == 1) BAR;
; template <bool ABLK, class Epi>
; __device__ __forceinline__ void gemm_phase(const bf16* A, int lda, const bf16* Bt, int ldb, int M, int N, int K, char* smem, const Epi& epi, int wv) {
;     ...
;     { int q = nwg / NXCD, r = nwg % NXCD, xcd = wgid % NXCD, off = wgid / NXCD;
;       wgid = (xcd < r ? xcd * (q + 1) : r * (q + 1) + (xcd - r) * q) + off; }
;     const int nig = WGM * nN, gid = wgid / nig, fm = gid * WGM, gsz = min(nM - fm, WGM);
;     const int pm = fm + ((wgid % nig) % gsz), pn = (wgid % nig) / gsz;
;     gemm_tile<ABLK>(A, lda, Bt, ldb, K, pm * BM, pn * BM, (bf16*)smem, epi, wv);
.LBB0_716:
	s_ashr_i32 s2, s84, 31
	s_lshr_b32 s2, s2, 29
	s_add_i32 s2, s84, s2
	s_ashr_i32 s33, s2, 3
	s_and_b32 s2, s2, -8
	v_mov_b32_e32 v135, v192
	s_sub_i32 s2, s84, s2
	s_cmp_lt_i32 s2, 0
	v_ashrrev_i32_e32 v0, 31, v135
	v_lshrrev_b32_e32 v0, 26, v0
	s_cselect_b32 s62, s0, 0x60
	v_add_u32_e32 v0, v135, v0
	s_mul_i32 s2, s62, s2
	v_ashrrev_i32_e32 v4, 6, v0
	v_bfe_i32 v0, v135, 27, 1
	s_add_i32 s2, s2, s33
	v_lshlrev_b32_e32 v11, 4, v135
	v_lshrrev_b32_e32 v0, 22, v0
	s_ashr_i32 s33, s2, 31
	v_add_u32_e32 v0, v11, v0
	s_lshr_b32 s33, s33, 28
	v_and_b32_e32 v0, 0xfffffc00, v0
	s_add_i32 s33, s2, s33
	v_sub_u32_e32 v0, v11, v0
	s_ashr_i32 s62, s33, 4
	s_and_b32 s33, s33, 0xfff0
	v_lshrrev_b32_e32 v1, 4, v0
	s_sub_i32 s2, s2, s33
	v_bitop3_b32 v0, v1, v0, 32 bitop3:0x6c
	s_bfe_i32 s33, s2, 0x80000
	v_ashrrev_i32_e32 v2, 31, v0
	s_bfe_u32 s33, s33, 0x2000d
	v_lshrrev_b32_e32 v2, 26, v2
	s_add_i32 s33, s2, s33
	v_lshlrev_b32_e32 v1, 3, v4
	v_add_u32_e32 v2, v0, v2
	s_bfe_i32 s63, s33, 0x80000
	s_and_b32 s33, s33, 0xfc
	v_and_b32_e32 v1, -16, v1
	v_ashrrev_i32_e32 v3, 6, v2
	v_and_b32_e32 v9, 0xffffffc0, v2
	s_sub_i32 s2, s2, s33
	v_add_u32_e32 v1, v3, v1
	v_lshlrev_b32_e32 v3, 5, v4
	v_sub_u32_e32 v0, v0, v9
	s_lshl_b32 s62, s62, 2
	s_sext_i32_i16 s63, s63
	s_sext_i32_i8 s2, s2
	v_and_b32_e32 v5, 32, v3
	v_ashrrev_i16_sdwa v0, v134, sext(v0) dst_sel:DWORD dst_unused:UNUSED_PAD src0_sel:DWORD src1_sel:BYTE_0
	v_lshlrev_b32_e32 v3, 1, v1
	s_add_i32 s64, s62, s2
	s_lshl_b32 s2, s63, 6
	v_bfe_i32 v6, v0, 0, 16
	v_and_b32_e32 v7, 0xffffffc0, v3
	v_lshlrev_b32_e32 v3, 2, v1
	s_and_b32 s62, s2, 0xffffff00
	v_add_u32_e32 v0, v5, v6
	v_and_b32_e32 v8, 60, v3
	v_bfe_u32 v10, v1, 4, 1
	v_lshl_add_u32 v2, v1, 6, v0
	v_or3_b32 v1, v7, v8, v10
	s_ashr_i32 s63, s62, 31
	v_lshl_add_u32 v0, v1, 11, v0
	s_lshl_b64 s[66:67], s[62:63], 12
	s_add_u32 s68, s72, s66
	v_ashrrev_i32_e32 v1, 31, v0
	s_addc_u32 s69, s73, s67
	v_lshlrev_b64 v[12:13], 1, v[0:1]
	s_ashr_i32 s65, s64, 31
	v_lshl_add_u64 v[0:1], s[68:69], 0, v[12:13]
	s_lshl_b64 s[68:69], s[64:65], 20
	s_add_u32 s70, s1, s68
	v_add_u32_e32 v144, s78, v11
	s_addc_u32 s71, s3, s69
	v_ashrrev_i32_e32 v3, 31, v2
	v_readfirstlane_b32 s2, v144
	v_add_u32_e32 v145, 0x2000, v144
	v_lshl_add_u64 v[128:129], v[2:3], 1, s[70:71]
	s_or_b32 s70, s62, 2
	s_mov_b32 m0, s2
	v_readfirstlane_b32 s2, v145
	v_add_u32_e32 v147, 0, v11
	s_ashr_i32 s71, s70, 31
	global_load_lds_dwordx4 v[0:1], off
	v_lshl_add_u64 v[14:15], v[0:1], 0, s[8:9]
	s_mov_b32 m0, s2
	v_readfirstlane_b32 s2, v147
	v_add_u32_e32 v148, 0x2000, v147
	s_lshl_b64 s[70:71], s[70:71], 12
	global_load_lds_dwordx4 v[14:15], off
	s_mov_b32 m0, s2
	v_readfirstlane_b32 s2, v148
	s_add_u32 s70, s72, s70
	v_add_u32_e32 v150, s79, v11
	global_load_lds_dwordx4 v[128:129], off
	v_lshl_add_u64 v[2:3], v[128:129], 0, s[10:11]
	s_mov_b32 m0, s2
	s_addc_u32 s71, s73, s71
	v_readfirstlane_b32 s2, v150
	v_add_u32_e32 v151, 0x2000, v150
	global_load_lds_dwordx4 v[2:3], off
	v_lshl_add_u64 v[2:3], s[70:71], 0, v[12:13]
	s_mov_b32 m0, s2
	v_readfirstlane_b32 s2, v151
	v_add_u32_e32 v152, 0x4000, v147
	global_load_lds_dwordx4 v[2:3], off
	v_lshl_add_u64 v[12:13], v[2:3], 0, s[8:9]
	s_mov_b32 m0, s2
	v_readfirstlane_b32 s2, v152
	v_add_u32_e32 v153, 0x6000, v147
	global_load_lds_dwordx4 v[12:13], off
	v_lshl_add_u64 v[12:13], v[128:129], 0, s[12:13]
	s_mov_b32 m0, s2
	v_readfirstlane_b32 s2, v153
	global_load_lds_dwordx4 v[12:13], off
	v_lshl_add_u64 v[12:13], v[128:129], 0, s[14:15]
	s_mov_b32 m0, s2
	s_nop 0
	global_load_lds_dwordx4 v[12:13], off
	v_mov_b32_e32 v20, 0
	v_mov_b32_e32 v21, 0
	v_mov_b32_e32 v22, 0
	v_mov_b32_e32 v23, 0
	v_mov_b32_e32 v24, 0
	v_mov_b32_e32 v25, 0
	v_mov_b32_e32 v26, 0
	v_mov_b32_e32 v27, 0
	v_mov_b32_e32 v28, 0
	v_mov_b32_e32 v29, 0
	v_mov_b32_e32 v30, 0
	v_mov_b32_e32 v31, 0
	v_mov_b32_e32 v32, 0
	v_mov_b32_e32 v33, 0
	v_mov_b32_e32 v34, 0
	v_mov_b32_e32 v35, 0
	v_mov_b32_e32 v36, 0
	v_mov_b32_e32 v37, 0
	v_mov_b32_e32 v38, 0
	v_mov_b32_e32 v39, 0
	v_mov_b32_e32 v40, 0
	v_mov_b32_e32 v41, 0
	v_mov_b32_e32 v42, 0
	v_mov_b32_e32 v43, 0
	v_mov_b32_e32 v44, 0
	v_mov_b32_e32 v45, 0
	v_mov_b32_e32 v46, 0
	v_mov_b32_e32 v47, 0
	v_mov_b32_e32 v48, 0
	v_mov_b32_e32 v49, 0
	v_mov_b32_e32 v50, 0
	v_mov_b32_e32 v51, 0
	v_mov_b32_e32 v52, 0
	v_mov_b32_e32 v53, 0
	v_mov_b32_e32 v54, 0
	v_mov_b32_e32 v55, 0
	v_mov_b32_e32 v56, 0
	v_mov_b32_e32 v57, 0
	v_mov_b32_e32 v58, 0
	v_mov_b32_e32 v59, 0
	v_mov_b32_e32 v60, 0
	v_mov_b32_e32 v61, 0
	v_mov_b32_e32 v62, 0
	v_mov_b32_e32 v63, 0
	v_mov_b32_e32 v64, 0
	v_mov_b32_e32 v65, 0
	v_mov_b32_e32 v66, 0
	v_mov_b32_e32 v67, 0
	v_mov_b32_e32 v68, 0
	v_mov_b32_e32 v69, 0
	v_mov_b32_e32 v70, 0
	v_mov_b32_e32 v71, 0
	v_mov_b32_e32 v72, 0
	v_mov_b32_e32 v73, 0
	v_mov_b32_e32 v74, 0
	v_mov_b32_e32 v75, 0
	v_mov_b32_e32 v76, 0
	v_mov_b32_e32 v77, 0
	v_mov_b32_e32 v78, 0
	v_mov_b32_e32 v79, 0
	v_mov_b32_e32 v80, 0
	v_mov_b32_e32 v81, 0
	v_mov_b32_e32 v82, 0
	v_mov_b32_e32 v83, 0
	v_mov_b32_e32 v84, 0
	v_mov_b32_e32 v85, 0
	v_mov_b32_e32 v86, 0
	v_mov_b32_e32 v87, 0
	v_mov_b32_e32 v88, 0
	v_mov_b32_e32 v89, 0
	v_mov_b32_e32 v90, 0
	v_mov_b32_e32 v91, 0
	v_mov_b32_e32 v92, 0
	v_mov_b32_e32 v93, 0
	v_mov_b32_e32 v94, 0
	v_mov_b32_e32 v95, 0
	v_mov_b32_e32 v96, 0
	v_mov_b32_e32 v97, 0
	v_mov_b32_e32 v98, 0
	v_mov_b32_e32 v99, 0
	v_mov_b32_e32 v100, 0
	v_mov_b32_e32 v101, 0
	v_mov_b32_e32 v102, 0
	v_mov_b32_e32 v103, 0
	v_mov_b32_e32 v104, 0
	v_mov_b32_e32 v105, 0
	v_mov_b32_e32 v106, 0
	v_mov_b32_e32 v107, 0
	v_mov_b32_e32 v108, 0
	v_mov_b32_e32 v109, 0
	v_mov_b32_e32 v110, 0
	v_mov_b32_e32 v111, 0
	v_mov_b32_e32 v112, 0
	v_mov_b32_e32 v113, 0
	v_mov_b32_e32 v114, 0
	v_mov_b32_e32 v115, 0
	v_mov_b32_e32 v116, 0
	v_mov_b32_e32 v117, 0
	v_mov_b32_e32 v118, 0
	v_mov_b32_e32 v119, 0
	v_mov_b32_e32 v120, 0
	v_mov_b32_e32 v121, 0
	v_mov_b32_e32 v122, 0
	v_mov_b32_e32 v123, 0
	v_mov_b32_e32 v124, 0
	v_mov_b32_e32 v125, 0
	v_mov_b32_e32 v126, 0
	v_mov_b32_e32 v127, 0
	v_ashrrev_i32_e32 v12, 8, v135
	v_cmp_eq_u32_e32 vcc, 1, v12
	s_and_saveexec_b64 s[70:71], vcc
	s_cbranch_execz .LBB0_718
	s_barrier
; #define STAGE_A(P, hf, kt) do { if constexpr (ABLK) { const bf16* _gp = A + ((long)(brow >> 8) * nt + (kt)) * 16384 + (hf) * 8192; GLDS2(_gp, 4096, offA, P); } \
;     else { const bf16* _gp = A + (long)(brow + (hf) * HALF) * lda + (long)(kt) * BK; GLDS2(_gp, 64 * (long)lda, offA, P); } } while (0)
; #define STAGE_B(P, hf, kt) do { const bf16* _gp = Bt + (long)(bcol + (hf) * 2) * ldb + (long)(kt) * BK; GLDS2(_gp, 128 * (long)ldb, offB, P); } while (0)
; #define WAIT_V(n) asm volatile("s_waitcnt vmcnt(" #n ")" ::: "memory")
; #define BAR __builtin_amdgcn_s_barrier()
; template <bool ABLK, class Epi>
; __device__ __forceinline__ void gemm_tile(const bf16* __restrict__ A, int lda, const bf16* __restrict__ Bt, int ldb, int K,
;                                           int brow, int bcol, bf16* shm, const Epi& epi, int wv) {
;     ...
;   if (wr == 1) BAR;
;   WAIT_V(4); BAR;
;   STAGE_B(SB(1, 0), 0, 1); STAGE_A(SA(1, 0), 0, 1); STAGE_B(SB(1, 1), 1, 1);
;   WAIT_V(6); BAR;
.LBB0_718:
	s_or_b64 exec, exec, s[70:71]
	v_add_u32_e32 v154, s80, v11
	v_add_u32_e32 v155, 0x2000, v154
	v_readfirstlane_b32 s2, v154
	v_lshl_add_u64 v[14:15], v[0:1], 0, s[16:17]
	s_mov_b32 m0, s2
	v_readfirstlane_b32 s2, v155
	v_add_u32_e32 v156, 0x8000, v147
	s_waitcnt vmcnt(4)
	s_barrier
	global_load_lds_dwordx4 v[14:15], off
	v_lshl_add_u64 v[0:1], v[0:1], 0, s[18:19]
	s_mov_b32 m0, s2
	v_readfirstlane_b32 s2, v156
	v_add_u32_e32 v157, 0xa000, v147
	global_load_lds_dwordx4 v[0:1], off
	v_lshl_add_u64 v[0:1], v[128:129], 0, s[20:21]
	s_mov_b32 m0, s2
	v_readfirstlane_b32 s2, v157
	v_add_u32_e32 v158, s81, v11
	global_load_lds_dwordx4 v[0:1], off
	v_lshl_add_u64 v[0:1], v[128:129], 0, s[22:23]
	s_mov_b32 m0, s2
	v_readfirstlane_b32 s2, v158
	v_add_u32_e32 v159, 0x2000, v158
	global_load_lds_dwordx4 v[0:1], off
	v_lshl_add_u64 v[0:1], v[2:3], 0, s[16:17]
	s_mov_b32 m0, s2
	v_readfirstlane_b32 s2, v159
	global_load_lds_dwordx4 v[0:1], off
	v_lshl_add_u64 v[0:1], v[2:3], 0, s[18:19]
	s_mov_b32 m0, s2
	v_and_b32_e32 v13, 15, v135
	global_load_lds_dwordx4 v[0:1], off
	v_bfe_u32 v137, v135, 4, 2
	v_lshlrev_b32_e32 v138, 2, v13
	v_lshlrev_b32_e32 v0, 4, v137
	v_lshlrev_b32_e32 v1, 6, v13
	v_and_b32_e32 v3, 32, v138
	v_bitop3_b32 v1, v0, v3, v1 bitop3:0x36
	v_add_u32_e32 v11, s78, v1
	v_add_u32_e32 v13, s79, v1
	v_add_u32_e32 v14, s80, v1
	v_add_u32_e32 v15, s81, v1
	v_add_u32_e32 v16, 0, v1
	v_lshlrev_b32_e32 v1, 6, v135
	v_and_or_b32 v0, v1, s82, v0
	v_xad_u32 v3, v0, v3, 0
	v_lshlrev_b32_e32 v0, 9, v4
	v_and_b32_e32 v0, 0xfffffc00, v0
	v_add_u32_e32 v0, v0, v9
	v_add3_u32 v0, v0, v5, v6
	s_add_u32 s68, s74, s68
	v_ashrrev_i32_e32 v1, 31, v0
	s_addc_u32 s69, s75, s69
	v_lshl_add_u64 v[130:131], v[0:1], 1, s[68:69]
	v_add3_u32 v0, v7, v8, v10
	v_lshl_or_b32 v0, v0, 11, v5
	v_add_u32_e32 v0, v0, v6
	s_add_u32 s66, s76, s66
	v_bfe_u32 v136, v135, 6, 2
	s_waitcnt vmcnt(6)
	v_lshlrev_b32_e32 v139, 6, v12
	v_lshlrev_b32_e32 v12, 13, v12
	v_ashrrev_i32_e32 v1, 31, v0
	s_addc_u32 s67, s77, s67
	v_lshlrev_b32_e32 v2, 12, v136
	v_or_b32_e32 v17, 0x800, v12
	v_or_b32_e32 v18, 0x1000, v12
	v_or_b32_e32 v19, 0x1800, v12
	v_lshl_add_u64 v[132:133], v[0:1], 1, s[66:67]
	v_mov_b32_e32 v0, 0
	s_mov_b32 s33, -2
	v_add_u32_e32 v161, v11, v2
	v_add_u32_e32 v143, v16, v12
	v_add_u32_e32 v142, v3, v17
	v_add_u32_e32 v141, v3, v18
	v_add_u32_e32 v140, v3, v19
	v_add_u32_e32 v160, v13, v2
	v_add_u32_e32 v149, v14, v2
	v_add_u32_e32 v146, v15, v2
	v_mov_b32_e32 v1, v0
	v_mov_b32_e32 v2, v0
	v_mov_b32_e32 v3, v0
	v_mov_b32_e32 v4, v0
	v_mov_b32_e32 v5, v0
	v_mov_b32_e32 v6, v0
	v_mov_b32_e32 v7, v0
	v_mov_b32_e32 v8, v0
	v_mov_b32_e32 v9, v0
	v_mov_b32_e32 v10, v0
	v_mov_b32_e32 v11, v0
	v_mov_b32_e32 v12, v0
	v_mov_b32_e32 v13, v0
	v_mov_b32_e32 v14, v0
	v_mov_b32_e32 v15, v0
	v_mov_b32_e32 v16, v0
	v_mov_b32_e32 v17, v0
	v_mov_b32_e32 v18, v0
	v_mov_b32_e32 v19, v0
	s_barrier

; #define STAGE_A(P, hf, kt) do { if constexpr (ABLK) { const bf16* _gp = A + ((long)(brow >> 8) * nt + (kt)) * 16384 + (hf) * 8192; GLDS2(_gp, 4096, offA, P); } \
;     else { const bf16* _gp = A + (long)(brow + (hf) * HALF) * lda + (long)(kt) * BK; GLDS2(_gp, 64 * (long)lda, offA, P); } } while (0)
; #define STAGE_B(P, hf, kt) do { const bf16* _gp = Bt + (long)(bcol + (hf) * 2) * ldb + (long)(kt) * BK; GLDS2(_gp, 128 * (long)ldb, offB, P); } while (0)
; #define BAR __builtin_amdgcn_s_barrier()
; template <bool ABLK, class Epi>
; __device__ __forceinline__ void gemm_tile(const bf16* __restrict__ A, int lda, const bf16* __restrict__ Bt, int ldb, int K,
;                                           int brow, int bcol, bf16* shm, const Epi& epi, int wv) {
;     ...
;   int offA, offB;
;   { int r_, c_; stage_rc(tid * 16, r_, c_); offA = ABLK ? r_ * 64 + c_ : r_ * lda + c_;
;     offB = ((r_ >> 5) * 64 + (r_ & 15) * 4 + ((r_ >> 4) & 1)) * ldb + c_; }
;   STAGE_B(SB(0, 0), 0, 0); STAGE_A(SA(0, 0), 0, 0);
;   STAGE_B(SB(0, 1), 1, 0); STAGE_A(SA(0, 1), 1, 0);
;   if (wr == 1) BAR;
; template <bool ABLK, class Epi>
; __device__ __forceinline__ void gemm_phase(const bf16* A, int lda, const bf16* Bt, int ldb, int M, int N, int K, char* smem, const Epi& epi, int wv) {
;     ...
;     { int q = nwg / NXCD, r = nwg % NXCD, xcd = wgid % NXCD, off = wgid / NXCD;
;       wgid = (xcd < r ? xcd * (q + 1) : r * (q + 1) + (xcd - r) * q) + off; }
;     const int nig = WGM * nN, gid = wgid / nig, fm = gid * WGM, gsz = min(nM - fm, WGM);
;     const int pm = fm + ((wgid % nig) % gsz), pn = (wgid % nig) / gsz;
;     gemm_tile<ABLK>(A, lda, Bt, ldb, K, pm * BM, pn * BM, (bf16*)smem, epi, wv);
.LBB0_811:
	s_ashr_i32 s2, s82, 31
	s_lshr_b32 s2, s2, 29
	s_add_i32 s2, s82, s2
	v_mov_b32_e32 v128, v192
	s_ashr_i32 s8, s2, 3
	s_and_b32 s2, s2, -8
	s_sub_i32 s2, s82, s2
	v_ashrrev_i32_e32 v0, 31, v128
	v_lshrrev_b32_e32 v0, 26, v0
	s_cmp_lt_i32 s2, 0
	s_movk_i32 s9, 0x181
	v_add_u32_e32 v0, v128, v0
	s_cselect_b32 s9, s9, 0x180
	v_ashrrev_i32_e32 v6, 6, v0
	v_bfe_i32 v0, v128, 27, 1
	s_mul_i32 s2, s9, s2
	v_lshlrev_b32_e32 v13, 4, v128
	v_lshrrev_b32_e32 v0, 22, v0
	s_add_i32 s2, s2, s8
	v_add_u32_e32 v0, v13, v0
	s_ashr_i32 s8, s2, 31
	v_and_b32_e32 v0, 0xfffffc00, v0
	s_lshr_b32 s8, s8, 26
	v_sub_u32_e32 v0, v13, v0
	s_add_i32 s8, s2, s8
	v_lshrrev_b32_e32 v1, 4, v0
	s_and_b32 s9, s8, 0xffc0
	v_bitop3_b32 v0, v1, v0, 32 bitop3:0x6c
	s_sub_i32 s2, s2, s9
	v_ashrrev_i32_e32 v2, 31, v0
	s_bfe_i32 s9, s2, 0x80000
	v_lshrrev_b32_e32 v2, 26, v2
	s_bfe_u32 s9, s9, 0x2000d
	v_lshlrev_b32_e32 v1, 3, v6
	v_add_u32_e32 v2, v0, v2
	s_add_i32 s9, s2, s9
	v_and_b32_e32 v1, -16, v1
	v_ashrrev_i32_e32 v7, 6, v2
	s_bfe_i32 s33, s9, 0x80000
	v_add_u32_e32 v1, v7, v1
	v_and_b32_e32 v2, 0xc0, v2
	s_sext_i32_i16 s33, s33
	s_and_b32 s9, s9, 0xfc
	v_lshlrev_b32_e32 v3, 5, v6
	v_sub_u32_e32 v0, v0, v2
	v_lshlrev_b32_e32 v2, 1, v1
	s_sub_i32 s2, s2, s9
	s_ashr_i32 s83, s33, 2
	v_and_b32_e32 v8, 32, v3
	v_ashrrev_i16_sdwa v9, v138, sext(v0) dst_sel:DWORD dst_unused:UNUSED_PAD src0_sel:DWORD src1_sel:BYTE_0
	v_and_b32_e32 v10, 0xffffffc0, v2
	v_lshlrev_b32_e32 v2, 2, v1
	s_sext_i32_i8 s2, s2
	s_lshl_b32 s8, s8, 4
	s_lshl_b32 s64, s83, 8
	v_add_u32_sdwa v0, v8, sext(v9) dst_sel:DWORD dst_unused:UNUSED_PAD src0_sel:DWORD src1_sel:WORD_0
	v_and_b32_e32 v11, 60, v2
	v_bfe_u32 v12, v1, 4, 1
	s_and_b32 s8, s8, 0xfffffc00
	s_lshl_b32 s2, s2, 8
	v_lshl_add_u32 v130, v1, 9, v0
	v_or3_b32 v1, v10, v11, v12
	s_ashr_i32 s65, s64, 31
	s_add_i32 s8, s2, s8
	v_lshl_add_u32 v0, v1, 9, v0
	s_lshl_b64 s[66:67], s[64:65], 10
	s_add_u32 s68, s3, s66
	v_ashrrev_i32_e32 v1, 31, v0
	s_addc_u32 s69, s74, s67
	v_lshlrev_b64 v[4:5], 1, v[0:1]
	s_ashr_i32 s9, s8, 31
	v_lshl_add_u64 v[0:1], s[68:69], 0, v[4:5]
	s_lshl_b64 s[68:69], s[8:9], 10
	s_add_u32 s70, s0, s68
	s_addc_u32 s71, s1, s69
	s_or_b32 s64, s64, 2
	s_ashr_i32 s65, s64, 31
	v_add_u32_e32 v148, s75, v13
	s_lshl_b64 s[64:65], s[64:65], 10
	v_readfirstlane_b32 s2, v148
	v_add_u32_e32 v149, 0x2000, v148
	s_add_u32 s64, s3, s64
	s_mov_b32 m0, s2
	v_readfirstlane_b32 s2, v149
	v_ashrrev_i32_e32 v131, 31, v130
	v_add_u32_e32 v150, 0, v13
	s_addc_u32 s65, s74, s65
	global_load_lds_dwordx4 v[0:1], off
	v_lshl_add_u64 v[2:3], v[0:1], 0, s[18:19]
	s_mov_b32 m0, s2
	v_lshlrev_b64 v[14:15], 1, v[130:131]
	v_readfirstlane_b32 s2, v150
	v_add_u32_e32 v152, 0x2000, v150
	v_lshl_add_u64 v[4:5], s[64:65], 0, v[4:5]
	s_or_b32 s64, s8, 0x80
	global_load_lds_dwordx4 v[2:3], off
	v_lshl_add_u64 v[2:3], s[70:71], 0, v[14:15]
	s_mov_b32 m0, s2
	v_readfirstlane_b32 s2, v152
	v_add_u32_e32 v153, s76, v13
	s_ashr_i32 s65, s64, 31
	global_load_lds_dwordx4 v[2:3], off
	v_lshl_add_u64 v[16:17], v[2:3], 0, s[20:21]
	s_mov_b32 m0, s2
	v_readfirstlane_b32 s2, v153
	v_add_u32_e32 v154, 0x2000, v153
	s_lshl_b64 s[64:65], s[64:65], 10
	global_load_lds_dwordx4 v[16:17], off
	s_mov_b32 m0, s2
	v_readfirstlane_b32 s2, v154
	s_add_u32 s64, s0, s64
	v_add_u32_e32 v156, 0x4000, v150
	global_load_lds_dwordx4 v[4:5], off
	v_lshl_add_u64 v[16:17], v[4:5], 0, s[18:19]
	s_mov_b32 m0, s2
	s_addc_u32 s65, s1, s65
	v_readfirstlane_b32 s2, v156
	v_add_u32_e32 v157, 0x6000, v150
	global_load_lds_dwordx4 v[16:17], off
	v_lshl_add_u64 v[132:133], s[64:65], 0, v[14:15]
	s_mov_b32 m0, s2
	v_readfirstlane_b32 s2, v157
	global_load_lds_dwordx4 v[132:133], off
	v_lshl_add_u64 v[14:15], v[132:133], 0, s[20:21]
	s_mov_b32 m0, s2
	s_nop 0
	global_load_lds_dwordx4 v[14:15], off
	v_mov_b32_e32 v20, 0
	v_mov_b32_e32 v21, 0
	v_mov_b32_e32 v22, 0
	v_mov_b32_e32 v23, 0
	v_mov_b32_e32 v24, 0
	v_mov_b32_e32 v25, 0
	v_mov_b32_e32 v26, 0
	v_mov_b32_e32 v27, 0
	v_mov_b32_e32 v28, 0
	v_mov_b32_e32 v29, 0
	v_mov_b32_e32 v30, 0
	v_mov_b32_e32 v31, 0
	v_mov_b32_e32 v32, 0
	v_mov_b32_e32 v33, 0
	v_mov_b32_e32 v34, 0
	v_mov_b32_e32 v35, 0
	v_mov_b32_e32 v36, 0
	v_mov_b32_e32 v37, 0
	v_mov_b32_e32 v38, 0
	v_mov_b32_e32 v39, 0
	v_mov_b32_e32 v40, 0
	v_mov_b32_e32 v41, 0
	v_mov_b32_e32 v42, 0
	v_mov_b32_e32 v43, 0
	v_mov_b32_e32 v44, 0
	v_mov_b32_e32 v45, 0
	v_mov_b32_e32 v46, 0
	v_mov_b32_e32 v47, 0
	v_mov_b32_e32 v48, 0
	v_mov_b32_e32 v49, 0
	v_mov_b32_e32 v50, 0
	v_mov_b32_e32 v51, 0
	v_mov_b32_e32 v52, 0
	v_mov_b32_e32 v53, 0
	v_mov_b32_e32 v54, 0
	v_mov_b32_e32 v55, 0
	v_mov_b32_e32 v56, 0
	v_mov_b32_e32 v57, 0
	v_mov_b32_e32 v58, 0
	v_mov_b32_e32 v59, 0
	v_mov_b32_e32 v60, 0
	v_mov_b32_e32 v61, 0
	v_mov_b32_e32 v62, 0
	v_mov_b32_e32 v63, 0
	v_mov_b32_e32 v64, 0
	v_mov_b32_e32 v65, 0
	v_mov_b32_e32 v66, 0
	v_mov_b32_e32 v67, 0
	v_mov_b32_e32 v68, 0
	v_mov_b32_e32 v69, 0
	v_mov_b32_e32 v70, 0
	v_mov_b32_e32 v71, 0
	v_mov_b32_e32 v72, 0
	v_mov_b32_e32 v73, 0
	v_mov_b32_e32 v74, 0
	v_mov_b32_e32 v75, 0
	v_mov_b32_e32 v76, 0
	v_mov_b32_e32 v77, 0
	v_mov_b32_e32 v78, 0
	v_mov_b32_e32 v79, 0
	v_mov_b32_e32 v80, 0
	v_mov_b32_e32 v81, 0
	v_mov_b32_e32 v82, 0
	v_mov_b32_e32 v83, 0
	v_mov_b32_e32 v84, 0
	v_mov_b32_e32 v85, 0
	v_mov_b32_e32 v86, 0
	v_mov_b32_e32 v87, 0
	v_mov_b32_e32 v88, 0
	v_mov_b32_e32 v89, 0
	v_mov_b32_e32 v90, 0
	v_mov_b32_e32 v91, 0
	v_mov_b32_e32 v92, 0
	v_mov_b32_e32 v93, 0
	v_mov_b32_e32 v94, 0
	v_mov_b32_e32 v95, 0
	v_mov_b32_e32 v96, 0
	v_mov_b32_e32 v97, 0
	v_mov_b32_e32 v98, 0
	v_mov_b32_e32 v99, 0
	v_mov_b32_e32 v100, 0
	v_mov_b32_e32 v101, 0
	v_mov_b32_e32 v102, 0
	v_mov_b32_e32 v103, 0
	v_mov_b32_e32 v104, 0
	v_mov_b32_e32 v105, 0
	v_mov_b32_e32 v106, 0
	v_mov_b32_e32 v107, 0
	v_mov_b32_e32 v108, 0
	v_mov_b32_e32 v109, 0
	v_mov_b32_e32 v110, 0
	v_mov_b32_e32 v111, 0
	v_mov_b32_e32 v112, 0
	v_mov_b32_e32 v113, 0
	v_mov_b32_e32 v114, 0
	v_mov_b32_e32 v115, 0
	v_mov_b32_e32 v116, 0
	v_mov_b32_e32 v117, 0
	v_mov_b32_e32 v118, 0
	v_mov_b32_e32 v119, 0
	v_mov_b32_e32 v120, 0
	v_mov_b32_e32 v121, 0
	v_mov_b32_e32 v122, 0
	v_mov_b32_e32 v123, 0
	v_mov_b32_e32 v124, 0
	v_mov_b32_e32 v125, 0
	v_mov_b32_e32 v126, 0
	v_mov_b32_e32 v127, 0
	v_ashrrev_i32_e32 v14, 8, v128
	v_cmp_eq_u32_e32 vcc, 1, v14
	s_and_saveexec_b64 s[72:73], vcc
	s_cbranch_execz .LBB0_813
	s_barrier
; #define STAGE_A(P, hf, kt) do { if constexpr (ABLK) { const bf16* _gp = A + ((long)(brow >> 8) * nt + (kt)) * 16384 + (hf) * 8192; GLDS2(_gp, 4096, offA, P); } \
;     else { const bf16* _gp = A + (long)(brow + (hf) * HALF) * lda + (long)(kt) * BK; GLDS2(_gp, 64 * (long)lda, offA, P); } } while (0)
; #define STAGE_B(P, hf, kt) do { const bf16* _gp = Bt + (long)(bcol + (hf) * 2) * ldb + (long)(kt) * BK; GLDS2(_gp, 128 * (long)ldb, offB, P); } while (0)
; #define WAIT_V(n) asm volatile("s_waitcnt vmcnt(" #n ")" ::: "memory")
; #define BAR __builtin_amdgcn_s_barrier()
; template <bool ABLK, class Epi>
; __device__ __forceinline__ void gemm_tile(const bf16* __restrict__ A, int lda, const bf16* __restrict__ Bt, int ldb, int K,
;                                           int brow, int bcol, bf16* shm, const Epi& epi, int wv) {
;     ...
;   if (wr == 1) BAR;
;   WAIT_V(4); BAR;
;   STAGE_B(SB(1, 0), 0, 1); STAGE_A(SA(1, 0), 0, 1); STAGE_B(SB(1, 1), 1, 1);
;   WAIT_V(6); BAR;
.LBB0_813:
	s_or_b64 exec, exec, s[72:73]
	v_add_u32_e32 v158, s77, v13
	v_add_u32_e32 v159, 0x2000, v158
	v_readfirstlane_b32 s2, v158
	v_lshl_add_u64 v[16:17], v[0:1], 0, s[22:23]
	s_mov_b32 m0, s2
	v_readfirstlane_b32 s2, v159
	v_add_u32_e32 v160, 0x8000, v150
	s_waitcnt vmcnt(4)
	s_barrier
	global_load_lds_dwordx4 v[16:17], off
	v_lshl_add_u64 v[0:1], v[0:1], 0, s[24:25]
	s_mov_b32 m0, s2
	v_readfirstlane_b32 s2, v160
	global_load_lds_dwordx4 v[0:1], off
	v_lshl_add_u64 v[0:1], v[2:3], 0, s[22:23]
	s_mov_b32 m0, s2
	v_add_u32_e32 v161, 0xa000, v150
	global_load_lds_dwordx4 v[0:1], off
	v_lshl_add_u64 v[0:1], v[130:131], 1, s[70:71]
	s_mov_b64 s[70:71], 0x10080
	v_readfirstlane_b32 s2, v161
	v_add_u32_e32 v162, s78, v13
	v_lshl_add_u64 v[0:1], v[0:1], 0, s[70:71]
	s_mov_b32 m0, s2
	v_readfirstlane_b32 s2, v162
	v_add_u32_e32 v163, 0x2000, v162
	global_load_lds_dwordx4 v[0:1], off
	v_lshl_add_u64 v[0:1], v[4:5], 0, s[22:23]
	s_mov_b32 m0, s2
	v_readfirstlane_b32 s2, v163
	global_load_lds_dwordx4 v[0:1], off
	v_lshl_add_u64 v[0:1], v[4:5], 0, s[24:25]
	s_mov_b32 m0, s2
	v_and_b32_e32 v15, 15, v128
	global_load_lds_dwordx4 v[0:1], off
	v_bfe_u32 v139, v128, 4, 2
	v_lshlrev_b32_e32 v142, 2, v15
	v_lshlrev_b32_e32 v0, 4, v139
	v_lshlrev_b32_e32 v1, 6, v15
	v_and_b32_e32 v3, 32, v142
	v_bitop3_b32 v1, v0, v3, v1 bitop3:0x36
	v_add_u32_e32 v4, s75, v1
	v_add_u32_e32 v5, s76, v1
	v_add_u32_e32 v13, s77, v1
	v_add_u32_e32 v15, s78, v1
	v_add_u32_e32 v16, 0, v1
	v_lshlrev_b32_e32 v1, 6, v128
	s_movk_i32 s2, 0x3c0
	v_and_or_b32 v0, v1, s2, v0
	v_xad_u32 v3, v0, v3, 0
	v_add3_u32 v0, v10, v11, v12
	s_lshr_b32 s72, s33, 2
	v_lshl_or_b32 v0, v0, 9, v8
	v_add_u32_sdwa v0, v0, sext(v9) dst_sel:DWORD dst_unused:UNUSED_PAD src0_sel:DWORD src1_sel:WORD_0
	s_add_u32 s66, s12, s66
	v_ashrrev_i32_e32 v1, 31, v0
	s_addc_u32 s67, s13, s67
	v_lshl_add_u64 v[134:135], v[0:1], 1, s[66:67]
	v_lshlrev_b32_e32 v0, 12, v6
	v_and_b32_e32 v0, 0xffffe000, v0
	v_lshl_add_u32 v0, v7, 9, v0
	v_or_b32_e32 v0, v0, v8
	v_add_u32_sdwa v0, v0, sext(v9) dst_sel:DWORD dst_unused:UNUSED_PAD src0_sel:DWORD src1_sel:WORD_0
	s_add_u32 s66, s10, s68
	v_bfe_u32 v141, v128, 6, 2
	s_waitcnt vmcnt(6)
	v_lshlrev_b32_e32 v143, 6, v14
	v_lshlrev_b32_e32 v14, 13, v14
	v_ashrrev_i32_e32 v1, 31, v0
	s_addc_u32 s67, s11, s69
	v_lshlrev_b32_e32 v2, 12, v141
	v_or_b32_e32 v17, 0x800, v14
	v_or_b32_e32 v18, 0x1000, v14
	v_or_b32_e32 v19, 0x1800, v14
	v_lshl_add_u64 v[136:137], v[0:1], 1, s[66:67]
	v_mov_b32_e32 v0, 0
	v_lshrrev_b32_e32 v140, 4, v128
	s_mov_b32 s9, -2
	s_mov_b64 s[66:67], 0
	v_add_u32_e32 v165, v4, v2
	v_add_u32_e32 v147, v16, v14
	v_add_u32_e32 v146, v3, v17
	v_add_u32_e32 v145, v3, v18
	v_add_u32_e32 v144, v3, v19
	v_add_u32_e32 v164, v5, v2
	v_add_u32_e32 v155, v13, v2
	v_add_u32_e32 v151, v15, v2
	v_mov_b32_e32 v1, v0
	v_mov_b32_e32 v2, v0
	v_mov_b32_e32 v3, v0
	v_mov_b32_e32 v4, v0
	v_mov_b32_e32 v5, v0
	v_mov_b32_e32 v6, v0
	v_mov_b32_e32 v7, v0
	v_mov_b32_e32 v8, v0
	v_mov_b32_e32 v9, v0
	v_mov_b32_e32 v10, v0
	v_mov_b32_e32 v11, v0
	v_mov_b32_e32 v12, v0
	v_mov_b32_e32 v13, v0
	v_mov_b32_e32 v14, v0
	v_mov_b32_e32 v15, v0
	v_mov_b32_e32 v16, v0
	v_mov_b32_e32 v17, v0
	v_mov_b32_e32 v18, v0
	v_mov_b32_e32 v19, v0
	s_barrier

; __device__ __forceinline__ void attn_body8(const bf16* __restrict__ Qb, const unsigned char* __restrict__ Kg, const unsigned char* __restrict__ Vg, ...
;     ...
;   float m_reg = -1e30f; f32x16 o[4] = {}; f32x16 lacc = {}; i32x8 qf[3];
;   {
;     const bf16* Qw = Qb + (long)(wid * QBLK + r32) * NUQ;
; #pragma unroll
;     for (int st = 0; st < 2; ++st)
; #pragma unroll
;       for (int c = 0; c < 4; ++c) { float f[8]; unpack8(*reinterpret_cast<const u32x4*>(Qw + st * 64 + hi * 32 + c * 8), f);
; #pragma unroll
;         for (int e = 0; e < 8; ++e) f[e] *= QS8;
;         qf[st][2 * c] = (int)pk4fp8(f[0], f[1], f[2], f[3]); qf[st][2 * c + 1] = (int)pk4fp8(f[4], f[5], f[6], f[7]); }
.LBB0_905:
	s_or_b64 exec, exec, s[8:9]
	v_and_b32_e32 v113, 0x3fffffc0, v113
	v_lshl_add_u32 v159, v113, 2, s60
	v_and_b32_e32 v242, 1, v192
	v_bfe_u32 v243, v192, 4, 2
	v_lshlrev_b32_e32 v242, 6, v242
	v_lshl_add_u32 v242, v243, 4, v242
	v_add_u32_e32 v242, v159, v242
	v_lshlrev_b32_e32 v113, 16, v118
	v_and_b32_e32 v118, 0xffff0000, v118
	v_lshlrev_b32_e32 v123, 16, v120
	v_and_b32_e32 v120, 0xffff0000, v120
	v_lshlrev_b32_e32 v132, 16, v121
	v_and_b32_e32 v133, 0xffff0000, v121
	v_mul_f32_e32 v113, 0x3f553b94, v113
	v_mul_f32_e32 v118, 0x3f553b94, v118
	v_mul_f32_e32 v123, 0x3f553b94, v123
	v_mul_f32_e32 v134, 0x3f553b94, v120
	v_mov_b32_e32 v120, v145
	v_mov_b32_e32 v121, v145
	v_cvt_pk_fp8_f32 v120, v113, v118
	v_cvt_pk_fp8_f32 v121, v123, v134
	v_lshlrev_b32_e32 v122, 16, v119
	v_and_b32_e32 v119, 0xffff0000, v119
	v_mul_f32_e32 v122, 0x3f553b94, v122
	v_mul_f32_e32 v119, 0x3f553b94, v119
	v_mul_f32_e32 v113, 0x3f553b94, v132
	v_mul_f32_e32 v118, 0x3f553b94, v133
	v_cvt_pk_fp8_f32 v120, v122, v119 op_sel:[0,0,1]
	v_cvt_pk_fp8_f32 v121, v113, v118 op_sel:[0,0,1]
	v_lshlrev_b32_e32 v113, 16, v128
	v_and_b32_e32 v118, 0xffff0000, v128
	v_and_b32_e32 v122, 0xffff0000, v129
	v_lshlrev_b32_e32 v123, 16, v130
	v_and_b32_e32 v128, 0xffff0000, v130
	v_lshlrev_b32_e32 v119, 16, v129
	v_lshlrev_b32_e32 v129, 16, v131
	v_and_b32_e32 v130, 0xffff0000, v131
	v_mul_f32_e32 v113, 0x3f553b94, v113
	v_mul_f32_e32 v118, 0x3f553b94, v118
	v_mul_f32_e32 v131, 0x3f553b94, v122
	v_mul_f32_e32 v132, 0x3f553b94, v123
	v_mul_f32_e32 v128, 0x3f553b94, v128
	v_mov_b32_e32 v122, v145
	v_mov_b32_e32 v123, v145
	v_cvt_pk_fp8_f32 v122, v113, v118
	v_cvt_pk_fp8_f32 v123, v132, v128
	v_mul_f32_e32 v119, 0x3f553b94, v119
	v_mul_f32_e32 v113, 0x3f553b94, v129
	v_mul_f32_e32 v118, 0x3f553b94, v130
	v_cvt_pk_fp8_f32 v122, v119, v131 op_sel:[0,0,1]
	v_cvt_pk_fp8_f32 v123, v113, v118 op_sel:[0,0,1]
	v_lshlrev_b32_e32 v113, 16, v124
	v_and_b32_e32 v118, 0xffff0000, v124
	v_lshlrev_b32_e32 v119, 16, v125
	v_and_b32_e32 v124, 0xffff0000, v125
	v_lshlrev_b32_e32 v125, 16, v126
	v_and_b32_e32 v126, 0xffff0000, v126
	v_mul_f32_e32 v130, 0x3f553b94, v125
	v_mul_f32_e32 v126, 0x3f553b94, v126
	v_mov_b32_e32 v125, v145
	v_cvt_pk_fp8_f32 v125, v130, v126
	v_lshlrev_b32_e32 v128, 16, v127
	v_and_b32_e32 v127, 0xffff0000, v127
	v_mul_f32_e32 v113, 0x3f553b94, v113
	v_mul_f32_e32 v118, 0x3f553b94, v118
	v_mul_f32_e32 v129, 0x3f553b94, v124
	v_mov_b32_e32 v124, v145
	v_cvt_pk_fp8_f32 v124, v113, v118
	v_mul_f32_e32 v113, 0x3f553b94, v128
	v_mul_f32_e32 v118, 0x3f553b94, v127
	v_cvt_pk_fp8_f32 v125, v113, v118 op_sel:[0,0,1]
	v_lshlrev_b32_e32 v113, 16, v114
	v_and_b32_e32 v114, 0xffff0000, v114
	v_mul_f32_e32 v113, 0x3f553b94, v113
	v_mul_f32_e32 v114, 0x3f553b94, v114
	v_mov_b32_e32 v126, v145
	v_mul_f32_e32 v119, 0x3f553b94, v119
	v_cvt_pk_fp8_f32 v126, v113, v114
	v_cvt_pk_fp8_f32 v124, v119, v129 op_sel:[0,0,1]
	v_lshlrev_b32_e32 v119, 16, v116
	v_and_b32_e32 v116, 0xffff0000, v116
	v_lshlrev_b32_e32 v118, 16, v115
	v_and_b32_e32 v115, 0xffff0000, v115
	v_mul_f32_e32 v119, 0x3f553b94, v119
	v_mul_f32_e32 v116, 0x3f553b94, v116
	v_mov_b32_e32 v127, v145
	v_mul_f32_e32 v118, 0x3f553b94, v118
	v_mul_f32_e32 v115, 0x3f553b94, v115
	v_cvt_pk_fp8_f32 v127, v119, v116
	v_cvt_pk_fp8_f32 v126, v118, v115 op_sel:[0,0,1]
	v_lshlrev_b32_e32 v115, 16, v110
	v_and_b32_e32 v110, 0xffff0000, v110
	v_lshlrev_b32_e32 v128, 16, v117
	v_and_b32_e32 v117, 0xffff0000, v117
	v_mul_f32_e32 v115, 0x3f553b94, v115
	v_mul_f32_e32 v110, 0x3f553b94, v110
	v_mov_b32_e32 v129, v145
	v_mul_f32_e32 v113, 0x3f553b94, v128
	v_mul_f32_e32 v114, 0x3f553b94, v117
	v_cvt_pk_fp8_f32 v129, v115, v110
	v_cvt_pk_fp8_f32 v127, v113, v114 op_sel:[0,0,1]
	v_lshlrev_b32_e32 v113, 16, v108
	v_and_b32_e32 v108, 0xffff0000, v108
	v_lshlrev_b32_e32 v116, 16, v111
	v_and_b32_e32 v111, 0xffff0000, v111
	v_mul_f32_e32 v113, 0x3f553b94, v113
	v_mul_f32_e32 v108, 0x3f553b94, v108
	v_mov_b32_e32 v128, v145
	v_cvt_pk_fp8_f32 v128, v113, v108
	v_mul_f32_e32 v108, 0x3f553b94, v116
	v_mul_f32_e32 v110, 0x3f553b94, v111
	v_cvt_pk_fp8_f32 v129, v108, v110 op_sel:[0,0,1]
	v_lshlrev_b32_e32 v110, 16, v106
	v_and_b32_e32 v106, 0xffff0000, v106
	v_mul_f32_e32 v110, 0x3f553b94, v110
	v_mul_f32_e32 v106, 0x3f553b94, v106
	v_mov_b32_e32 v131, v145
	v_cvt_pk_fp8_f32 v131, v110, v106
	v_lshlrev_b32_e32 v108, 16, v104
	v_and_b32_e32 v104, 0xffff0000, v104
	v_lshlrev_b32_e32 v111, 16, v107
	v_and_b32_e32 v107, 0xffff0000, v107
	v_mul_f32_e32 v108, 0x3f553b94, v108
	v_mul_f32_e32 v104, 0x3f553b94, v104
	v_mov_b32_e32 v130, v145
	v_cvt_pk_fp8_f32 v130, v108, v104
	v_mul_f32_e32 v104, 0x3f553b94, v111
	v_mul_f32_e32 v106, 0x3f553b94, v107
	v_cvt_pk_fp8_f32 v131, v104, v106 op_sel:[0,0,1]
	v_lshlrev_b32_e32 v106, 16, v102
	v_and_b32_e32 v102, 0xffff0000, v102
	v_mul_f32_e32 v106, 0x3f553b94, v106
	v_mul_f32_e32 v102, 0x3f553b94, v102
	v_mov_b32_e32 v133, v145
	v_cvt_pk_fp8_f32 v133, v106, v102
	v_lshlrev_b32_e32 v104, 16, v100
	v_and_b32_e32 v100, 0xffff0000, v100
	v_lshlrev_b32_e32 v114, 16, v109
	v_and_b32_e32 v109, 0xffff0000, v109
	v_lshlrev_b32_e32 v107, 16, v103
	v_and_b32_e32 v103, 0xffff0000, v103
	v_mul_f32_e32 v104, 0x3f553b94, v104
	v_mul_f32_e32 v100, 0x3f553b94, v100
	v_mov_b32_e32 v132, v145
	v_mul_f32_e32 v114, 0x3f553b94, v114
	v_mul_f32_e32 v109, 0x3f553b94, v109
	v_cvt_pk_fp8_f32 v132, v104, v100
	v_mul_f32_e32 v100, 0x3f553b94, v107
	v_mul_f32_e32 v102, 0x3f553b94, v103
	v_cvt_pk_fp8_f32 v128, v114, v109 op_sel:[0,0,1]
	v_lshlrev_b32_e32 v109, 16, v105
	v_and_b32_e32 v105, 0xffff0000, v105
	v_cvt_pk_fp8_f32 v133, v100, v102 op_sel:[0,0,1]
; __device__ __forceinline__ void attn_body8(const bf16* __restrict__ Qb, const unsigned char* __restrict__ Kg, const unsigned char* __restrict__ Vg, ...
;     ...
;       for (int c = 0; c < 4; ++c) { float f[8]; unpack8(*reinterpret_cast<const u32x4*>(Qw + st * 64 + hi * 32 + c * 8), f);
; #pragma unroll
;         for (int e = 0; e < 8; ++e) f[e] *= QS8;
;         qf[st][2 * c] = (int)pk4fp8(f[0], f[1], f[2], f[3]); qf[st][2 * c + 1] = (int)pk4fp8(f[4], f[5], f[6], f[7]); }
;     const int t = qpos0 + wid * QBLK + r32;
; #pragma unroll
;     for (int c = 0; c < 4; ++c) {
;       float x1[8], x2[8], cs[8], sn[8];
;       unpack8(*reinterpret_cast<const u32x4*>(Qw + 128 + c * 8), x1); unpack8(*reinterpret_cast<const u32x4*>(Qw + 160 + c * 8), x2);
;       *reinterpret_cast<f32x4*>(cs) = *reinterpret_cast<const f32x4*>(cosT + t * 32 + c * 8); *reinterpret_cast<f32x4*>(cs + 4) = *reinterpret_cast<const f32x4*>(cosT + t * 32 + c * 8 + 4);
;       *reinterpret_cast<f32x4*>(sn) = *reinterpret_cast<const f32x4*>(sinT + t * 32 + c * 8); *reinterpret_cast<f32x4*>(sn + 4) = *reinterpret_cast<const f32x4*>(sinT + t * 32 + c * 8 + 4);
;       float y[8];
; #pragma unroll
;       for (int e = 0; e < 8; ++e) y[e] = QS8 * (hi ? (x1[e] * sn[e] + x2[e] * cs[e]) : (x1[e] * cs[e] - x2[e] * sn[e]));
;       qf[2][2 * c] = (int)pk4fp8(y[0], y[1], y[2], y[3]); qf[2][2 * c + 1] = (int)pk4fp8(y[4], y[5], y[6], y[7]);
	v_lshlrev_b32_e32 v100, 16, v96
	v_and_b32_e32 v96, 0xffff0000, v96
	v_lshlrev_b32_e32 v102, 16, v98
	v_and_b32_e32 v98, 0xffff0000, v98
	v_mul_f32_e32 v109, 0x3f553b94, v109
	v_mul_f32_e32 v105, 0x3f553b94, v105
	v_mul_f32_e32 v100, 0x3f553b94, v100
	v_mul_f32_e32 v96, 0x3f553b94, v96
	v_mul_f32_e32 v102, 0x3f553b94, v102
	v_mul_f32_e32 v98, 0x3f553b94, v98
	v_mov_b32_e32 v134, v145
	v_mov_b32_e32 v135, v145
	v_cvt_pk_fp8_f32 v130, v109, v105 op_sel:[0,0,1]
	v_lshlrev_b32_e32 v105, 16, v101
	v_and_b32_e32 v101, 0xffff0000, v101
	v_cvt_pk_fp8_f32 v134, v100, v96
	v_cvt_pk_fp8_f32 v135, v102, v98
	v_mul_f32_e32 v105, 0x3f553b94, v105
	v_mul_f32_e32 v101, 0x3f553b94, v101
	v_cvt_pk_fp8_f32 v132, v105, v101 op_sel:[0,0,1]
	v_lshlrev_b32_e32 v101, 16, v97
	v_and_b32_e32 v97, 0xffff0000, v97
	v_lshlrev_b32_e32 v103, 16, v99
	v_and_b32_e32 v99, 0xffff0000, v99
	v_mul_f32_e32 v101, 0x3f553b94, v101
	v_mul_f32_e32 v97, 0x3f553b94, v97
	v_mul_f32_e32 v96, 0x3f553b94, v103
	v_mul_f32_e32 v98, 0x3f553b94, v99
	v_cvt_pk_fp8_f32 v134, v101, v97 op_sel:[0,0,1]
	v_cvt_pk_fp8_f32 v135, v96, v98 op_sel:[0,0,1]
	v_lshlrev_b32_e32 v97, 16, v84
	v_lshlrev_b32_e32 v96, 16, v76
	v_mov_b32_e32 v98, v92
	v_mov_b32_e32 v99, v88
	s_lshr_b32 s2, s63, 1
	v_pk_mul_f32 v[98:99], v[98:99], v[96:97]
	s_bfe_u32 s8, s63, 0x20008
	s_and_b32 s2, s2, 3
	v_add_f32_e32 v100, v99, v98
	v_mov_b32_e32 v98, v88
	v_mov_b32_e32 v99, v92
	s_mul_i32 s9, s8, 0x300
	s_mul_i32 s12, s2, 0xc0
	s_lshl_b32 s8, s8, 23
	s_lshl_b32 s2, s2, 21
	v_pk_mul_f32 v[96:97], v[98:99], v[96:97]
	s_add_i32 s34, s9, s12
	s_or_b32 s33, s8, s2
	v_sub_f32_e32 v88, v96, v97
	v_cmp_eq_u32_e64 s[8:9], 0, v210
	v_and_b32_e32 v97, 0xffff0000, v84
	v_and_b32_e32 v96, 0xffff0000, v76
	v_cndmask_b32_e64 v88, v100, v88, s[8:9]
	v_mul_f32_e32 v100, 0x3f553b94, v88
	v_mov_b32_e32 v88, v93
	v_mov_b32_e32 v92, v89
	v_pk_mul_f32 v[98:99], v[88:89], v[96:97]
	v_pk_mul_f32 v[88:89], v[92:93], v[96:97]
	v_add_f32_e32 v76, v99, v98
	v_sub_f32_e32 v84, v88, v89
	v_lshlrev_b32_e32 v89, 16, v85
	v_lshlrev_b32_e32 v88, 16, v77
	v_mov_b32_e32 v92, v94
	v_mov_b32_e32 v93, v90
	v_cndmask_b32_e64 v76, v76, v84, s[8:9]
	v_pk_mul_f32 v[92:93], v[92:93], v[88:89]
	v_mul_f32_e32 v96, 0x3f553b94, v76
	v_add_f32_e32 v76, v93, v92
	v_mov_b32_e32 v92, v90
	v_mov_b32_e32 v93, v94
	v_pk_mul_f32 v[88:89], v[92:93], v[88:89]
	v_and_b32_e32 v85, 0xffff0000, v85
	v_sub_f32_e32 v84, v88, v89
	v_cndmask_b32_e64 v76, v76, v84, s[8:9]
	v_and_b32_e32 v84, 0xffff0000, v77
	v_mov_b32_e32 v90, v95
	v_mul_f32_e32 v88, 0x3f553b94, v76
	v_pk_mul_f32 v[76:77], v[90:91], v[84:85]
	v_mov_b32_e32 v94, v91
	v_add_f32_e32 v89, v77, v76
	v_pk_mul_f32 v[76:77], v[94:95], v[84:85]
	v_mov_b32_e32 v84, v80
	v_sub_f32_e32 v76, v76, v77
	v_cndmask_b32_e64 v76, v89, v76, s[8:9]
	v_mul_f32_e32 v89, 0x3f553b94, v76
	v_lshlrev_b32_e32 v77, 16, v86
	v_lshlrev_b32_e32 v76, 16, v78
	v_mov_b32_e32 v85, v72
	v_pk_mul_f32 v[84:85], v[84:85], v[76:77]
	v_mov_b32_e32 v137, v145
	v_add_f32_e32 v90, v85, v84
	v_mov_b32_e32 v84, v72
	v_mov_b32_e32 v85, v80
	v_pk_mul_f32 v[76:77], v[84:85], v[76:77]
	v_mov_b32_e32 v80, v73
	v_sub_f32_e32 v72, v76, v77
	v_cndmask_b32_e64 v72, v90, v72, s[8:9]
	v_mul_f32_e32 v90, 0x3f553b94, v72
	v_and_b32_e32 v77, 0xffff0000, v86
	v_and_b32_e32 v76, 0xffff0000, v78
	v_mov_b32_e32 v72, v81
	v_pk_mul_f32 v[84:85], v[72:73], v[76:77]
	v_pk_mul_f32 v[72:73], v[80:81], v[76:77]
	v_add_f32_e32 v78, v85, v84
	v_sub_f32_e32 v72, v72, v73
	v_cndmask_b32_e64 v72, v78, v72, s[8:9]
	v_mul_f32_e32 v78, 0x3f553b94, v72
	v_lshlrev_b32_e32 v73, 16, v87
	v_lshlrev_b32_e32 v72, 16, v79
	v_mov_b32_e32 v76, v82
	v_mov_b32_e32 v77, v74
	v_pk_mul_f32 v[76:77], v[76:77], v[72:73]
	v_cvt_pk_fp8_f32 v137, v90, v78
	v_add_f32_e32 v80, v77, v76
	v_mov_b32_e32 v76, v74
	v_mov_b32_e32 v77, v82
	v_pk_mul_f32 v[72:73], v[76:77], v[72:73]
	v_mov_b32_e32 v74, v83
	v_sub_f32_e32 v72, v72, v73
	v_cndmask_b32_e64 v72, v80, v72, s[8:9]
	v_mul_f32_e32 v80, 0x3f553b94, v72
	v_and_b32_e32 v73, 0xffff0000, v87
	v_and_b32_e32 v72, 0xffff0000, v79
	v_mov_b32_e32 v82, v75
	v_pk_mul_f32 v[76:77], v[74:75], v[72:73]
	v_pk_mul_f32 v[72:73], v[82:83], v[72:73]
	v_add_f32_e32 v74, v77, v76
	v_sub_f32_e32 v72, v72, v73
	v_cndmask_b32_e64 v72, v74, v72, s[8:9]
	v_mul_f32_e32 v72, 0x3f553b94, v72
	v_cvt_pk_fp8_f32 v137, v80, v72 op_sel:[0,0,1]
	v_lshlrev_b32_e32 v73, 16, v60
	v_lshlrev_b32_e32 v72, 16, v56
	v_mov_b32_e32 v74, v68
	v_mov_b32_e32 v75, v64
	v_pk_mul_f32 v[74:75], v[74:75], v[72:73]
	v_mov_b32_e32 v139, v145
	v_add_f32_e32 v76, v75, v74
	v_mov_b32_e32 v74, v64
	v_mov_b32_e32 v75, v68
	v_pk_mul_f32 v[72:73], v[74:75], v[72:73]
	v_mov_b32_e32 v68, v65
	v_sub_f32_e32 v64, v72, v73
	v_cndmask_b32_e64 v64, v76, v64, s[8:9]
	v_mul_f32_e32 v76, 0x3f553b94, v64
	v_and_b32_e32 v73, 0xffff0000, v60
	v_and_b32_e32 v72, 0xffff0000, v56
	v_mov_b32_e32 v64, v69
	v_pk_mul_f32 v[74:75], v[64:65], v[72:73]
	v_pk_mul_f32 v[64:65], v[68:69], v[72:73]
	v_add_f32_e32 v56, v75, v74
	v_sub_f32_e32 v60, v64, v65
	v_lshlrev_b32_e32 v65, 16, v61
	v_lshlrev_b32_e32 v64, 16, v57
	v_mov_b32_e32 v68, v70
	v_mov_b32_e32 v69, v66
	v_cndmask_b32_e64 v56, v56, v60, s[8:9]
	v_pk_mul_f32 v[68:69], v[68:69], v[64:65]
	v_mul_f32_e32 v72, 0x3f553b94, v56
	v_add_f32_e32 v56, v69, v68
	v_mov_b32_e32 v68, v66
	v_mov_b32_e32 v69, v70
	v_pk_mul_f32 v[64:65], v[68:69], v[64:65]
	v_and_b32_e32 v61, 0xffff0000, v61
	v_sub_f32_e32 v60, v64, v65
	v_cndmask_b32_e64 v56, v56, v60, s[8:9]
	v_and_b32_e32 v60, 0xffff0000, v57
	v_mov_b32_e32 v66, v71
	v_mul_f32_e32 v64, 0x3f553b94, v56
	v_pk_mul_f32 v[56:57], v[66:67], v[60:61]
	v_mov_b32_e32 v70, v67
; #define SBAR() __builtin_amdgcn_sched_barrier(0)
; #define SLOAD(k0) do { sv0 = *reinterpret_cast<const bf16x8*>(Vp + (k0) * LDV); sv1 = *reinterpret_cast<const bf16x8*>(Vp + ((k0) + 32) * LDV); \
;     sk0 = *reinterpret_cast<const bf16x8*>(Kp + (k0) * LDK); sk1 = *reinterpret_cast<const bf16x8*>(Kp + ((k0) + 32) * LDK); \
;     if constexpr (DQK == 192) sk2 = *reinterpret_cast<const bf16x8*>(Kp2 + (k0) * LDK); } while (0)
; #define SWRITE(KB, VB) do { *(bf16x8*)(V_lds + (VB) * SHM_V + vst0) = sv0; *(bf16x8*)(V_lds + (VB) * SHM_V + vst1) = sv1; \
;     *(bf16x8*)(K_lds + (KB) * SHM_K + kst0) = sk0; *(bf16x8*)(K_lds + (KB) * SHM_K + kst1) = sk1; } while (0)
; #define SLOAD(TILE) do { sv = *reinterpret_cast<const u32x4*>(Vp + (TILE) * 8192); sk0 = *reinterpret_cast<const u32x4*>(Kp0 + (TILE) * (64 * 3072)); \
;     if (two) sk1 = *reinterpret_cast<const u32x4*>(Kp1 + (TILE) * (64 * 3072)); } while (0)
; #define SWRITE(KB, VB) do { *(u32x4*)(V_lds + (VB) * SHM_V8 + vst) = sv; *(u32x4*)(K_lds + (KB) * SHM_K8 + kst0) = sk0; \
;     if (two) *(u32x4*)(K_lds + (KB) * SHM_K8 + kst1) = sk1; } while (0)
; __device__ __forceinline__ void attn_body8(const bf16* __restrict__ Qb, const unsigned char* __restrict__ Kg, const unsigned char* __restrict__ Vg, ...
;     ...
;     const int t = qpos0 + wid * QBLK + r32;
; #pragma unroll
;     for (int c = 0; c < 4; ++c) {
;       float x1[8], x2[8], cs[8], sn[8];
;       unpack8(*reinterpret_cast<const u32x4*>(Qw + 128 + c * 8), x1); unpack8(*reinterpret_cast<const u32x4*>(Qw + 160 + c * 8), x2);
;       *reinterpret_cast<f32x4*>(cs) = *reinterpret_cast<const f32x4*>(cosT + t * 32 + c * 8); *reinterpret_cast<f32x4*>(cs + 4) = *reinterpret_cast<const f32x4*>(cosT + t * 32 + c * 8 + 4);
;       *reinterpret_cast<f32x4*>(sn) = *reinterpret_cast<const f32x4*>(sinT + t * 32 + c * 8); *reinterpret_cast<f32x4*>(sn + 4) = *reinterpret_cast<const f32x4*>(sinT + t * 32 + c * 8 + 4);
;       float y[8];
; #pragma unroll
;       for (int e = 0; e < 8; ++e) y[e] = QS8 * (hi ? (x1[e] * sn[e] + x2[e] * cs[e]) : (x1[e] * cs[e] - x2[e] * sn[e]));
;       qf[2][2 * c] = (int)pk4fp8(y[0], y[1], y[2], y[3]); qf[2][2 * c + 1] = (int)pk4fp8(y[4], y[5], y[6], y[7]);
;     }
;     ...
;     if (j + 2 < NT) SWRITE((k4 + 2) & 3, VP2());
;     if (j + 3 < NT) SLOAD(j + 3);
;     SBAR(); qkt8(pB0, pB1, K_lds + k4 * SHM_K8, qf, r32, hi);
	v_add_f32_e32 v65, v57, v56
	v_pk_mul_f32 v[56:57], v[70:71], v[60:61]
	v_mov_b32_e32 v60, v52
	v_sub_f32_e32 v56, v56, v57
	v_cndmask_b32_e64 v56, v65, v56, s[8:9]
	v_mul_f32_e32 v65, 0x3f553b94, v56
	v_lshlrev_b32_e32 v57, 16, v62
	v_lshlrev_b32_e32 v56, 16, v58
	v_mov_b32_e32 v61, v48
	v_pk_mul_f32 v[60:61], v[60:61], v[56:57]
	v_mov_b32_e32 v141, v145
	v_add_f32_e32 v66, v61, v60
	v_mov_b32_e32 v60, v48
	v_mov_b32_e32 v61, v52
	v_pk_mul_f32 v[56:57], v[60:61], v[56:57]
	v_mov_b32_e32 v52, v49
	v_sub_f32_e32 v48, v56, v57
	v_cndmask_b32_e64 v48, v66, v48, s[8:9]
	v_mul_f32_e32 v66, 0x3f553b94, v48
	v_and_b32_e32 v57, 0xffff0000, v62
	v_and_b32_e32 v56, 0xffff0000, v58
	v_mov_b32_e32 v48, v53
	v_pk_mul_f32 v[60:61], v[48:49], v[56:57]
	v_pk_mul_f32 v[48:49], v[52:53], v[56:57]
	v_add_f32_e32 v58, v61, v60
	v_sub_f32_e32 v48, v48, v49
	v_cndmask_b32_e64 v48, v58, v48, s[8:9]
	v_mul_f32_e32 v56, 0x3f553b94, v48
	v_lshlrev_b32_e32 v49, 16, v63
	v_lshlrev_b32_e32 v48, 16, v59
	v_mov_b32_e32 v52, v54
	v_mov_b32_e32 v53, v50
	v_pk_mul_f32 v[52:53], v[52:53], v[48:49]
	v_cvt_pk_fp8_f32 v139, v66, v56
	v_add_f32_e32 v57, v53, v52
	v_mov_b32_e32 v52, v50
	v_mov_b32_e32 v53, v54
	v_pk_mul_f32 v[48:49], v[52:53], v[48:49]
	v_mov_b32_e32 v50, v55
	v_sub_f32_e32 v48, v48, v49
	v_cndmask_b32_e64 v48, v57, v48, s[8:9]
	v_mul_f32_e32 v57, 0x3f553b94, v48
	v_and_b32_e32 v49, 0xffff0000, v63
	v_and_b32_e32 v48, 0xffff0000, v59
	v_mov_b32_e32 v54, v51
	v_pk_mul_f32 v[52:53], v[50:51], v[48:49]
	v_pk_mul_f32 v[48:49], v[54:55], v[48:49]
	v_add_f32_e32 v50, v53, v52
	v_sub_f32_e32 v48, v48, v49
	v_cndmask_b32_e64 v48, v50, v48, s[8:9]
	v_mul_f32_e32 v48, 0x3f553b94, v48
	v_cvt_pk_fp8_f32 v139, v57, v48 op_sel:[0,0,1]
	v_lshlrev_b32_e32 v49, 16, v28
	v_lshlrev_b32_e32 v48, 16, v24
	v_mov_b32_e32 v50, v44
	v_mov_b32_e32 v51, v40
	v_pk_mul_f32 v[50:51], v[50:51], v[48:49]
	v_lshlrev_b32_e32 v144, 5, v210
	v_add_f32_e32 v52, v51, v50
	v_mov_b32_e32 v50, v40
	v_mov_b32_e32 v51, v44
	v_pk_mul_f32 v[48:49], v[50:51], v[48:49]
	v_mov_b32_e32 v44, v41
	v_sub_f32_e32 v40, v48, v49
	v_cndmask_b32_e64 v40, v52, v40, s[8:9]
	v_mul_f32_e32 v52, 0x3f553b94, v40
	v_and_b32_e32 v49, 0xffff0000, v28
	v_and_b32_e32 v48, 0xffff0000, v24
	v_mov_b32_e32 v40, v45
	v_pk_mul_f32 v[50:51], v[40:41], v[48:49]
	v_pk_mul_f32 v[40:41], v[44:45], v[48:49]
	v_add_f32_e32 v24, v51, v50
	v_sub_f32_e32 v28, v40, v41
	v_lshlrev_b32_e32 v41, 16, v29
	v_lshlrev_b32_e32 v40, 16, v25
	v_mov_b32_e32 v44, v46
	v_mov_b32_e32 v45, v42
	v_cndmask_b32_e64 v24, v24, v28, s[8:9]
	v_pk_mul_f32 v[44:45], v[44:45], v[40:41]
	v_mul_f32_e32 v48, 0x3f553b94, v24
	v_add_f32_e32 v24, v45, v44
	v_mov_b32_e32 v44, v42
	v_mov_b32_e32 v45, v46
	v_pk_mul_f32 v[40:41], v[44:45], v[40:41]
	v_and_b32_e32 v29, 0xffff0000, v29
	v_sub_f32_e32 v28, v40, v41
	v_cndmask_b32_e64 v24, v24, v28, s[8:9]
	v_and_b32_e32 v28, 0xffff0000, v25
	v_mov_b32_e32 v42, v47
	v_mul_f32_e32 v40, 0x3f553b94, v24
	v_pk_mul_f32 v[24:25], v[42:43], v[28:29]
	v_mov_b32_e32 v46, v43
	v_add_f32_e32 v41, v25, v24
	v_pk_mul_f32 v[24:25], v[46:47], v[28:29]
	v_mov_b32_e32 v28, v36
	v_sub_f32_e32 v24, v24, v25
	v_cndmask_b32_e64 v24, v41, v24, s[8:9]
	v_mul_f32_e32 v41, 0x3f553b94, v24
	v_lshlrev_b32_e32 v25, 16, v30
	v_lshlrev_b32_e32 v24, 16, v26
	v_mov_b32_e32 v29, v32
	v_pk_mul_f32 v[28:29], v[28:29], v[24:25]
	v_mul_u32_u24_e32 v212, 0xd0, v209
	v_add_f32_e32 v42, v29, v28
	v_mov_b32_e32 v28, v32
	v_mov_b32_e32 v29, v36
	v_pk_mul_f32 v[24:25], v[28:29], v[24:25]
	v_mov_b32_e32 v32, v37
	v_sub_f32_e32 v24, v24, v25
	v_cndmask_b32_e64 v24, v42, v24, s[8:9]
	v_mul_f32_e32 v42, 0x3f553b94, v24
	v_and_b32_e32 v25, 0xffff0000, v30
	v_and_b32_e32 v24, 0xffff0000, v26
	v_mov_b32_e32 v36, v33
	v_pk_mul_f32 v[28:29], v[32:33], v[24:25]
	v_pk_mul_f32 v[24:25], v[36:37], v[24:25]
	v_add_f32_e32 v26, v29, v28
	v_sub_f32_e32 v24, v24, v25
	v_cndmask_b32_e64 v24, v26, v24, s[8:9]
	v_mul_f32_e32 v30, 0x3f553b94, v24
	v_lshlrev_b32_e32 v25, 16, v31
	v_lshlrev_b32_e32 v24, 16, v27
	v_mov_b32_e32 v28, v38
	v_mov_b32_e32 v29, v34
	v_pk_mul_f32 v[28:29], v[28:29], v[24:25]
	v_cvt_pk_fp8_f32 v141, v42, v30
	v_add_f32_e32 v26, v29, v28
	v_mov_b32_e32 v28, v34
	v_mov_b32_e32 v29, v38
	v_pk_mul_f32 v[24:25], v[28:29], v[24:25]
	v_mov_b32_e32 v34, v39
	v_sub_f32_e32 v24, v24, v25
	v_cndmask_b32_e64 v24, v26, v24, s[8:9]
	v_mul_f32_e32 v28, 0x3f553b94, v24
	v_and_b32_e32 v25, 0xffff0000, v31
	v_and_b32_e32 v24, 0xffff0000, v27
	v_mov_b32_e32 v38, v35
	v_pk_mul_f32 v[26:27], v[34:35], v[24:25]
	v_pk_mul_f32 v[24:25], v[38:39], v[24:25]
	v_add_f32_e32 v26, v27, v26
	v_sub_f32_e32 v24, v24, v25
	v_cndmask_b32_e64 v24, v26, v24, s[8:9]
	v_mul_f32_e32 v24, 0x3f553b94, v24
	v_cvt_pk_fp8_f32 v141, v28, v24 op_sel:[0,0,1]
	v_lshlrev_b32_e32 v25, 16, v4
	v_lshlrev_b32_e32 v24, 16, v0
	v_mov_b32_e32 v26, v20
	v_mov_b32_e32 v27, v16
	v_pk_mul_f32 v[26:27], v[26:27], v[24:25]
	v_add3_u32 v214, 0, v212, v144
	v_add_f32_e32 v28, v27, v26
	v_mov_b32_e32 v26, v16
	v_mov_b32_e32 v27, v20
	v_pk_mul_f32 v[24:25], v[26:27], v[24:25]
	v_mov_b32_e32 v20, v17
	v_sub_f32_e32 v16, v24, v25
	v_cndmask_b32_e64 v16, v28, v16, s[8:9]
	v_mul_f32_e32 v56, 0x3f553b94, v16
	v_and_b32_e32 v25, 0xffff0000, v4
	v_and_b32_e32 v24, 0xffff0000, v0
	v_mov_b32_e32 v16, v21
	v_pk_mul_f32 v[26:27], v[16:17], v[24:25]
	v_pk_mul_f32 v[16:17], v[20:21], v[24:25]
	v_add_f32_e32 v0, v27, v26
	v_sub_f32_e32 v4, v16, v17
	v_lshlrev_b32_e32 v17, 16, v5
	v_lshlrev_b32_e32 v16, 16, v1
	v_mov_b32_e32 v20, v22
	v_mov_b32_e32 v21, v18
	v_mov_b32_e32 v140, v145
	v_cndmask_b32_e64 v0, v0, v4, s[8:9]
	v_pk_mul_f32 v[20:21], v[20:21], v[16:17]
	ds_read_b128 v[24:27], v214 offset:51200
	ds_read_b128 v[28:31], v214 offset:51216
	v_cvt_pk_fp8_f32 v140, v52, v48
	v_mul_f32_e32 v57, 0x3f553b94, v0
	v_add_f32_e32 v0, v21, v20
	v_mov_b32_e32 v20, v18
	v_mov_b32_e32 v21, v22
	v_pk_mul_f32 v[16:17], v[20:21], v[16:17]
	v_and_b32_e32 v5, 0xffff0000, v5
	v_sub_f32_e32 v4, v16, v17
	v_cndmask_b32_e64 v0, v0, v4, s[8:9]
	v_and_b32_e32 v4, 0xffff0000, v1
	v_mov_b32_e32 v18, v23
	v_cvt_pk_fp8_f32 v140, v40, v41 op_sel:[0,0,1]
	v_mul_f32_e32 v58, 0x3f553b94, v0
	v_pk_mul_f32 v[0:1], v[18:19], v[4:5]
	v_mov_b32_e32 v22, v19
	s_waitcnt lgkmcnt(0)
; __device__ __forceinline__ void qkt8(f32x16& p0, f32x16& p1, const char* Ks, const i32x8* qf, int r32, int hi) {
;   p0 = f32x16{}; p1 = f32x16{};
;   const char* kb = Ks + r32 * K8ROW + hi * 32;
;   i32x8 a0 = ld32B(kb), a1 = ld32B(kb + 32 * K8ROW);
;   i32x8 b0 = ld32B(kb + 64), b1 = ld32B(kb + 32 * K8ROW + 64);
;   p0 = mfma8(a0, qf[0], p0); p1 = mfma8(a1, qf[0], p1);
;   a0 = ld32B(kb + 128); a1 = ld32B(kb + 32 * K8ROW + 128);
;   p0 = mfma8(b0, qf[1], p0); p1 = mfma8(b1, qf[1], p1);
;   p0 = mfma8(a0, qf[2], p0); p1 = mfma8(a1, qf[2], p1);
; }
; __device__ __forceinline__ void attn_body8(const bf16* __restrict__ Qb, const unsigned char* __restrict__ Kg, const unsigned char* __restrict__ Vg, ...
;     ...
;     const int t = qpos0 + wid * QBLK + r32;
; #pragma unroll
;     for (int c = 0; c < 4; ++c) {
;       float x1[8], x2[8], cs[8], sn[8];
;       unpack8(*reinterpret_cast<const u32x4*>(Qw + 128 + c * 8), x1); unpack8(*reinterpret_cast<const u32x4*>(Qw + 160 + c * 8), x2);
;       *reinterpret_cast<f32x4*>(cs) = *reinterpret_cast<const f32x4*>(cosT + t * 32 + c * 8); *reinterpret_cast<f32x4*>(cs + 4) = *reinterpret_cast<const f32x4*>(cosT + t * 32 + c * 8 + 4);
;       *reinterpret_cast<f32x4*>(sn) = *reinterpret_cast<const f32x4*>(sinT + t * 32 + c * 8); *reinterpret_cast<f32x4*>(sn + 4) = *reinterpret_cast<const f32x4*>(sinT + t * 32 + c * 8 + 4);
;       float y[8];
; #pragma unroll
;       for (int e = 0; e < 8; ++e) y[e] = QS8 * (hi ? (x1[e] * sn[e] + x2[e] * cs[e]) : (x1[e] * cs[e] - x2[e] * sn[e]));
;       qf[2][2 * c] = (int)pk4fp8(y[0], y[1], y[2], y[3]); qf[2][2 * c + 1] = (int)pk4fp8(y[4], y[5], y[6], y[7]);
;     }
	v_mfma_scale_f32_32x32x64_f8f6f4 v[32:47], v[24:31], v[120:127], 0, v193, v193 op_sel_hi:[0,0,0]
	v_add_f32_e32 v16, v1, v0
	v_mul_f32_e64 v0, v22, v4
	v_mul_f32_e64 v1, v23, v5
	v_mov_b32_e32 v4, v12
	v_sub_f32_e32 v0, v0, v1
	v_cndmask_b32_e64 v0, v16, v0, s[8:9]
	v_mul_f32_e32 v59, 0x3f553b94, v0
	v_lshlrev_b32_e32 v1, 16, v6
	v_lshlrev_b32_e32 v0, 16, v2
	v_mov_b32_e32 v5, v8
	ds_read_b128 v[16:19], v214 offset:57856
	ds_read_b128 v[20:23], v214 offset:57872
	v_mul_f32_e64 v4, v4, v0
	v_mul_f32_e64 v5, v5, v1
	ds_read_b128 v[48:51], v214 offset:51264
	ds_read_b128 v[52:55], v214 offset:51280
	v_add_f32_e32 v24, v5, v4
	v_mov_b32_e32 v4, v8
	v_mov_b32_e32 v5, v12
	v_pk_mul_f32 v[0:1], v[4:5], v[0:1]
	v_mov_b32_e32 v8, v13
	v_sub_f32_e32 v0, v0, v1
	v_cndmask_b32_e64 v0, v24, v0, s[8:9]
	s_waitcnt lgkmcnt(2)
	v_mfma_scale_f32_32x32x64_f8f6f4 v[16:31], v[16:23], v[120:127], 0, v193, v193 op_sel_hi:[0,0,0]
	v_mul_f32_e32 v60, 0x3f553b94, v0
	v_and_b32_e32 v1, 0xffff0000, v6
	v_and_b32_e32 v0, 0xffff0000, v2
	v_mov_b32_e32 v12, v9
	v_mul_f32_e64 v4, v8, v0
	v_mul_f32_e64 v5, v9, v1
	v_mul_f32_e64 v0, v12, v0
	v_mul_f32_e64 v1, v13, v1
	v_add_f32_e32 v2, v5, v4
	v_sub_f32_e32 v0, v0, v1
	v_cndmask_b32_e64 v0, v2, v0, s[8:9]
	v_mul_f32_e32 v6, 0x3f553b94, v0
	v_lshlrev_b32_e32 v1, 16, v7
	v_lshlrev_b32_e32 v0, 16, v3
	v_mov_b32_e32 v4, v14
	v_mov_b32_e32 v5, v10
	v_pk_mul_f32 v[4:5], v[4:5], v[0:1]
	s_waitcnt lgkmcnt(0)
	v_mfma_scale_f32_32x32x64_f8f6f4 v[32:47], v[48:55], v[128:135], v[32:47], v193, v193 op_sel_hi:[0,0,0]
	v_add_f32_e32 v2, v5, v4
	v_mov_b32_e32 v4, v10
	v_mov_b32_e32 v5, v14
	v_mul_f32_e64 v0, v4, v0
	v_mul_f32_e64 v1, v5, v1
	ds_read_b128 v[48:51], v214 offset:57920
	ds_read_b128 v[52:55], v214 offset:57936
	v_sub_f32_e32 v0, v0, v1
	v_cndmask_b32_e64 v0, v2, v0, s[8:9]
	v_mov_b32_e32 v136, v145
	v_mov_b32_e32 v138, v145
	v_mul_f32_e32 v8, 0x3f553b94, v0
	v_and_b32_e32 v1, 0xffff0000, v7
	v_and_b32_e32 v0, 0xffff0000, v3
	v_mov_b32_e32 v10, v15
	v_mov_b32_e32 v14, v11
	v_mov_b32_e32 v142, v145
	v_mov_b32_e32 v143, v145
	v_cvt_pk_fp8_f32 v136, v100, v96
	v_cvt_pk_fp8_f32 v138, v76, v72
	v_pk_mul_f32 v[2:3], v[10:11], v[0:1]
	v_pk_mul_f32 v[0:1], v[14:15], v[0:1]
	v_cvt_pk_fp8_f32 v142, v56, v57
	v_cvt_pk_fp8_f32 v143, v60, v6
	v_add_f32_e32 v9, v3, v2
	s_waitcnt lgkmcnt(0)
	v_mfma_scale_f32_32x32x64_f8f6f4 v[16:31], v[48:55], v[128:135], v[16:31], v193, v193 op_sel_hi:[0,0,0]
	v_sub_f32_e32 v10, v0, v1
	v_cndmask_b32_e64 v9, v9, v10, s[8:9]
	ds_read_b128 v[0:3], v214 offset:51328
	ds_read_b128 v[4:7], v214 offset:51344
	v_mul_f32_e32 v9, 0x3f553b94, v9
	v_cvt_pk_fp8_f32 v136, v88, v89 op_sel:[0,0,1]
	v_cvt_pk_fp8_f32 v138, v64, v65 op_sel:[0,0,1]
	v_cvt_pk_fp8_f32 v142, v58, v59 op_sel:[0,0,1]
	v_cvt_pk_fp8_f32 v143, v8, v9 op_sel:[0,0,1]
	ds_read_b128 v[48:51], v214 offset:57984
	ds_read_b128 v[52:55], v214 offset:58000
	s_mov_b32 s12, s35
	s_mov_b32 s13, s35
	s_mov_b32 s14, s35
	s_mov_b32 s15, s35
	s_mov_b32 s16, s35
	s_mov_b32 s17, s35
	s_waitcnt lgkmcnt(2)
	v_mfma_scale_f32_32x32x64_f8f6f4 v[32:47], v[0:7], v[136:143], v[32:47], v193, v193 op_sel_hi:[0,0,0]
	s_mov_b32 s18, s35
	s_mov_b32 s19, s35
	s_mov_b32 s20, s35
	s_mov_b32 s21, s35
	s_mov_b32 s22, s35
	s_mov_b32 s23, s35
	s_mov_b32 s24, s35
	s_mov_b32 s25, s35
	s_mov_b32 s26, s35
	s_mov_b32 s27, s35
	v_mov_b64_e32 v[0:1], s[12:13]
	v_mov_b64_e32 v[14:15], s[26:27]
	v_mov_b64_e32 v[2:3], s[14:15]
	v_mov_b64_e32 v[4:5], s[16:17]
	v_mov_b64_e32 v[6:7], s[18:19]
	s_waitcnt lgkmcnt(0)
; #define SLOAD(k0) do { sv0 = *reinterpret_cast<const bf16x8*>(Vp + (k0) * LDV); sv1 = *reinterpret_cast<const bf16x8*>(Vp + ((k0) + 32) * LDV); \
;     sk0 = *reinterpret_cast<const bf16x8*>(Kp + (k0) * LDK); sk1 = *reinterpret_cast<const bf16x8*>(Kp + ((k0) + 32) * LDK); \
;     if constexpr (DQK == 192) sk2 = *reinterpret_cast<const bf16x8*>(Kp2 + (k0) * LDK); } while (0)
; #define ADV() do { k3 = (k3 == 2) ? 0 : k3 + 1; v4 = (v4 + 1) & 3; } while (0)
; __device__ __forceinline__ void partialSM8(f32x16& p0, f32x16& p1, float& m_reg, float& mn, float& alpha) {
;   float pmax = p0[0];
; #pragma unroll
;   for (int r = 1; r < 16; ++r) pmax = fmaxf(pmax, p0[r]);
; #pragma unroll
;   for (int r = 0; r < 16; ++r) pmax = fmaxf(pmax, p1[r]);
;   { auto rr = __builtin_amdgcn_permlane32_swap(__float_as_uint(pmax), __float_as_uint(pmax), false, false);
;     pmax = fmaxf(__uint_as_float(rr[0]), __uint_as_float(rr[1])); }
;   if (__builtin_expect(__all(pmax - m_reg <= THR8 * 8.f * 1.4426950408889634f), 1)) { mn = m_reg; alpha = 1.f; }
;   else { mn = fmaxf(m_reg, pmax); alpha = __builtin_amdgcn_exp2f((m_reg - mn) * 0.125f); m_reg = mn; }
;   const float mn8 = (P8SHIFT + 7.f - 0.0436f) * 8.f + 0.5f - mn;
; #pragma unroll
;   for (int r = 0; r < 16; ++r) p0[r] += mn8;
; #pragma unroll
;   for (int r = 0; r < 16; ++r) p1[r] += mn8;
; }
; __device__ __forceinline__ void attn_body8(const bf16* __restrict__ Qb, const unsigned char* __restrict__ Kg, const unsigned char* __restrict__ Vg, ...
;     ...
;   const int kr0_ = tid / 12, kp0_ = tid - kr0_ * 12, kr1_ = (512 + tid) / 12, kp1_ = (512 + tid) - kr1_ * 12;
;   const unsigned char* Kp0 = Kg + kr0_ * 3072 + kp0_ * 16; const unsigned char* Kp1 = Kg + kr1_ * 3072 + kp1_ * 16;
;   const unsigned char* Vp = Vg + tid * 16;
;   const int kst0 = kr0_ * K8ROW + kp0_ * 16, kst1 = kr1_ * K8ROW + kp1_ * 16, vst = (tid >> 2) * V8ROW + (tid & 3) * 16;
;   const bool two = tid < 256;
;   u32x4 sk0, sk1 = {}, sv;
;     ...
;   f32x16 pA0, pA1, pB0, pB1; float mnA, mnB, alA, alB; i32x8 pf;
;   int k4 = 0, v5 = 0;
;     ...
;   SLOAD(0); SWRITE(0, 0); SLOAD(1); SWRITE(1, 1); SLOAD(2); __syncthreads();
;   SWRITE(2, 2); SLOAD(3);
;   qkt8(pA0, pA1, K_lds, qf, r32, hi); partialSM8(pA0, pA1, m_reg, mnA, alA);
;   ADV();
;   for (int j = 1; j + 1 < NT; j += 2) {
;     __syncthreads();
;     if (j + 2 < NT) SWRITE((k4 + 2) & 3, VP2());
;     if (j + 3 < NT) SLOAD(j + 3);
	v_mfma_scale_f32_32x32x64_f8f6f4 v[16:31], v[48:55], v[136:143], v[16:31], v193, v193 op_sel_hi:[0,0,0]
	s_nop 2
	v_max_f32_e32 v48, v33, v33
	v_max_f32_e32 v49, v32, v32
	v_max_f32_e32 v48, v49, v48
	v_max3_f32 v48, v48, v34, v35
	v_max3_f32 v48, v48, v36, v37
	v_max3_f32 v48, v48, v38, v39
	v_max3_f32 v48, v48, v40, v41
	v_max3_f32 v48, v48, v42, v43
	v_max3_f32 v48, v48, v44, v45
	v_max3_f32 v48, v48, v46, v47
	v_mov_b64_e32 v[8:9], s[20:21]
	v_mov_b64_e32 v[10:11], s[22:23]
	v_mov_b64_e32 v[12:13], s[24:25]
	v_mov_b64_e32 v[78:79], v[14:15]
	v_lshl_add_u32 v215, v209, 2, v159
	s_nop 1
	v_max3_f32 v48, v48, v16, v17
	v_max3_f32 v48, v48, v18, v19
	v_max3_f32 v48, v48, v20, v21
	v_max3_f32 v48, v48, v22, v23
	v_max3_f32 v48, v48, v24, v25
	v_max3_f32 v48, v48, v26, v27
	v_max3_f32 v48, v48, v28, v29
	v_max3_f32 v48, v48, v30, v31
	v_mov_b32_e32 v49, v48
	s_nop 1
	v_permlane32_swap_b32_e32 v48, v49
	v_max_f32_e32 v49, v49, v49
	v_max_f32_e32 v48, v48, v48
	v_max_f32_e32 v48, v48, v49
	v_add_f32_e32 v49, 0x7149f2ca, v48
	v_cmp_ge_f32_e32 vcc, s61, v49
	s_cmp_lg_u64 vcc, exec
	v_max_f32_e32 v48, 0xf149f2ca, v48
	s_cselect_b64 vcc, -1, 0
	v_cndmask_b32_e32 v216, v208, v48, vcc
	v_sub_f32_e32 v48, 0x42c04d6a, v216
	v_pk_add_f32 v[198:199], v[16:17], v[48:49] op_sel_hi:[1,0]
	v_lshlrev_b32_e32 v16, 7, v209
	v_sub_u32_e32 v217, v214, v16
	v_add_u32_e32 v252, v162, v164
	v_add_u32_e32 v253, v168, v170
	s_add_u32 s100, s10, s34
	s_addc_u32 s101, s11, s35
	s_add_u32 s100, s100, s30
	s_addc_u32 s101, s101, s31
	s_add_u32 s100, s100, 0x17b00000
	s_addc_u32 s101, s101, 0
	s_add_u32 s10, s33, s46
	v_pk_add_f32 v[114:115], v[46:47], v[48:49] op_sel_hi:[1,0]
	v_pk_add_f32 v[116:117], v[44:45], v[48:49] op_sel_hi:[1,0]
	v_pk_add_f32 v[118:119], v[42:43], v[48:49] op_sel_hi:[1,0]
	v_pk_add_f32 v[172:173], v[40:41], v[48:49] op_sel_hi:[1,0]
	v_pk_add_f32 v[174:175], v[38:39], v[48:49] op_sel_hi:[1,0]
	v_pk_add_f32 v[178:179], v[36:37], v[48:49] op_sel_hi:[1,0]
	v_pk_add_f32 v[182:183], v[34:35], v[48:49] op_sel_hi:[1,0]
	v_pk_add_f32 v[184:185], v[32:33], v[48:49] op_sel_hi:[1,0]
	v_pk_add_f32 v[176:177], v[30:31], v[48:49] op_sel_hi:[1,0]
	v_pk_add_f32 v[180:181], v[28:29], v[48:49] op_sel_hi:[1,0]
	v_pk_add_f32 v[186:187], v[26:27], v[48:49] op_sel_hi:[1,0]
	v_pk_add_f32 v[188:189], v[24:25], v[48:49] op_sel_hi:[1,0]
	v_pk_add_f32 v[190:191], v[22:23], v[48:49] op_sel_hi:[1,0]
	v_pk_add_f32 v[194:195], v[20:21], v[48:49] op_sel_hi:[1,0]
	v_pk_add_f32 v[196:197], v[18:19], v[48:49] op_sel_hi:[1,0]
	s_addc_u32 s11, 0, s47
	v_mov_b64_e32 v[30:31], v[14:15]
	v_mov_b64_e32 v[46:47], v[14:15]
	v_mov_b64_e32 v[62:63], v[14:15]
	v_lshlrev_b32_e32 v213, 4, v210
	s_add_u32 s98, s10, s30
	s_addc_u32 s99, s11, s31
	s_add_u32 s98, s98, 0x25e48000
	s_addc_u32 s99, s99, 0
	s_mov_b32 s18, 1
	v_mov_b64_e32 v[28:29], v[12:13]
	v_mov_b64_e32 v[26:27], v[10:11]
	v_mov_b64_e32 v[24:25], v[8:9]
	v_mov_b64_e32 v[22:23], v[6:7]
	v_mov_b64_e32 v[20:21], v[4:5]
	v_mov_b64_e32 v[18:19], v[2:3]
	v_mov_b64_e32 v[16:17], v[0:1]
	v_mov_b64_e32 v[44:45], v[12:13]
	v_mov_b64_e32 v[42:43], v[10:11]
	v_mov_b64_e32 v[40:41], v[8:9]
	v_mov_b64_e32 v[38:39], v[6:7]
	v_mov_b64_e32 v[36:37], v[4:5]
	v_mov_b64_e32 v[34:35], v[2:3]
	v_mov_b64_e32 v[32:33], v[0:1]
	v_mov_b64_e32 v[60:61], v[12:13]
	v_mov_b64_e32 v[58:59], v[10:11]
	v_mov_b64_e32 v[56:57], v[8:9]
	v_mov_b64_e32 v[54:55], v[6:7]
	v_mov_b64_e32 v[52:53], v[4:5]
	v_mov_b64_e32 v[50:51], v[2:3]
	v_mov_b64_e32 v[48:49], v[0:1]
	s_mov_b32 s21, 1
	s_mov_b32 s22, 1
	v_mov_b64_e32 v[76:77], v[12:13]
	v_mov_b64_e32 v[74:75], v[10:11]
	v_mov_b64_e32 v[72:73], v[8:9]
	v_mov_b64_e32 v[70:71], v[6:7]
	v_mov_b64_e32 v[68:69], v[4:5]
	v_mov_b64_e32 v[66:67], v[2:3]
	v_mov_b64_e32 v[64:65], v[0:1]
.LBB0_906:
	s_cmp_gt_i32 s21, 2
	s_cselect_b32 s2, -3, 2
	s_add_i32 s2, s2, s21
	s_mulk_i32 s2, 0x2800
	s_xor_b32 s19, s22, 2
	v_add_u32_e32 v80, s2, v161
	s_mul_i32 s2, s19, 0x3400
	s_add_i32 s20, s2, 0
	s_barrier
	s_waitcnt vmcnt(1)
	ds_write_b128 v80, v[150:153]
	v_add_u32_e32 v80, s20, v158
	s_waitcnt vmcnt(0)
	ds_write_b128 v80, v[154:157] offset:51200
	s_and_saveexec_b64 s[10:11], s[6:7]
	v_add_u32_e32 v80, s20, v160
	ds_write_b128 v80, v[146:149] offset:51200
	s_or_b64 exec, exec, s[10:11]
	s_cmpk_lt_u32 s18, 0xfd
	s_cselect_b64 s[14:15], -1, 0
	s_cmpk_gt_u32 s18, 0xfc
	s_cselect_b64 s[12:13], -1, 0
	s_and_b64 vcc, exec, s[12:13]
	s_cbranch_vccnz .LBB0_912
	global_load_dwordx4 v[150:153], v166, s[98:99]
	global_load_dwordx4 v[154:157], v252, s[100:101]
	s_and_saveexec_b64 s[10:11], s[6:7]
	s_cbranch_execz .LBB0_911
	global_load_dwordx4 v[146:149], v253, s[100:101]
.LBB0_911:
	s_or_b64 exec, exec, s[10:11]
	s_add_u32 s98, s98, 0x2000
	s_addc_u32 s99, s99, 0
	s_add_u32 s100, s100, 0x30000
	s_addc_u32 s101, s101, 0

; #define SLOAD(k0) do { sv0 = *reinterpret_cast<const bf16x8*>(Vp + (k0) * LDV); sv1 = *reinterpret_cast<const bf16x8*>(Vp + ((k0) + 32) * LDV); \
;     sk0 = *reinterpret_cast<const bf16x8*>(Kp + (k0) * LDK); sk1 = *reinterpret_cast<const bf16x8*>(Kp + ((k0) + 32) * LDK); \
;     if constexpr (DQK == 192) sk2 = *reinterpret_cast<const bf16x8*>(Kp2 + (k0) * LDK); } while (0)
; #define SWRITE(KB, VB) do { *(bf16x8*)(V_lds + (VB) * SHM_V + vst0) = sv0; *(bf16x8*)(V_lds + (VB) * SHM_V + vst1) = sv1; \
;     *(bf16x8*)(K_lds + (KB) * SHM_K + kst0) = sk0; *(bf16x8*)(K_lds + (KB) * SHM_K + kst1) = sk1; } while (0)
; #define SLOAD(TILE) do { sv = *reinterpret_cast<const u32x4*>(Vp + (TILE) * 8192); sk0 = *reinterpret_cast<const u32x4*>(Kp0 + (TILE) * (64 * 3072)); \
;     if (two) sk1 = *reinterpret_cast<const u32x4*>(Kp1 + (TILE) * (64 * 3072)); } while (0)
; #define SWRITE(KB, VB) do { *(u32x4*)(V_lds + (VB) * SHM_V8 + vst) = sv; *(u32x4*)(K_lds + (KB) * SHM_K8 + kst0) = sk0; \
;     if (two) *(u32x4*)(K_lds + (KB) * SHM_K8 + kst1) = sk1; } while (0)
; __device__ __forceinline__ void attn_body8(const bf16* __restrict__ Qb, const unsigned char* __restrict__ Kg, const unsigned char* __restrict__ Vg, ...
;     ...
;     if (j + 3 < NT) SWRITE((k4 + 2) & 3, VP2());
;     if (j + 4 < NT) SLOAD(j + 4);
.LBB0_920:
	s_cmpk_gt_u32 s18, 0xfb
	s_cbranch_scc1 .LBB0_924
	global_load_dwordx4 v[150:153], v166, s[98:99]
	global_load_dwordx4 v[154:157], v252, s[100:101]
	s_and_saveexec_b64 s[14:15], s[6:7]
	s_cbranch_execz .LBB0_923
	global_load_dwordx4 v[146:149], v253, s[100:101]
.LBB0_923:
	s_or_b64 exec, exec, s[14:15]
	s_add_u32 s98, s98, 0x2000
	s_addc_u32 s99, s99, 0
	s_add_u32 s100, s100, 0x30000
	s_addc_u32 s101, s101, 0

; #define RESC(a) do { if (__any((a) < 1.f)) { if (hi == 0) al_l[r32] = (a); asm volatile("s_waitcnt lgkmcnt(0)" ::: "memory"); \
;     _Pragma("unroll") for (int d = 0; d < 4; ++d) _Pragma("unroll") for (int r = 0; r < 16; ++r) o[d][r] *= al_l[crow(r, hi)]; } } while (0)
; #define ADV() do { k3 = (k3 == 2) ? 0 : k3 + 1; v4 = (v4 + 1) & 3; } while (0)
; #define RESC(a) do { if (__any((a) < 1.f)) { if (hi == 0) al_l[r32] = (a); asm volatile("s_waitcnt lgkmcnt(0)" ::: "memory"); \
;     _Pragma("unroll") for (int r = 0; r < 16; ++r) { const float a_ = al_l[crow(r, hi)]; lacc[r] *= a_; _Pragma("unroll") for (int d = 0; d < 4; ++d) o[d][r] *= a_; } } } while (0)
; #define ADV() do { k4 = (k4 + 1) & 3; v5 = (v5 == 4) ? 0 : v5 + 1; } while (0)
; __device__ __forceinline__ void partialSM8(f32x16& p0, f32x16& p1, float& m_reg, float& mn, float& alpha) {
;     ...
;   const float mn8 = (P8SHIFT + 7.f - 0.0436f) * 8.f + 0.5f - mn;
; #pragma unroll
;   for (int r = 0; r < 16; ++r) p0[r] += mn8;
; #pragma unroll
;   for (int r = 0; r < 16; ++r) p1[r] += mn8;
; __device__ __forceinline__ void attn_body8(const bf16* __restrict__ Qb, const unsigned char* __restrict__ Kg, const unsigned char* __restrict__ Vg, ...
;     ...
;     pv8(o, lacc, V_lds + VM1() * SHM_V8, pf, r32, hi); partialSM8(pA0, pA1, m_reg, mnA, alA);
;     RESC(alA);
;     ADV();
;   }
.LBB0_928:
	v_cndmask_b32_e64 v216, v169, v168, s[10:11]
	s_add_i32 s18, s18, 2
	s_add_i32 s2, s16, 1
	v_sub_f32_e32 v168, 0x42c04d6a, v216
	s_cmp_lg_u32 s16, 4
	v_pk_add_f32 v[184:185], v[96:97], v[168:169] op_sel_hi:[1,0]
	v_pk_add_f32 v[182:183], v[98:99], v[168:169] op_sel_hi:[1,0]
	v_pk_add_f32 v[178:179], v[100:101], v[168:169] op_sel_hi:[1,0]
	v_pk_add_f32 v[174:175], v[102:103], v[168:169] op_sel_hi:[1,0]
	v_pk_add_f32 v[172:173], v[104:105], v[168:169] op_sel_hi:[1,0]
	v_pk_add_f32 v[118:119], v[106:107], v[168:169] op_sel_hi:[1,0]
	v_pk_add_f32 v[116:117], v[108:109], v[168:169] op_sel_hi:[1,0]
	v_pk_add_f32 v[114:115], v[110:111], v[168:169] op_sel_hi:[1,0]
	v_pk_add_f32 v[198:199], v[80:81], v[168:169] op_sel_hi:[1,0]
	v_pk_add_f32 v[196:197], v[82:83], v[168:169] op_sel_hi:[1,0]
	v_pk_add_f32 v[194:195], v[84:85], v[168:169] op_sel_hi:[1,0]
	v_pk_add_f32 v[190:191], v[86:87], v[168:169] op_sel_hi:[1,0]
	v_pk_add_f32 v[188:189], v[88:89], v[168:169] op_sel_hi:[1,0]
	v_pk_add_f32 v[186:187], v[90:91], v[168:169] op_sel_hi:[1,0]
	v_pk_add_f32 v[180:181], v[92:93], v[168:169] op_sel_hi:[1,0]
	v_pk_add_f32 v[176:177], v[94:95], v[168:169] op_sel_hi:[1,0]
	s_cselect_b32 s21, s2, 0
	s_and_b64 vcc, exec, s[12:13]
	s_cbranch_vccnz .LBB0_930
	s_mov_b32 s22, s19
	s_branch .LBB0_906

; __device__ __forceinline__ int mytid(int wv) { return (wv << 6) | (int)__builtin_amdgcn_mbcnt_hi(~0u, __builtin_amdgcn_mbcnt_lo(~0u, 0u)); }
; #define STAGE_A(P, hf, kt) do { if constexpr (ABLK) { const bf16* _gp = A + ((long)(brow >> 8) * nt + (kt)) * 16384 + (hf) * 8192; GLDS2(_gp, 4096, offA, P); } \
;     else { const bf16* _gp = A + (long)(brow + (hf) * HALF) * lda + (long)(kt) * BK; GLDS2(_gp, 64 * (long)lda, offA, P); } } while (0)
; #define STAGE_B(P, hf, kt) do { const bf16* _gp = Bt + (long)(bcol + (hf) * 2) * ldb + (long)(kt) * BK; GLDS2(_gp, 128 * (long)ldb, offB, P); } while (0)
; #define BAR __builtin_amdgcn_s_barrier()
; template <bool ABLK, class Epi>
; __device__ __forceinline__ void gemm_tile(const bf16* __restrict__ A, int lda, const bf16* __restrict__ Bt, int ldb, int K,
;                                           int brow, int bcol, bf16* shm, const Epi& epi, int wv) {
;     ...
;   int tid = mytid(wv); asm volatile("" : "+v"(tid));
;   const int wid = tid >> 6, lane = tid & 63, wr = wid >> 2, wc = wid & 3, fr = lane & 15, fq = lane >> 4;
;   f32x4 acc[2][2][4][2] = {};
;   bf16x8 At[4][2], B0[2][2], B1[2][2];
;   const int nt = K / BK;
;   int offA, offB;
;   { int r_, c_; stage_rc(tid * 16, r_, c_); offA = ABLK ? r_ * 64 + c_ : r_ * lda + c_;
;     offB = ((r_ >> 5) * 64 + (r_ & 15) * 4 + ((r_ >> 4) & 1)) * ldb + c_; }
;   STAGE_B(SB(0, 0), 0, 0); STAGE_A(SA(0, 0), 0, 0);
;   STAGE_B(SB(0, 1), 1, 0); STAGE_A(SA(0, 1), 1, 0);
;   if (wr == 1) BAR;
; template <bool ABLK, class Epi>
; __device__ __forceinline__ void gemm_phase(const bf16* A, int lda, const bf16* Bt, int ldb, int M, int N, int K, char* smem, const Epi& epi, int wv) {
;     ...
;   for (int w = blockIdx.x; w < nwg; w += gridDim.x) {
;     int wgid = w;
;     { int q = nwg / NXCD, r = nwg % NXCD, xcd = wgid % NXCD, off = wgid / NXCD;
;       wgid = (xcd < r ? xcd * (q + 1) : r * (q + 1) + (xcd - r) * q) + off; }
;     const int nig = WGM * nN, gid = wgid / nig, fm = gid * WGM, gsz = min(nM - fm, WGM);
;     const int pm = fm + ((wgid % nig) % gsz), pn = (wgid % nig) / gsz;
;     gemm_tile<ABLK>(A, lda, Bt, ldb, K, pm * BM, pn * BM, (bf16*)smem, epi, wv);
.LBB0_974:
	s_ashr_i32 s2, s84, 31
	s_lshr_b32 s2, s2, 29
	s_add_i32 s2, s84, s2
	s_ashr_i32 s33, s2, 3
	s_and_b32 s2, s2, -8
	v_mov_b32_e32 v135, v192
	s_sub_i32 s2, s84, s2
	s_cmp_lt_i32 s2, 0
	v_ashrrev_i32_e32 v0, 31, v135
	v_lshrrev_b32_e32 v0, 26, v0
	s_cselect_b32 s62, s0, 0xc0
	v_add_u32_e32 v0, v135, v0
	s_mul_i32 s2, s62, s2
	v_ashrrev_i32_e32 v4, 6, v0
	v_bfe_i32 v0, v135, 27, 1
	s_add_i32 s2, s2, s33
	v_lshlrev_b32_e32 v11, 4, v135
	v_lshrrev_b32_e32 v0, 22, v0
	s_ashr_i32 s33, s2, 31
	v_add_u32_e32 v0, v11, v0
	s_lshr_b32 s33, s33, 27
	v_and_b32_e32 v0, 0xfffffc00, v0
	s_add_i32 s33, s2, s33
	v_sub_u32_e32 v0, v11, v0
	s_ashr_i32 s62, s33, 5
	s_and_b32 s33, s33, 0xffe0
	v_lshrrev_b32_e32 v1, 4, v0
	s_sub_i32 s2, s2, s33
	v_bitop3_b32 v0, v1, v0, 32 bitop3:0x6c
	s_bfe_i32 s33, s2, 0x80000
	v_ashrrev_i32_e32 v2, 31, v0
	s_bfe_u32 s33, s33, 0x2000d
	v_lshrrev_b32_e32 v2, 26, v2
	s_add_i32 s33, s2, s33
	v_lshlrev_b32_e32 v1, 3, v4
	v_add_u32_e32 v2, v0, v2
	s_bfe_i32 s63, s33, 0x80000
	s_and_b32 s33, s33, 0xfc
	v_and_b32_e32 v1, -16, v1
	v_ashrrev_i32_e32 v3, 6, v2
	v_and_b32_e32 v9, 0xffffffc0, v2
	s_sub_i32 s2, s2, s33
	v_add_u32_e32 v1, v3, v1
	v_lshlrev_b32_e32 v3, 5, v4
	v_sub_u32_e32 v0, v0, v9
	s_lshl_b32 s62, s62, 2
	s_sext_i32_i16 s63, s63
	s_sext_i32_i8 s2, s2
	v_and_b32_e32 v5, 32, v3
	v_ashrrev_i16_sdwa v0, v134, sext(v0) dst_sel:DWORD dst_unused:UNUSED_PAD src0_sel:DWORD src1_sel:BYTE_0
	v_lshlrev_b32_e32 v3, 1, v1
	s_add_i32 s64, s62, s2
	s_lshl_b32 s2, s63, 6
	v_bfe_i32 v6, v0, 0, 16
	v_and_b32_e32 v7, 0xffffffc0, v3
	v_lshlrev_b32_e32 v3, 2, v1
	s_and_b32 s62, s2, 0xffffff00
	v_add_u32_e32 v0, v5, v6
	v_and_b32_e32 v8, 60, v3
	v_bfe_u32 v10, v1, 4, 1
	v_lshl_add_u32 v2, v1, 6, v0
	v_or3_b32 v1, v7, v8, v10
	s_ashr_i32 s63, s62, 31
	v_lshl_add_u32 v0, v1, 11, v0
	s_lshl_b64 s[66:67], s[62:63], 12
	s_add_u32 s68, s72, s66
	v_ashrrev_i32_e32 v1, 31, v0
	s_addc_u32 s69, s73, s67
	v_lshlrev_b64 v[12:13], 1, v[0:1]
	s_ashr_i32 s65, s64, 31
	v_lshl_add_u64 v[0:1], s[68:69], 0, v[12:13]
	s_lshl_b64 s[68:69], s[64:65], 20
	s_add_u32 s70, s1, s68
	v_add_u32_e32 v144, s78, v11
	s_addc_u32 s71, s3, s69
	v_ashrrev_i32_e32 v3, 31, v2
	v_readfirstlane_b32 s2, v144
	v_add_u32_e32 v145, 0x2000, v144
	v_lshl_add_u64 v[128:129], v[2:3], 1, s[70:71]
	s_or_b32 s70, s62, 2
	s_mov_b32 m0, s2
	v_readfirstlane_b32 s2, v145
	v_add_u32_e32 v147, 0, v11
	s_ashr_i32 s71, s70, 31
	global_load_lds_dwordx4 v[0:1], off
	v_lshl_add_u64 v[14:15], v[0:1], 0, s[8:9]
	s_mov_b32 m0, s2
	v_readfirstlane_b32 s2, v147
	v_add_u32_e32 v148, 0x2000, v147
	s_lshl_b64 s[70:71], s[70:71], 12
	global_load_lds_dwordx4 v[14:15], off
	s_mov_b32 m0, s2
	v_readfirstlane_b32 s2, v148
	s_add_u32 s70, s72, s70
	v_add_u32_e32 v150, s79, v11
	global_load_lds_dwordx4 v[128:129], off
	v_lshl_add_u64 v[2:3], v[128:129], 0, s[10:11]
	s_mov_b32 m0, s2
	s_addc_u32 s71, s73, s71
	v_readfirstlane_b32 s2, v150
	v_add_u32_e32 v151, 0x2000, v150
	global_load_lds_dwordx4 v[2:3], off
	v_lshl_add_u64 v[2:3], s[70:71], 0, v[12:13]
	s_mov_b32 m0, s2
	v_readfirstlane_b32 s2, v151
	v_add_u32_e32 v152, 0x4000, v147
	global_load_lds_dwordx4 v[2:3], off
	v_lshl_add_u64 v[12:13], v[2:3], 0, s[8:9]
	s_mov_b32 m0, s2
	v_readfirstlane_b32 s2, v152
	v_add_u32_e32 v153, 0x6000, v147
	global_load_lds_dwordx4 v[12:13], off
	v_lshl_add_u64 v[12:13], v[128:129], 0, s[12:13]
	s_mov_b32 m0, s2
	v_readfirstlane_b32 s2, v153
	global_load_lds_dwordx4 v[12:13], off
	v_lshl_add_u64 v[12:13], v[128:129], 0, s[14:15]
	s_mov_b32 m0, s2
	s_nop 0
	global_load_lds_dwordx4 v[12:13], off
	v_mov_b32_e32 v20, 0
	v_mov_b32_e32 v21, 0
	v_mov_b32_e32 v22, 0
	v_mov_b32_e32 v23, 0
	v_mov_b32_e32 v24, 0
	v_mov_b32_e32 v25, 0
	v_mov_b32_e32 v26, 0
	v_mov_b32_e32 v27, 0
	v_mov_b32_e32 v28, 0
	v_mov_b32_e32 v29, 0
	v_mov_b32_e32 v30, 0
	v_mov_b32_e32 v31, 0
	v_mov_b32_e32 v32, 0
	v_mov_b32_e32 v33, 0
	v_mov_b32_e32 v34, 0
	v_mov_b32_e32 v35, 0
	v_mov_b32_e32 v36, 0
	v_mov_b32_e32 v37, 0
	v_mov_b32_e32 v38, 0
	v_mov_b32_e32 v39, 0
	v_mov_b32_e32 v40, 0
	v_mov_b32_e32 v41, 0
	v_mov_b32_e32 v42, 0
	v_mov_b32_e32 v43, 0
	v_mov_b32_e32 v44, 0
	v_mov_b32_e32 v45, 0
	v_mov_b32_e32 v46, 0
	v_mov_b32_e32 v47, 0
	v_mov_b32_e32 v48, 0
	v_mov_b32_e32 v49, 0
	v_mov_b32_e32 v50, 0
	v_mov_b32_e32 v51, 0
	v_mov_b32_e32 v52, 0
	v_mov_b32_e32 v53, 0
	v_mov_b32_e32 v54, 0
	v_mov_b32_e32 v55, 0
	v_mov_b32_e32 v56, 0
	v_mov_b32_e32 v57, 0
	v_mov_b32_e32 v58, 0
	v_mov_b32_e32 v59, 0
	v_mov_b32_e32 v60, 0
	v_mov_b32_e32 v61, 0
	v_mov_b32_e32 v62, 0
	v_mov_b32_e32 v63, 0
	v_mov_b32_e32 v64, 0
	v_mov_b32_e32 v65, 0
	v_mov_b32_e32 v66, 0
	v_mov_b32_e32 v67, 0
	v_mov_b32_e32 v68, 0
	v_mov_b32_e32 v69, 0
	v_mov_b32_e32 v70, 0
	v_mov_b32_e32 v71, 0
	v_mov_b32_e32 v72, 0
	v_mov_b32_e32 v73, 0
	v_mov_b32_e32 v74, 0
	v_mov_b32_e32 v75, 0
	v_mov_b32_e32 v76, 0
	v_mov_b32_e32 v77, 0
	v_mov_b32_e32 v78, 0
	v_mov_b32_e32 v79, 0
	v_mov_b32_e32 v80, 0
	v_mov_b32_e32 v81, 0
	v_mov_b32_e32 v82, 0
	v_mov_b32_e32 v83, 0
	v_mov_b32_e32 v84, 0
	v_mov_b32_e32 v85, 0
	v_mov_b32_e32 v86, 0
	v_mov_b32_e32 v87, 0
	v_mov_b32_e32 v88, 0
	v_mov_b32_e32 v89, 0
	v_mov_b32_e32 v90, 0
	v_mov_b32_e32 v91, 0
	v_mov_b32_e32 v92, 0
	v_mov_b32_e32 v93, 0
	v_mov_b32_e32 v94, 0
	v_mov_b32_e32 v95, 0
	v_mov_b32_e32 v96, 0
	v_mov_b32_e32 v97, 0
	v_mov_b32_e32 v98, 0
	v_mov_b32_e32 v99, 0
	v_mov_b32_e32 v100, 0
	v_mov_b32_e32 v101, 0
	v_mov_b32_e32 v102, 0
	v_mov_b32_e32 v103, 0
	v_mov_b32_e32 v104, 0
	v_mov_b32_e32 v105, 0
	v_mov_b32_e32 v106, 0
	v_mov_b32_e32 v107, 0
	v_mov_b32_e32 v108, 0
	v_mov_b32_e32 v109, 0
	v_mov_b32_e32 v110, 0
	v_mov_b32_e32 v111, 0
	v_mov_b32_e32 v112, 0
	v_mov_b32_e32 v113, 0
	v_mov_b32_e32 v114, 0
	v_mov_b32_e32 v115, 0
	v_mov_b32_e32 v116, 0
	v_mov_b32_e32 v117, 0
	v_mov_b32_e32 v118, 0
	v_mov_b32_e32 v119, 0
	v_mov_b32_e32 v120, 0
	v_mov_b32_e32 v121, 0
	v_mov_b32_e32 v122, 0
	v_mov_b32_e32 v123, 0
	v_mov_b32_e32 v124, 0
	v_mov_b32_e32 v125, 0
	v_mov_b32_e32 v126, 0
	v_mov_b32_e32 v127, 0
	v_ashrrev_i32_e32 v12, 8, v135
	v_cmp_eq_u32_e32 vcc, 1, v12
	s_and_saveexec_b64 s[70:71], vcc
	s_cbranch_execz .LBB0_976
	s_barrier

; __device__ __forceinline__ int mytid(int wv) { return (wv << 6) | (int)__builtin_amdgcn_mbcnt_hi(~0u, __builtin_amdgcn_mbcnt_lo(~0u, 0u)); }
; #define STAGE_A(P, hf, kt) do { if constexpr (ABLK) { const bf16* _gp = A + ((long)(brow >> 8) * nt + (kt)) * 16384 + (hf) * 8192; GLDS2(_gp, 4096, offA, P); } \
;     else { const bf16* _gp = A + (long)(brow + (hf) * HALF) * lda + (long)(kt) * BK; GLDS2(_gp, 64 * (long)lda, offA, P); } } while (0)
; #define STAGE_B(P, hf, kt) do { const bf16* _gp = Bt + (long)(bcol + (hf) * 2) * ldb + (long)(kt) * BK; GLDS2(_gp, 128 * (long)ldb, offB, P); } while (0)
; #define BAR __builtin_amdgcn_s_barrier()
; template <bool ABLK, class Epi>
; __device__ __forceinline__ void gemm_tile(const bf16* __restrict__ A, int lda, const bf16* __restrict__ Bt, int ldb, int K,
;                                           int brow, int bcol, bf16* shm, const Epi& epi, int wv) {
;     ...
;   int tid = mytid(wv); asm volatile("" : "+v"(tid));
;   const int wid = tid >> 6, lane = tid & 63, wr = wid >> 2, wc = wid & 3, fr = lane & 15, fq = lane >> 4;
;   f32x4 acc[2][2][4][2] = {};
;   bf16x8 At[4][2], B0[2][2], B1[2][2];
;   const int nt = K / BK;
;   int offA, offB;
;   { int r_, c_; stage_rc(tid * 16, r_, c_); offA = ABLK ? r_ * 64 + c_ : r_ * lda + c_;
;     offB = ((r_ >> 5) * 64 + (r_ & 15) * 4 + ((r_ >> 4) & 1)) * ldb + c_; }
;   STAGE_B(SB(0, 0), 0, 0); STAGE_A(SA(0, 0), 0, 0);
;   STAGE_B(SB(0, 1), 1, 0); STAGE_A(SA(0, 1), 1, 0);
;   if (wr == 1) BAR;
; template <bool ABLK, class Epi>
; __device__ __forceinline__ void gemm_phase(const bf16* A, int lda, const bf16* Bt, int ldb, int M, int N, int K, char* smem, const Epi& epi, int wv) {
;     ...
;   for (int w = blockIdx.x; w < nwg; w += gridDim.x) {
;     int wgid = w;
;     { int q = nwg / NXCD, r = nwg % NXCD, xcd = wgid % NXCD, off = wgid / NXCD;
;       wgid = (xcd < r ? xcd * (q + 1) : r * (q + 1) + (xcd - r) * q) + off; }
;     const int nig = WGM * nN, gid = wgid / nig, fm = gid * WGM, gsz = min(nM - fm, WGM);
;     const int pm = fm + ((wgid % nig) % gsz), pn = (wgid % nig) / gsz;
;     gemm_tile<ABLK>(A, lda, Bt, ldb, K, pm * BM, pn * BM, (bf16*)smem, epi, wv);
.LBB0_1061:
	s_ashr_i32 s2, s84, 31
	s_lshr_b32 s2, s2, 29
	s_add_i32 s2, s84, s2
	s_ashr_i32 s33, s2, 3
	s_and_b32 s2, s2, -8
	v_mov_b32_e32 v128, v192
	s_sub_i32 s2, s84, s2
	s_cmp_lt_i32 s2, 0
	v_ashrrev_i32_e32 v0, 31, v128
	v_lshrrev_b32_e32 v0, 26, v0
	s_cselect_b32 s60, s0, 0x420
	v_add_u32_e32 v0, v128, v0
	s_mul_i32 s2, s60, s2
	v_ashrrev_i32_e32 v4, 6, v0
	v_bfe_i32 v0, v128, 27, 1
	s_add_i32 s2, s2, s33
	v_lshlrev_b32_e32 v11, 4, v128
	v_lshrrev_b32_e32 v0, 22, v0
	s_mul_hi_i32 s33, s2, 0x2e8ba2e9
	v_add_u32_e32 v0, v11, v0
	s_lshr_b32 s60, s33, 31
	s_ashr_i32 s33, s33, 5
	v_and_b32_e32 v0, 0xfffffc00, v0
	s_add_i32 s33, s33, s60
	v_sub_u32_e32 v0, v11, v0
	s_lshl_b32 s60, s33, 2
	s_mulk_i32 s33, 0xb0
	v_lshrrev_b32_e32 v1, 4, v0
	s_sub_i32 s2, s2, s33
	v_bitop3_b32 v0, v1, v0, 32 bitop3:0x6c
	s_sext_i32_i16 s33, s2
	v_ashrrev_i32_e32 v2, 31, v0
	s_bfe_u32 s33, s33, 0x2001d
	v_lshrrev_b32_e32 v2, 26, v2
	s_add_i32 s33, s2, s33
	v_lshlrev_b32_e32 v1, 3, v4
	v_add_u32_e32 v2, v0, v2
	s_sext_i32_i16 s61, s33
	s_and_b32 s33, s33, 0xfffc
	v_and_b32_e32 v1, -16, v1
	v_ashrrev_i32_e32 v3, 6, v2
	v_and_b32_e32 v9, 0xffffffc0, v2
	s_sub_i32 s2, s2, s33
	v_add_u32_e32 v1, v3, v1
	v_lshlrev_b32_e32 v3, 5, v4
	v_sub_u32_e32 v0, v0, v9
	s_sext_i32_i16 s2, s2
	v_and_b32_e32 v5, 32, v3
	v_ashrrev_i16_sdwa v0, v136, sext(v0) dst_sel:DWORD dst_unused:UNUSED_PAD src0_sel:DWORD src1_sel:BYTE_0
	v_lshlrev_b32_e32 v3, 1, v1
	s_add_i32 s62, s60, s2
	s_lshl_b32 s2, s61, 6
	v_bfe_i32 v6, v0, 0, 16
	v_and_b32_e32 v7, 0xffffffc0, v3
	v_lshlrev_b32_e32 v3, 2, v1
	s_and_b32 s60, s2, 0xffffff00
	v_add_u32_e32 v0, v5, v6
	v_and_b32_e32 v8, 60, v3
	v_bfe_u32 v10, v1, 4, 1
	v_lshl_add_u32 v2, v1, 6, v0
	v_or3_b32 v1, v7, v8, v10
	s_ashr_i32 s61, s60, 31
	v_lshl_add_u32 v0, v1, 11, v0
	s_lshl_b64 s[64:65], s[60:61], 12
	s_add_u32 s66, s70, s64
	v_ashrrev_i32_e32 v1, 31, v0
	s_addc_u32 s67, s71, s65
	v_lshlrev_b64 v[12:13], 1, v[0:1]
	s_ashr_i32 s63, s62, 31
	v_lshl_add_u64 v[0:1], s[66:67], 0, v[12:13]
	s_lshl_b64 s[66:67], s[62:63], 20
	s_add_u32 s68, s1, s66
	v_add_u32_e32 v145, s76, v11
	s_addc_u32 s69, s3, s67
	v_ashrrev_i32_e32 v3, 31, v2
	v_readfirstlane_b32 s2, v145
	v_add_u32_e32 v146, 0x2000, v145
	v_lshl_add_u64 v[130:131], v[2:3], 1, s[68:69]
	s_or_b32 s68, s60, 2
	s_mov_b32 m0, s2
	v_readfirstlane_b32 s2, v146
	v_add_u32_e32 v148, 0, v11
	s_ashr_i32 s69, s68, 31
	global_load_lds_dwordx4 v[0:1], off
	v_lshl_add_u64 v[14:15], v[0:1], 0, s[8:9]
	s_mov_b32 m0, s2
	v_readfirstlane_b32 s2, v148
	v_add_u32_e32 v149, 0x2000, v148
	s_lshl_b64 s[68:69], s[68:69], 12
	global_load_lds_dwordx4 v[14:15], off
	s_mov_b32 m0, s2
	v_readfirstlane_b32 s2, v149
	s_add_u32 s68, s70, s68
	v_add_u32_e32 v151, s77, v11
	global_load_lds_dwordx4 v[130:131], off
	v_lshl_add_u64 v[2:3], v[130:131], 0, s[10:11]
	s_mov_b32 m0, s2
	s_addc_u32 s69, s71, s69
	v_readfirstlane_b32 s2, v151
	v_add_u32_e32 v152, 0x2000, v151
	global_load_lds_dwordx4 v[2:3], off
	v_lshl_add_u64 v[2:3], s[68:69], 0, v[12:13]
	s_mov_b32 m0, s2
	v_readfirstlane_b32 s2, v152
	v_add_u32_e32 v153, 0x4000, v148
	global_load_lds_dwordx4 v[2:3], off
	v_lshl_add_u64 v[12:13], v[2:3], 0, s[8:9]
	s_mov_b32 m0, s2
	v_readfirstlane_b32 s2, v153
	v_add_u32_e32 v154, 0x6000, v148
	global_load_lds_dwordx4 v[12:13], off
	v_lshl_add_u64 v[12:13], v[130:131], 0, s[12:13]
	s_mov_b32 m0, s2
	v_readfirstlane_b32 s2, v154
	global_load_lds_dwordx4 v[12:13], off
	v_lshl_add_u64 v[12:13], v[130:131], 0, s[14:15]
	s_mov_b32 m0, s2
	s_nop 0
	global_load_lds_dwordx4 v[12:13], off
	v_mov_b32_e32 v20, 0
	v_mov_b32_e32 v21, 0
	v_mov_b32_e32 v22, 0
	v_mov_b32_e32 v23, 0
	v_mov_b32_e32 v24, 0
	v_mov_b32_e32 v25, 0
	v_mov_b32_e32 v26, 0
	v_mov_b32_e32 v27, 0
	v_mov_b32_e32 v28, 0
	v_mov_b32_e32 v29, 0
	v_mov_b32_e32 v30, 0
	v_mov_b32_e32 v31, 0
	v_mov_b32_e32 v32, 0
	v_mov_b32_e32 v33, 0
	v_mov_b32_e32 v34, 0
	v_mov_b32_e32 v35, 0
	v_mov_b32_e32 v36, 0
	v_mov_b32_e32 v37, 0
	v_mov_b32_e32 v38, 0
	v_mov_b32_e32 v39, 0
	v_mov_b32_e32 v40, 0
	v_mov_b32_e32 v41, 0
	v_mov_b32_e32 v42, 0
	v_mov_b32_e32 v43, 0
	v_mov_b32_e32 v44, 0
	v_mov_b32_e32 v45, 0
	v_mov_b32_e32 v46, 0
	v_mov_b32_e32 v47, 0
	v_mov_b32_e32 v48, 0
	v_mov_b32_e32 v49, 0
	v_mov_b32_e32 v50, 0
	v_mov_b32_e32 v51, 0
	v_mov_b32_e32 v52, 0
	v_mov_b32_e32 v53, 0
	v_mov_b32_e32 v54, 0
	v_mov_b32_e32 v55, 0
	v_mov_b32_e32 v56, 0
	v_mov_b32_e32 v57, 0
	v_mov_b32_e32 v58, 0
	v_mov_b32_e32 v59, 0
	v_mov_b32_e32 v60, 0
	v_mov_b32_e32 v61, 0
	v_mov_b32_e32 v62, 0
	v_mov_b32_e32 v63, 0
	v_mov_b32_e32 v64, 0
	v_mov_b32_e32 v65, 0
	v_mov_b32_e32 v66, 0
	v_mov_b32_e32 v67, 0
	v_mov_b32_e32 v68, 0
	v_mov_b32_e32 v69, 0
	v_mov_b32_e32 v70, 0
	v_mov_b32_e32 v71, 0
	v_mov_b32_e32 v72, 0
	v_mov_b32_e32 v73, 0
	v_mov_b32_e32 v74, 0
	v_mov_b32_e32 v75, 0
	v_mov_b32_e32 v76, 0
	v_mov_b32_e32 v77, 0
	v_mov_b32_e32 v78, 0
	v_mov_b32_e32 v79, 0
	v_mov_b32_e32 v80, 0
	v_mov_b32_e32 v81, 0
	v_mov_b32_e32 v82, 0
	v_mov_b32_e32 v83, 0
	v_mov_b32_e32 v84, 0
	v_mov_b32_e32 v85, 0
	v_mov_b32_e32 v86, 0
	v_mov_b32_e32 v87, 0
	v_mov_b32_e32 v88, 0
	v_mov_b32_e32 v89, 0
	v_mov_b32_e32 v90, 0
	v_mov_b32_e32 v91, 0
	v_mov_b32_e32 v92, 0
	v_mov_b32_e32 v93, 0
	v_mov_b32_e32 v94, 0
	v_mov_b32_e32 v95, 0
	v_mov_b32_e32 v96, 0
	v_mov_b32_e32 v97, 0
	v_mov_b32_e32 v98, 0
	v_mov_b32_e32 v99, 0
	v_mov_b32_e32 v100, 0
	v_mov_b32_e32 v101, 0
	v_mov_b32_e32 v102, 0
	v_mov_b32_e32 v103, 0
	v_mov_b32_e32 v104, 0
	v_mov_b32_e32 v105, 0
	v_mov_b32_e32 v106, 0
	v_mov_b32_e32 v107, 0
	v_mov_b32_e32 v108, 0
	v_mov_b32_e32 v109, 0
	v_mov_b32_e32 v110, 0
	v_mov_b32_e32 v111, 0
	v_mov_b32_e32 v112, 0
	v_mov_b32_e32 v113, 0
	v_mov_b32_e32 v114, 0
	v_mov_b32_e32 v115, 0
	v_mov_b32_e32 v116, 0
	v_mov_b32_e32 v117, 0
	v_mov_b32_e32 v118, 0
	v_mov_b32_e32 v119, 0
	v_mov_b32_e32 v120, 0
	v_mov_b32_e32 v121, 0
	v_mov_b32_e32 v122, 0
	v_mov_b32_e32 v123, 0
	v_mov_b32_e32 v124, 0
	v_mov_b32_e32 v125, 0
	v_mov_b32_e32 v126, 0
	v_mov_b32_e32 v127, 0
	v_ashrrev_i32_e32 v12, 8, v128
	v_cmp_eq_u32_e32 vcc, 1, v12
	s_and_saveexec_b64 s[68:69], vcc
	s_cbranch_execz .LBB0_1063
	s_barrier
; #define STAGE_A(P, hf, kt) do { if constexpr (ABLK) { const bf16* _gp = A + ((long)(brow >> 8) * nt + (kt)) * 16384 + (hf) * 8192; GLDS2(_gp, 4096, offA, P); } \
;     else { const bf16* _gp = A + (long)(brow + (hf) * HALF) * lda + (long)(kt) * BK; GLDS2(_gp, 64 * (long)lda, offA, P); } } while (0)
; #define STAGE_B(P, hf, kt) do { const bf16* _gp = Bt + (long)(bcol + (hf) * 2) * ldb + (long)(kt) * BK; GLDS2(_gp, 128 * (long)ldb, offB, P); } while (0)
; #define WAIT_V(n) asm volatile("s_waitcnt vmcnt(" #n ")" ::: "memory")
; #define BAR __builtin_amdgcn_s_barrier()
; template <bool ABLK, class Epi>
; __device__ __forceinline__ void gemm_tile(const bf16* __restrict__ A, int lda, const bf16* __restrict__ Bt, int ldb, int K,
;                                           int brow, int bcol, bf16* shm, const Epi& epi, int wv) {
;     ...
;   const int wid = tid >> 6, lane = tid & 63, wr = wid >> 2, wc = wid & 3, fr = lane & 15, fq = lane >> 4;
;   f32x4 acc[2][2][4][2] = {};
;   bf16x8 At[4][2], B0[2][2], B1[2][2];
;   const int nt = K / BK;
;   int offA, offB;
;   { int r_, c_; stage_rc(tid * 16, r_, c_); offA = ABLK ? r_ * 64 + c_ : r_ * lda + c_;
;     offB = ((r_ >> 5) * 64 + (r_ & 15) * 4 + ((r_ >> 4) & 1)) * ldb + c_; }
;   STAGE_B(SB(0, 0), 0, 0); STAGE_A(SA(0, 0), 0, 0);
;   STAGE_B(SB(0, 1), 1, 0); STAGE_A(SA(0, 1), 1, 0);
;   if (wr == 1) BAR;
;   WAIT_V(4); BAR;
;   STAGE_B(SB(1, 0), 0, 1); STAGE_A(SA(1, 0), 0, 1); STAGE_B(SB(1, 1), 1, 1);
;   WAIT_V(6); BAR;
.LBB0_1063:
	s_or_b64 exec, exec, s[68:69]
	v_add_u32_e32 v155, s78, v11
	v_add_u32_e32 v156, 0x2000, v155
	v_readfirstlane_b32 s2, v155
	v_lshl_add_u64 v[14:15], v[0:1], 0, s[16:17]
	s_mov_b32 m0, s2
	v_readfirstlane_b32 s2, v156
	v_add_u32_e32 v157, 0x8000, v148
	s_waitcnt vmcnt(4)
	s_barrier
	global_load_lds_dwordx4 v[14:15], off
	v_lshl_add_u64 v[0:1], v[0:1], 0, s[18:19]
	s_mov_b32 m0, s2
	v_readfirstlane_b32 s2, v157
	v_add_u32_e32 v158, 0xa000, v148
	global_load_lds_dwordx4 v[0:1], off
	v_lshl_add_u64 v[0:1], v[130:131], 0, s[20:21]
	s_mov_b32 m0, s2
	v_readfirstlane_b32 s2, v158
	v_add_u32_e32 v159, s79, v11
	global_load_lds_dwordx4 v[0:1], off
	v_lshl_add_u64 v[0:1], v[130:131], 0, s[22:23]
	s_mov_b32 m0, s2
	v_readfirstlane_b32 s2, v159
	v_add_u32_e32 v160, 0x2000, v159
	global_load_lds_dwordx4 v[0:1], off
	v_lshl_add_u64 v[0:1], v[2:3], 0, s[16:17]
	s_mov_b32 m0, s2
	v_readfirstlane_b32 s2, v160
	global_load_lds_dwordx4 v[0:1], off
	v_lshl_add_u64 v[0:1], v[2:3], 0, s[18:19]
	s_mov_b32 m0, s2
	v_and_b32_e32 v13, 15, v128
	global_load_lds_dwordx4 v[0:1], off
	v_bfe_u32 v138, v128, 4, 2
	v_lshlrev_b32_e32 v139, 2, v13
	v_lshlrev_b32_e32 v0, 4, v138
	v_lshlrev_b32_e32 v1, 6, v13
	v_and_b32_e32 v3, 32, v139
	v_bitop3_b32 v1, v0, v3, v1 bitop3:0x36
	v_add_u32_e32 v11, s76, v1
	v_add_u32_e32 v13, s77, v1
	v_add_u32_e32 v14, s78, v1
	v_add_u32_e32 v15, s79, v1
	v_add_u32_e32 v16, 0, v1
	v_lshlrev_b32_e32 v1, 6, v128
	v_and_or_b32 v0, v1, s80, v0
	v_xad_u32 v3, v0, v3, 0
	v_lshlrev_b32_e32 v0, 9, v4
	v_and_b32_e32 v0, 0xfffffc00, v0
	v_add_u32_e32 v0, v0, v9
	v_add3_u32 v0, v0, v5, v6
	s_add_u32 s66, s72, s66
	v_ashrrev_i32_e32 v1, 31, v0
	s_addc_u32 s67, s73, s67
	v_lshl_add_u64 v[132:133], v[0:1], 1, s[66:67]
	v_add3_u32 v0, v7, v8, v10
	v_lshl_or_b32 v0, v0, 11, v5
	v_add_u32_e32 v0, v0, v6
	s_add_u32 s64, s74, s64
	v_bfe_u32 v137, v128, 6, 2
	s_waitcnt vmcnt(6)
	v_lshlrev_b32_e32 v140, 6, v12
	v_lshlrev_b32_e32 v12, 13, v12
	v_ashrrev_i32_e32 v1, 31, v0
	s_addc_u32 s65, s75, s65
	v_lshlrev_b32_e32 v2, 12, v137
	v_or_b32_e32 v17, 0x800, v12
	v_or_b32_e32 v18, 0x1000, v12
	v_or_b32_e32 v19, 0x1800, v12
	v_lshl_add_u64 v[134:135], v[0:1], 1, s[64:65]
	v_mov_b32_e32 v0, 0
	s_mov_b32 s33, -2
	v_add_u32_e32 v162, v11, v2
	v_add_u32_e32 v144, v16, v12
	v_add_u32_e32 v143, v3, v17
	v_add_u32_e32 v142, v3, v18
	v_add_u32_e32 v141, v3, v19
	v_add_u32_e32 v161, v13, v2
	v_add_u32_e32 v150, v14, v2
	v_add_u32_e32 v147, v15, v2
	v_mov_b32_e32 v1, v0
	v_mov_b32_e32 v2, v0
	v_mov_b32_e32 v3, v0
	v_mov_b32_e32 v4, v0
	v_mov_b32_e32 v5, v0
	v_mov_b32_e32 v6, v0
	v_mov_b32_e32 v7, v0
	v_mov_b32_e32 v8, v0
	v_mov_b32_e32 v9, v0
	v_mov_b32_e32 v10, v0
	v_mov_b32_e32 v11, v0
	v_mov_b32_e32 v12, v0
	v_mov_b32_e32 v13, v0
	v_mov_b32_e32 v14, v0
	v_mov_b32_e32 v15, v0
	v_mov_b32_e32 v16, v0
	v_mov_b32_e32 v17, v0
	v_mov_b32_e32 v18, v0
	v_mov_b32_e32 v19, v0
	s_barrier

; __device__ __forceinline__ int mytid(int wv) { return (wv << 6) | (int)__builtin_amdgcn_mbcnt_hi(~0u, __builtin_amdgcn_mbcnt_lo(~0u, 0u)); }
; #define STAGE_A(P, hf, kt) do { if constexpr (ABLK) { const bf16* _gp = A + ((long)(brow >> 8) * nt + (kt)) * 16384 + (hf) * 8192; GLDS2(_gp, 4096, offA, P); } \
;     else { const bf16* _gp = A + (long)(brow + (hf) * HALF) * lda + (long)(kt) * BK; GLDS2(_gp, 64 * (long)lda, offA, P); } } while (0)
; #define STAGE_B(P, hf, kt) do { const bf16* _gp = Bt + (long)(bcol + (hf) * 2) * ldb + (long)(kt) * BK; GLDS2(_gp, 128 * (long)ldb, offB, P); } while (0)
; #define BAR __builtin_amdgcn_s_barrier()
; template <bool ABLK, class Epi>
; __device__ __forceinline__ void gemm_tile(const bf16* __restrict__ A, int lda, const bf16* __restrict__ Bt, int ldb, int K,
;                                           int brow, int bcol, bf16* shm, const Epi& epi, int wv) {
;     ...
;   int tid = mytid(wv); asm volatile("" : "+v"(tid));
;   const int wid = tid >> 6, lane = tid & 63, wr = wid >> 2, wc = wid & 3, fr = lane & 15, fq = lane >> 4;
;   f32x4 acc[2][2][4][2] = {};
;   bf16x8 At[4][2], B0[2][2], B1[2][2];
;   const int nt = K / BK;
;   int offA, offB;
;   { int r_, c_; stage_rc(tid * 16, r_, c_); offA = ABLK ? r_ * 64 + c_ : r_ * lda + c_;
;     offB = ((r_ >> 5) * 64 + (r_ & 15) * 4 + ((r_ >> 4) & 1)) * ldb + c_; }
;   STAGE_B(SB(0, 0), 0, 0); STAGE_A(SA(0, 0), 0, 0);
;   STAGE_B(SB(0, 1), 1, 0); STAGE_A(SA(0, 1), 1, 0);
;   if (wr == 1) BAR;
; template <bool ABLK, class Epi>
; __device__ __forceinline__ void gemm_phase(const bf16* A, int lda, const bf16* Bt, int ldb, int M, int N, int K, char* smem, const Epi& epi, int wv) {
;     ...
;   for (int w = blockIdx.x; w < nwg; w += gridDim.x) {
;     int wgid = w;
;     { int q = nwg / NXCD, r = nwg % NXCD, xcd = wgid % NXCD, off = wgid / NXCD;
;       wgid = (xcd < r ? xcd * (q + 1) : r * (q + 1) + (xcd - r) * q) + off; }
;     const int nig = WGM * nN, gid = wgid / nig, fm = gid * WGM, gsz = min(nM - fm, WGM);
;     const int pm = fm + ((wgid % nig) % gsz), pn = (wgid % nig) / gsz;
;     gemm_tile<ABLK>(A, lda, Bt, ldb, K, pm * BM, pn * BM, (bf16*)smem, epi, wv);
.LBB0_1108:
	v_mov_b32_e32 v135, v192
	s_ashr_i32 s2, s89, 31
	s_lshr_b32 s2, s2, 29
	v_ashrrev_i32_e32 v0, 31, v135
	v_lshrrev_b32_e32 v0, 26, v0
	s_add_i32 s2, s89, s2
	v_add_u32_e32 v0, v135, v0
	s_ashr_i32 s33, s2, 3
	s_and_b32 s2, s2, -8
	v_ashrrev_i32_e32 v2, 6, v0
	v_bfe_i32 v0, v135, 27, 1
	s_sub_i32 s2, s89, s2
	v_lshlrev_b32_e32 v9, 4, v135
	v_lshrrev_b32_e32 v0, 22, v0
	s_cmp_lt_i32 s2, 0
	s_movk_i32 s66, 0xc1
	v_add_u32_e32 v0, v9, v0
	s_cselect_b32 s66, s66, 0xc0
	v_and_b32_e32 v0, 0xfffffc00, v0
	s_mul_i32 s2, s66, s2
	v_sub_u32_e32 v0, v9, v0
	s_add_i32 s2, s2, s33
	v_lshrrev_b32_e32 v1, 4, v0
	s_ashr_i32 s33, s2, 31
	v_bitop3_b32 v0, v1, v0, 32 bitop3:0x6c
	s_lshr_b32 s33, s33, 27
	v_ashrrev_i32_e32 v3, 31, v0
	s_add_i32 s33, s2, s33
	v_lshrrev_b32_e32 v3, 26, v3
	s_ashr_i32 s66, s33, 5
	s_and_b32 s33, s33, 0xffe0
	v_add_u32_e32 v4, v0, v3
	s_sub_i32 s2, s2, s33
	v_lshlrev_b32_e32 v1, 3, v2
	v_and_b32_e32 v7, 0xffffffc0, v4
	s_bfe_i32 s33, s2, 0x80000
	v_and_b32_e32 v1, -16, v1
	v_ashrrev_i32_e32 v3, 6, v4
	v_sub_u32_e32 v0, v0, v7
	s_bfe_u32 s33, s33, 0x2000d
	v_add_u32_e32 v1, v3, v1
	v_lshlrev_b32_e32 v3, 5, v2
	v_ashrrev_i16_sdwa v0, v134, sext(v0) dst_sel:DWORD dst_unused:UNUSED_PAD src0_sel:DWORD src1_sel:BYTE_0
	s_add_i32 s33, s2, s33
	v_and_b32_e32 v3, 32, v3
	v_bfe_i32 v4, v0, 0, 16
	v_lshlrev_b32_e32 v5, 1, v1
	v_lshlrev_b32_e32 v6, 2, v1
	s_lshl_b32 s82, s66, 2
	s_bfe_i32 s66, s33, 0x80000
	v_add_u32_e32 v0, v3, v4
	v_and_b32_e32 v5, 0xffffffc0, v5
	v_and_b32_e32 v6, 60, v6
	v_bfe_u32 v8, v1, 4, 1
	s_sext_i32_i16 s66, s66
	v_lshl_add_u32 v10, v1, 6, v0
	v_or3_b32 v1, v5, v6, v8
	s_and_b32 s33, s33, 0xfc
	s_ashr_i32 s83, s66, 2
	v_mad_u64_u32 v[0:1], s[66:67], v1, s0, v[0:1]
	s_sub_i32 s2, s2, s33
	s_mul_i32 s66, s83, 0x160000
	s_sext_i32_i8 s2, s2
	s_ashr_i32 s67, s66, 31
	s_add_i32 s82, s82, s2
	s_lshl_b64 s[66:67], s[66:67], 1
	s_add_u32 s68, s70, s66
	s_addc_u32 s69, s71, s67
	v_ashrrev_i32_e32 v1, 31, v0
	v_add_u32_e32 v145, s76, v9
	v_lshl_add_u64 v[0:1], v[0:1], 1, s[68:69]
	v_readfirstlane_b32 s2, v145
	s_mov_b64 s[68:69], 0x160000
	v_add_u32_e32 v146, 0x2000, v145
	s_mul_i32 s84, s82, 0x2c0000
	s_mov_b32 m0, s2
	v_lshl_add_u64 v[12:13], v[0:1], 0, s[68:69]
	v_readfirstlane_b32 s2, v146
	s_mul_hi_i32 s33, s82, 0x2c0000
	s_add_u32 s68, s1, s84
	v_add_u32_e32 v147, 0, v9
	global_load_lds_dwordx4 v[0:1], off
	s_mov_b32 m0, s2
	s_addc_u32 s69, s3, s33
	v_ashrrev_i32_e32 v11, 31, v10
	v_readfirstlane_b32 s2, v147
	v_add_u32_e32 v148, 0x2000, v147
	global_load_lds_dwordx4 v[12:13], off
	v_lshl_add_u64 v[128:129], v[10:11], 1, s[68:69]
	s_mov_b32 m0, s2
	v_readfirstlane_b32 s2, v148
	v_add_u32_e32 v150, s77, v9
	global_load_lds_dwordx4 v[128:129], off
	v_lshl_add_u64 v[10:11], v[128:129], 0, s[6:7]
	s_mov_b32 m0, s2
	v_readfirstlane_b32 s2, v150
	v_add_u32_e32 v151, 0x2000, v150
	global_load_lds_dwordx4 v[10:11], off
	v_lshl_add_u64 v[10:11], v[0:1], 0, s[8:9]
	s_mov_b32 m0, s2
	v_readfirstlane_b32 s2, v151
	v_add_u32_e32 v152, 0x4000, v147
	global_load_lds_dwordx4 v[10:11], off
	v_lshl_add_u64 v[10:11], v[0:1], 0, s[10:11]
	s_mov_b32 m0, s2
	v_readfirstlane_b32 s2, v152
	v_add_u32_e32 v153, 0x6000, v147
	global_load_lds_dwordx4 v[10:11], off
	v_lshl_add_u64 v[10:11], v[128:129], 0, s[12:13]
	s_mov_b32 m0, s2
	v_readfirstlane_b32 s2, v153
	global_load_lds_dwordx4 v[10:11], off
	v_lshl_add_u64 v[10:11], v[128:129], 0, s[14:15]
	s_mov_b32 m0, s2
	s_nop 0
	global_load_lds_dwordx4 v[10:11], off
	v_mov_b32_e32 v20, 0
	v_mov_b32_e32 v21, 0
	v_mov_b32_e32 v22, 0
	v_mov_b32_e32 v23, 0
	v_mov_b32_e32 v24, 0
	v_mov_b32_e32 v25, 0
	v_mov_b32_e32 v26, 0
	v_mov_b32_e32 v27, 0
	v_mov_b32_e32 v28, 0
	v_mov_b32_e32 v29, 0
	v_mov_b32_e32 v30, 0
	v_mov_b32_e32 v31, 0
	v_mov_b32_e32 v32, 0
	v_mov_b32_e32 v33, 0
	v_mov_b32_e32 v34, 0
	v_mov_b32_e32 v35, 0
	v_mov_b32_e32 v36, 0
	v_mov_b32_e32 v37, 0
	v_mov_b32_e32 v38, 0
	v_mov_b32_e32 v39, 0
	v_mov_b32_e32 v40, 0
	v_mov_b32_e32 v41, 0
	v_mov_b32_e32 v42, 0
	v_mov_b32_e32 v43, 0
	v_mov_b32_e32 v44, 0
	v_mov_b32_e32 v45, 0
	v_mov_b32_e32 v46, 0
	v_mov_b32_e32 v47, 0
	v_mov_b32_e32 v48, 0
	v_mov_b32_e32 v49, 0
	v_mov_b32_e32 v50, 0
	v_mov_b32_e32 v51, 0
	v_mov_b32_e32 v52, 0
	v_mov_b32_e32 v53, 0
	v_mov_b32_e32 v54, 0
	v_mov_b32_e32 v55, 0
	v_mov_b32_e32 v56, 0
	v_mov_b32_e32 v57, 0
	v_mov_b32_e32 v58, 0
	v_mov_b32_e32 v59, 0
	v_mov_b32_e32 v60, 0
	v_mov_b32_e32 v61, 0
	v_mov_b32_e32 v62, 0
	v_mov_b32_e32 v63, 0
	v_mov_b32_e32 v64, 0
	v_mov_b32_e32 v65, 0
	v_mov_b32_e32 v66, 0
	v_mov_b32_e32 v67, 0
	v_mov_b32_e32 v68, 0
	v_mov_b32_e32 v69, 0
	v_mov_b32_e32 v70, 0
	v_mov_b32_e32 v71, 0
	v_mov_b32_e32 v72, 0
	v_mov_b32_e32 v73, 0
	v_mov_b32_e32 v74, 0
	v_mov_b32_e32 v75, 0
	v_mov_b32_e32 v76, 0
	v_mov_b32_e32 v77, 0
	v_mov_b32_e32 v78, 0
	v_mov_b32_e32 v79, 0
	v_mov_b32_e32 v80, 0
	v_mov_b32_e32 v81, 0
	v_mov_b32_e32 v82, 0
	v_mov_b32_e32 v83, 0
	v_mov_b32_e32 v84, 0
	v_mov_b32_e32 v85, 0
	v_mov_b32_e32 v86, 0
	v_mov_b32_e32 v87, 0
	v_mov_b32_e32 v88, 0
	v_mov_b32_e32 v89, 0
	v_mov_b32_e32 v90, 0
	v_mov_b32_e32 v91, 0
	v_mov_b32_e32 v92, 0
	v_mov_b32_e32 v93, 0
	v_mov_b32_e32 v94, 0
	v_mov_b32_e32 v95, 0
	v_mov_b32_e32 v96, 0
	v_mov_b32_e32 v97, 0
	v_mov_b32_e32 v98, 0
	v_mov_b32_e32 v99, 0
	v_mov_b32_e32 v100, 0
	v_mov_b32_e32 v101, 0
	v_mov_b32_e32 v102, 0
	v_mov_b32_e32 v103, 0
	v_mov_b32_e32 v104, 0
	v_mov_b32_e32 v105, 0
	v_mov_b32_e32 v106, 0
	v_mov_b32_e32 v107, 0
	v_mov_b32_e32 v108, 0
	v_mov_b32_e32 v109, 0
	v_mov_b32_e32 v110, 0
	v_mov_b32_e32 v111, 0
	v_mov_b32_e32 v112, 0
	v_mov_b32_e32 v113, 0
	v_mov_b32_e32 v114, 0
	v_mov_b32_e32 v115, 0
	v_mov_b32_e32 v116, 0
	v_mov_b32_e32 v117, 0
	v_mov_b32_e32 v118, 0
	v_mov_b32_e32 v119, 0
	v_mov_b32_e32 v120, 0
	v_mov_b32_e32 v121, 0
	v_mov_b32_e32 v122, 0
	v_mov_b32_e32 v123, 0
	v_mov_b32_e32 v124, 0
	v_mov_b32_e32 v125, 0
	v_mov_b32_e32 v126, 0
	v_mov_b32_e32 v127, 0
	v_ashrrev_i32_e32 v10, 8, v135
	v_cmp_eq_u32_e32 vcc, 1, v10
	s_and_saveexec_b64 s[68:69], vcc
	s_cbranch_execz .LBB0_1110
	s_barrier
; #define STAGE_A(P, hf, kt) do { if constexpr (ABLK) { const bf16* _gp = A + ((long)(brow >> 8) * nt + (kt)) * 16384 + (hf) * 8192; GLDS2(_gp, 4096, offA, P); } \
;     else { const bf16* _gp = A + (long)(brow + (hf) * HALF) * lda + (long)(kt) * BK; GLDS2(_gp, 64 * (long)lda, offA, P); } } while (0)
; #define STAGE_B(P, hf, kt) do { const bf16* _gp = Bt + (long)(bcol + (hf) * 2) * ldb + (long)(kt) * BK; GLDS2(_gp, 128 * (long)ldb, offB, P); } while (0)
; #define WAIT_V(n) asm volatile("s_waitcnt vmcnt(" #n ")" ::: "memory")
; #define BAR __builtin_amdgcn_s_barrier()
; template <bool ABLK, class Epi>
; __device__ __forceinline__ void gemm_tile(const bf16* __restrict__ A, int lda, const bf16* __restrict__ Bt, int ldb, int K,
;                                           int brow, int bcol, bf16* shm, const Epi& epi, int wv) {
;     ...
;   const int wid = tid >> 6, lane = tid & 63, wr = wid >> 2, wc = wid & 3, fr = lane & 15, fq = lane >> 4;
;   f32x4 acc[2][2][4][2] = {};
;   bf16x8 At[4][2], B0[2][2], B1[2][2];
;   const int nt = K / BK;
;   int offA, offB;
;   { int r_, c_; stage_rc(tid * 16, r_, c_); offA = ABLK ? r_ * 64 + c_ : r_ * lda + c_;
;     offB = ((r_ >> 5) * 64 + (r_ & 15) * 4 + ((r_ >> 4) & 1)) * ldb + c_; }
;   STAGE_B(SB(0, 0), 0, 0); STAGE_A(SA(0, 0), 0, 0);
;   STAGE_B(SB(0, 1), 1, 0); STAGE_A(SA(0, 1), 1, 0);
;   if (wr == 1) BAR;
;   WAIT_V(4); BAR;
;   STAGE_B(SB(1, 0), 0, 1); STAGE_A(SA(1, 0), 0, 1); STAGE_B(SB(1, 1), 1, 1);
;   WAIT_V(6); BAR;
.LBB0_1110:
	s_or_b64 exec, exec, s[68:69]
	v_add_u32_e32 v154, s78, v9
	v_add_u32_e32 v155, 0x2000, v154
	v_readfirstlane_b32 s2, v154
	v_lshl_add_u64 v[12:13], v[0:1], 0, s[16:17]
	s_mov_b32 m0, s2
	v_readfirstlane_b32 s2, v155
	v_add_u32_e32 v156, 0x8000, v147
	s_waitcnt vmcnt(4)
	s_barrier
	global_load_lds_dwordx4 v[12:13], off
	v_lshl_add_u64 v[12:13], v[0:1], 0, s[18:19]
	s_mov_b32 m0, s2
	v_readfirstlane_b32 s2, v156
	v_add_u32_e32 v157, 0xa000, v147
	global_load_lds_dwordx4 v[12:13], off
	v_lshl_add_u64 v[12:13], v[128:129], 0, s[20:21]
	s_mov_b32 m0, s2
	v_readfirstlane_b32 s2, v157
	v_add_u32_e32 v158, s79, v9
	global_load_lds_dwordx4 v[12:13], off
	v_lshl_add_u64 v[12:13], v[128:129], 0, s[22:23]
	s_mov_b32 m0, s2
	v_readfirstlane_b32 s2, v158
	v_add_u32_e32 v159, 0x2000, v158
	global_load_lds_dwordx4 v[12:13], off
	v_lshl_add_u64 v[12:13], v[0:1], 0, s[24:25]
	s_mov_b32 m0, s2
	v_readfirstlane_b32 s2, v159
	global_load_lds_dwordx4 v[12:13], off
	v_lshl_add_u64 v[0:1], v[0:1], 0, s[26:27]
	s_mov_b32 m0, s2
	v_and_b32_e32 v11, 15, v135
	global_load_lds_dwordx4 v[0:1], off
	v_bfe_u32 v137, v135, 4, 2
	v_lshlrev_b32_e32 v138, 2, v11
	v_lshlrev_b32_e32 v0, 4, v137
	v_lshlrev_b32_e32 v1, 6, v11
	v_and_b32_e32 v11, 32, v138
	v_bitop3_b32 v1, v0, v11, v1 bitop3:0x36
	v_add_u32_e32 v12, s76, v1
	v_add_u32_e32 v13, s77, v1
	v_add_u32_e32 v14, s78, v1
	v_add_u32_e32 v15, s79, v1
	v_add_u32_e32 v16, 0, v1
	v_lshlrev_b32_e32 v1, 6, v135
	v_and_or_b32 v0, v1, s80, v0
	v_xad_u32 v11, v0, v11, 0
	v_lshlrev_b32_e32 v0, 9, v2
	v_and_b32_e32 v0, 0xfffffc00, v0
	v_add_u32_e32 v0, v0, v7
	v_add3_u32 v0, v0, v3, v4
	s_add_u32 s68, s72, s84
	v_ashrrev_i32_e32 v1, 31, v0
	s_addc_u32 s69, s73, s33
	v_lshl_add_u64 v[130:131], v[0:1], 1, s[68:69]
	v_add3_u32 v0, v5, v6, v8
	v_mul_lo_u32 v0, v0, s0
	v_or_b32_e32 v0, v0, v3
	v_add_u32_e32 v0, v0, v4
	s_add_u32 s66, s74, s66
	v_bfe_u32 v136, v135, 6, 2
	s_waitcnt vmcnt(6)
	v_lshlrev_b32_e32 v139, 6, v10
	v_lshlrev_b32_e32 v10, 13, v10
	v_ashrrev_i32_e32 v1, 31, v0
	s_addc_u32 s67, s75, s67
	v_lshlrev_b32_e32 v9, 12, v136
	v_or_b32_e32 v17, 0x800, v10
	v_or_b32_e32 v18, 0x1000, v10
	v_or_b32_e32 v19, 0x1800, v10
	v_lshl_add_u64 v[132:133], v[0:1], 1, s[66:67]
	v_mov_b32_e32 v0, 0
	s_mov_b32 s33, -2
	v_add_u32_e32 v161, v12, v9
	v_add_u32_e32 v143, v16, v10
	v_add_u32_e32 v142, v11, v17
	v_add_u32_e32 v141, v11, v18
	v_add_u32_e32 v140, v11, v19
	v_add_u32_e32 v160, v13, v9
	v_add_u32_e32 v149, v14, v9
	v_add_u32_e32 v144, v15, v9
	v_mov_b32_e32 v1, v0
	v_mov_b32_e32 v2, v0
	v_mov_b32_e32 v3, v0
	v_mov_b32_e32 v4, v0
	v_mov_b32_e32 v5, v0
	v_mov_b32_e32 v6, v0
	v_mov_b32_e32 v7, v0
	v_mov_b32_e32 v8, v0
	v_mov_b32_e32 v9, v0
	v_mov_b32_e32 v10, v0
	v_mov_b32_e32 v11, v0
	v_mov_b32_e32 v12, v0
	v_mov_b32_e32 v13, v0
	v_mov_b32_e32 v14, v0
	v_mov_b32_e32 v15, v0
	v_mov_b32_e32 v16, v0
	v_mov_b32_e32 v17, v0
	v_mov_b32_e32 v18, v0
	v_mov_b32_e32 v19, v0
	s_barrier
